# as combo2 but GEMM epilogue stores plain instead of nt
# speedup vs baseline: 1.0150x; 1.0150x over previous
.LBB0_178:
	v_mov_b32_e32 v136, v139
	s_lshl_b32 s29, s38, 8
	s_add_i32 s29, s29, s62
	v_and_or_b32 v145, v136, 15, s29
	s_lshl_b32 s29, s73, 7
	v_lshrrev_b32_e32 v136, 1, v136
	v_and_or_b32 v136, v136, 24, s29
	v_or_b32_e32 v146, s63, v136
	v_mul_f32_e32 v136, 0xbfb8aa3b, v124
	v_exp_f32_e32 v136, v136
	v_mul_f32_e32 v137, 0xbfb8aa3b, v125
	v_exp_f32_e32 v137, v137
	v_ashrrev_i32_e32 v147, 31, v146
	v_add_f32_e32 v136, 1.0, v136
	v_rcp_f32_e32 v148, v136
	v_add_f32_e32 v136, 1.0, v137
	v_rcp_f32_e32 v149, v136
	v_mov_b64_e32 v[136:137], s[16:17]
	v_mad_i64_i32 v[150:151], s[40:41], v145, s65, v[136:137]
	v_pk_mul_f32 v[124:125], v[124:125], v[148:149]
	v_mul_f32_e32 v148, 0xbfb8aa3b, v126
	v_mul_f32_e32 v149, 0xbfb8aa3b, v127
	v_exp_f32_e32 v148, v148
	v_exp_f32_e32 v149, v149
	v_pk_mul_f32 v[120:121], v[124:125], v[120:121]
	s_andn2_b64 vcc, exec, s[4:5]
	v_add_f32_e32 v124, 1.0, v148
	v_add_f32_e32 v125, 1.0, v149
	v_mul_f32_e32 v148, 0xbfb8aa3b, v112
	v_mul_f32_e32 v149, 0xbfb8aa3b, v113
	v_rcp_f32_e32 v124, v124
	v_rcp_f32_e32 v125, v125
	v_exp_f32_e32 v148, v148
	v_exp_f32_e32 v149, v149
	s_mov_b64 s[4:5], -1
	v_pk_mul_f32 v[124:125], v[126:127], v[124:125]
	v_add_f32_e32 v126, 1.0, v148
	v_add_f32_e32 v127, 1.0, v149
	v_mul_f32_e32 v148, 0xbfb8aa3b, v114
	v_mul_f32_e32 v149, 0xbfb8aa3b, v115
	v_exp_f32_e32 v148, v148
	v_exp_f32_e32 v149, v149
	v_rcp_f32_e32 v126, v126
	v_rcp_f32_e32 v127, v127
	v_add_f32_e32 v148, 1.0, v148
	v_add_f32_e32 v149, 1.0, v149
	v_rcp_f32_e32 v148, v148
	v_rcp_f32_e32 v149, v149
	v_pk_mul_f32 v[112:113], v[112:113], v[126:127]
	v_pk_mul_f32 v[122:123], v[124:125], v[122:123]
	v_pk_mul_f32 v[116:117], v[112:113], v[116:117]
	v_pk_mul_f32 v[112:113], v[114:115], v[148:149]
	v_cvt_pk_bf16_f32 v116, v116, v117
	v_pk_mul_f32 v[118:119], v[112:113], v[118:119]
	v_lshlrev_b64 v[112:113], 1, v[146:147]
	v_cvt_pk_bf16_f32 v117, v118, v119
	v_mul_f32_e32 v118, 0xbfb8aa3b, v108
	v_mul_f32_e32 v119, 0xbfb8aa3b, v109
	v_exp_f32_e32 v118, v118
	v_exp_f32_e32 v119, v119
	v_lshl_add_u64 v[124:125], v[150:151], 0, v[112:113]
	v_cvt_pk_bf16_f32 v114, v120, v121
	v_cvt_pk_bf16_f32 v115, v122, v123
	global_store_dwordx4 v[124:125], v[114:117], off
	s_nop 1
	v_add_f32_e32 v114, 1.0, v118
	v_add_f32_e32 v115, 1.0, v119
	v_rcp_f32_e32 v114, v114
	v_rcp_f32_e32 v115, v115
	v_or_b32_e32 v116, 16, v145
	v_mad_i64_i32 v[116:117], s[40:41], v116, s65, v[136:137]
	v_pk_mul_f32 v[108:109], v[108:109], v[114:115]
	v_mul_f32_e32 v114, 0xbfb8aa3b, v110
	v_mul_f32_e32 v115, 0xbfb8aa3b, v111
	v_exp_f32_e32 v114, v114
	v_exp_f32_e32 v115, v115
	v_pk_mul_f32 v[104:105], v[108:109], v[104:105]
	v_add_f32_e32 v108, 1.0, v114
	v_add_f32_e32 v109, 1.0, v115
	v_mul_f32_e32 v114, 0xbfb8aa3b, v96
	v_mul_f32_e32 v115, 0xbfb8aa3b, v97
	v_rcp_f32_e32 v108, v108
	v_rcp_f32_e32 v109, v109
	v_exp_f32_e32 v114, v114
	v_exp_f32_e32 v115, v115
	v_pk_mul_f32 v[108:109], v[110:111], v[108:109]
	v_add_f32_e32 v110, 1.0, v114
	v_add_f32_e32 v111, 1.0, v115
	v_mul_f32_e32 v114, 0xbfb8aa3b, v98
	v_mul_f32_e32 v115, 0xbfb8aa3b, v99
	v_exp_f32_e32 v114, v114
	v_exp_f32_e32 v115, v115
	v_rcp_f32_e32 v110, v110
	v_rcp_f32_e32 v111, v111
	v_add_f32_e32 v114, 1.0, v114
	v_add_f32_e32 v115, 1.0, v115
	v_rcp_f32_e32 v114, v114
	v_rcp_f32_e32 v115, v115
	v_pk_mul_f32 v[96:97], v[96:97], v[110:111]
	v_pk_mul_f32 v[106:107], v[108:109], v[106:107]
	v_pk_mul_f32 v[100:101], v[96:97], v[100:101]
	v_pk_mul_f32 v[96:97], v[98:99], v[114:115]
	v_cvt_pk_bf16_f32 v98, v100, v101
	v_mul_f32_e32 v100, 0xbfb8aa3b, v92
	v_mul_f32_e32 v101, 0xbfb8aa3b, v93
	v_exp_f32_e32 v100, v100
	v_exp_f32_e32 v101, v101
	v_pk_mul_f32 v[102:103], v[96:97], v[102:103]
	v_lshl_add_u64 v[108:109], v[116:117], 0, v[112:113]
	v_cvt_pk_bf16_f32 v96, v104, v105
	v_cvt_pk_bf16_f32 v97, v106, v107
	v_cvt_pk_bf16_f32 v99, v102, v103
	global_store_dwordx4 v[108:109], v[96:99], off
	s_nop 1
	v_add_f32_e32 v96, 1.0, v100
	v_add_f32_e32 v97, 1.0, v101
	v_rcp_f32_e32 v96, v96
	v_rcp_f32_e32 v97, v97
	v_or_b32_e32 v98, 32, v145
	v_mad_i64_i32 v[98:99], s[40:41], v98, s65, v[136:137]
	v_pk_mul_f32 v[92:93], v[92:93], v[96:97]
	v_mul_f32_e32 v96, 0xbfb8aa3b, v94
	v_mul_f32_e32 v97, 0xbfb8aa3b, v95
	v_exp_f32_e32 v96, v96
	v_exp_f32_e32 v97, v97
	v_pk_mul_f32 v[88:89], v[92:93], v[88:89]
	v_add_f32_e32 v92, 1.0, v96
	v_add_f32_e32 v93, 1.0, v97
	v_mul_f32_e32 v96, 0xbfb8aa3b, v80
	v_mul_f32_e32 v97, 0xbfb8aa3b, v81
	v_rcp_f32_e32 v92, v92
	v_rcp_f32_e32 v93, v93
	v_exp_f32_e32 v96, v96
	v_exp_f32_e32 v97, v97
	v_pk_mul_f32 v[92:93], v[94:95], v[92:93]
	v_add_f32_e32 v94, 1.0, v96
	v_add_f32_e32 v95, 1.0, v97
	v_mul_f32_e32 v96, 0xbfb8aa3b, v82
	v_mul_f32_e32 v97, 0xbfb8aa3b, v83
	v_exp_f32_e32 v96, v96
	v_exp_f32_e32 v97, v97
	v_rcp_f32_e32 v94, v94
	v_rcp_f32_e32 v95, v95
	v_add_f32_e32 v96, 1.0, v96
	v_add_f32_e32 v97, 1.0, v97
	v_rcp_f32_e32 v96, v96
	v_rcp_f32_e32 v97, v97
	v_pk_mul_f32 v[80:81], v[80:81], v[94:95]
	v_pk_mul_f32 v[90:91], v[92:93], v[90:91]
	v_pk_mul_f32 v[84:85], v[80:81], v[84:85]
	v_pk_mul_f32 v[80:81], v[82:83], v[96:97]
	v_cvt_pk_bf16_f32 v82, v84, v85
	v_mul_f32_e32 v84, 0xbfb8aa3b, v76
	v_mul_f32_e32 v85, 0xbfb8aa3b, v77
	v_exp_f32_e32 v84, v84
	v_exp_f32_e32 v85, v85
	v_pk_mul_f32 v[86:87], v[80:81], v[86:87]
	v_lshl_add_u64 v[92:93], v[98:99], 0, v[112:113]
	v_cvt_pk_bf16_f32 v80, v88, v89
	v_cvt_pk_bf16_f32 v81, v90, v91
	v_cvt_pk_bf16_f32 v83, v86, v87
	global_store_dwordx4 v[92:93], v[80:83], off
	s_nop 1
	v_add_f32_e32 v80, 1.0, v84
	v_add_f32_e32 v81, 1.0, v85
	v_rcp_f32_e32 v80, v80
	v_rcp_f32_e32 v81, v81
	v_or_b32_e32 v82, 48, v145
	v_mad_i64_i32 v[82:83], s[40:41], v82, s65, v[136:137]
	v_pk_mul_f32 v[76:77], v[76:77], v[80:81]
	v_mul_f32_e32 v80, 0xbfb8aa3b, v78
	v_mul_f32_e32 v81, 0xbfb8aa3b, v79
	v_exp_f32_e32 v80, v80
	v_exp_f32_e32 v81, v81
	v_pk_mul_f32 v[72:73], v[76:77], v[72:73]
	v_add_f32_e32 v76, 1.0, v80
	v_add_f32_e32 v77, 1.0, v81
	v_mul_f32_e32 v80, 0xbfb8aa3b, v64
	v_mul_f32_e32 v81, 0xbfb8aa3b, v65
	v_rcp_f32_e32 v76, v76
	v_rcp_f32_e32 v77, v77
	v_exp_f32_e32 v80, v80
	v_exp_f32_e32 v81, v81
	v_pk_mul_f32 v[76:77], v[78:79], v[76:77]
	v_add_f32_e32 v78, 1.0, v80
	v_add_f32_e32 v79, 1.0, v81
	v_mul_f32_e32 v80, 0xbfb8aa3b, v66
	v_mul_f32_e32 v81, 0xbfb8aa3b, v67
	v_exp_f32_e32 v80, v80
	v_exp_f32_e32 v81, v81
	v_rcp_f32_e32 v78, v78
	v_rcp_f32_e32 v79, v79
	v_add_f32_e32 v80, 1.0, v80
	v_add_f32_e32 v81, 1.0, v81
	v_rcp_f32_e32 v80, v80
	v_rcp_f32_e32 v81, v81
	v_pk_mul_f32 v[64:65], v[64:65], v[78:79]
	v_pk_mul_f32 v[74:75], v[76:77], v[74:75]
	v_pk_mul_f32 v[68:69], v[64:65], v[68:69]
	v_pk_mul_f32 v[64:65], v[66:67], v[80:81]
	v_cvt_pk_bf16_f32 v66, v68, v69
	v_mul_f32_e32 v68, 0xbfb8aa3b, v60
	v_mul_f32_e32 v69, 0xbfb8aa3b, v61
	v_exp_f32_e32 v68, v68
	v_exp_f32_e32 v69, v69
	v_pk_mul_f32 v[70:71], v[64:65], v[70:71]
	v_lshl_add_u64 v[76:77], v[82:83], 0, v[112:113]
	v_cvt_pk_bf16_f32 v64, v72, v73
	v_cvt_pk_bf16_f32 v65, v74, v75
	v_cvt_pk_bf16_f32 v67, v70, v71
	global_store_dwordx4 v[76:77], v[64:67], off
	s_nop 1
	v_add_f32_e32 v64, 1.0, v68
	v_add_f32_e32 v65, 1.0, v69
	v_rcp_f32_e32 v64, v64
	v_rcp_f32_e32 v65, v65
	v_add_u32_e32 v66, 0x80, v145
	v_mad_i64_i32 v[66:67], s[40:41], v66, s65, v[136:137]
	v_pk_mul_f32 v[60:61], v[60:61], v[64:65]
	v_mul_f32_e32 v64, 0xbfb8aa3b, v62
	v_mul_f32_e32 v65, 0xbfb8aa3b, v63
	v_exp_f32_e32 v64, v64
	v_exp_f32_e32 v65, v65
	v_pk_mul_f32 v[56:57], v[60:61], v[56:57]
	v_add_f32_e32 v60, 1.0, v64
	v_add_f32_e32 v61, 1.0, v65
	v_mul_f32_e32 v64, 0xbfb8aa3b, v48
	v_mul_f32_e32 v65, 0xbfb8aa3b, v49
	v_rcp_f32_e32 v60, v60
	v_rcp_f32_e32 v61, v61
	v_exp_f32_e32 v64, v64
	v_exp_f32_e32 v65, v65
	v_pk_mul_f32 v[60:61], v[62:63], v[60:61]
	v_add_f32_e32 v62, 1.0, v64
	v_add_f32_e32 v63, 1.0, v65
	v_mul_f32_e32 v64, 0xbfb8aa3b, v50
	v_mul_f32_e32 v65, 0xbfb8aa3b, v51
	v_exp_f32_e32 v64, v64
	v_exp_f32_e32 v65, v65
	v_rcp_f32_e32 v62, v62
	v_rcp_f32_e32 v63, v63
	v_add_f32_e32 v64, 1.0, v64
	v_add_f32_e32 v65, 1.0, v65
	v_rcp_f32_e32 v64, v64
	v_rcp_f32_e32 v65, v65
	v_pk_mul_f32 v[48:49], v[48:49], v[62:63]
	v_pk_mul_f32 v[58:59], v[60:61], v[58:59]
	v_pk_mul_f32 v[52:53], v[48:49], v[52:53]
	v_pk_mul_f32 v[48:49], v[50:51], v[64:65]
	v_cvt_pk_bf16_f32 v50, v52, v53
	v_mul_f32_e32 v52, 0xbfb8aa3b, v44
	v_mul_f32_e32 v53, 0xbfb8aa3b, v45
	v_exp_f32_e32 v52, v52
	v_exp_f32_e32 v53, v53
	v_pk_mul_f32 v[54:55], v[48:49], v[54:55]
	v_lshl_add_u64 v[60:61], v[66:67], 0, v[112:113]
	v_cvt_pk_bf16_f32 v48, v56, v57
	v_cvt_pk_bf16_f32 v49, v58, v59
	v_cvt_pk_bf16_f32 v51, v54, v55
	global_store_dwordx4 v[60:61], v[48:51], off
	s_nop 1
	v_add_f32_e32 v48, 1.0, v52
	v_add_f32_e32 v49, 1.0, v53
	v_rcp_f32_e32 v48, v48
	v_rcp_f32_e32 v49, v49
	v_add_u32_e32 v50, 0x90, v145
	v_mad_i64_i32 v[50:51], s[40:41], v50, s65, v[136:137]
	v_pk_mul_f32 v[44:45], v[44:45], v[48:49]
	v_mul_f32_e32 v48, 0xbfb8aa3b, v46
	v_mul_f32_e32 v49, 0xbfb8aa3b, v47
	v_exp_f32_e32 v48, v48
	v_exp_f32_e32 v49, v49
	v_pk_mul_f32 v[40:41], v[44:45], v[40:41]
	v_add_f32_e32 v44, 1.0, v48
	v_add_f32_e32 v45, 1.0, v49
	v_mul_f32_e32 v48, 0xbfb8aa3b, v32
	v_mul_f32_e32 v49, 0xbfb8aa3b, v33
	v_rcp_f32_e32 v44, v44
	v_rcp_f32_e32 v45, v45
	v_exp_f32_e32 v48, v48
	v_exp_f32_e32 v49, v49
	v_pk_mul_f32 v[44:45], v[46:47], v[44:45]
	v_add_f32_e32 v46, 1.0, v48
	v_add_f32_e32 v47, 1.0, v49
	v_mul_f32_e32 v48, 0xbfb8aa3b, v34
	v_mul_f32_e32 v49, 0xbfb8aa3b, v35
	v_exp_f32_e32 v48, v48
	v_exp_f32_e32 v49, v49
	v_rcp_f32_e32 v46, v46
	v_rcp_f32_e32 v47, v47
	v_add_f32_e32 v48, 1.0, v48
	v_add_f32_e32 v49, 1.0, v49
	v_rcp_f32_e32 v48, v48
	v_rcp_f32_e32 v49, v49
	v_pk_mul_f32 v[32:33], v[32:33], v[46:47]
	v_pk_mul_f32 v[42:43], v[44:45], v[42:43]
	v_pk_mul_f32 v[36:37], v[32:33], v[36:37]
	v_pk_mul_f32 v[32:33], v[34:35], v[48:49]
	v_cvt_pk_bf16_f32 v34, v36, v37
	v_mul_f32_e32 v36, 0xbfb8aa3b, v28
	v_mul_f32_e32 v37, 0xbfb8aa3b, v29
	v_exp_f32_e32 v36, v36
	v_exp_f32_e32 v37, v37
	v_pk_mul_f32 v[38:39], v[32:33], v[38:39]
	v_lshl_add_u64 v[44:45], v[50:51], 0, v[112:113]
	v_cvt_pk_bf16_f32 v32, v40, v41
	v_cvt_pk_bf16_f32 v33, v42, v43
	v_cvt_pk_bf16_f32 v35, v38, v39
	global_store_dwordx4 v[44:45], v[32:35], off
	s_nop 1
	v_add_f32_e32 v32, 1.0, v36
	v_add_f32_e32 v33, 1.0, v37
	v_rcp_f32_e32 v32, v32
	v_rcp_f32_e32 v33, v33
	v_add_u32_e32 v34, 0xa0, v145
	v_mad_i64_i32 v[34:35], s[40:41], v34, s65, v[136:137]
	v_pk_mul_f32 v[28:29], v[28:29], v[32:33]
	v_mul_f32_e32 v32, 0xbfb8aa3b, v30
	v_mul_f32_e32 v33, 0xbfb8aa3b, v31
	v_exp_f32_e32 v32, v32
	v_exp_f32_e32 v33, v33
	v_pk_mul_f32 v[24:25], v[28:29], v[24:25]
	v_add_f32_e32 v28, 1.0, v32
	v_add_f32_e32 v29, 1.0, v33
	v_mul_f32_e32 v32, 0xbfb8aa3b, v16
	v_mul_f32_e32 v33, 0xbfb8aa3b, v17
	v_rcp_f32_e32 v28, v28
	v_rcp_f32_e32 v29, v29
	v_exp_f32_e32 v32, v32
	v_exp_f32_e32 v33, v33
	v_pk_mul_f32 v[28:29], v[30:31], v[28:29]
	v_add_f32_e32 v30, 1.0, v32
	v_add_f32_e32 v31, 1.0, v33
	v_mul_f32_e32 v32, 0xbfb8aa3b, v18
	v_mul_f32_e32 v33, 0xbfb8aa3b, v19
	v_exp_f32_e32 v32, v32
	v_exp_f32_e32 v33, v33
	v_rcp_f32_e32 v30, v30
	v_rcp_f32_e32 v31, v31
	v_add_f32_e32 v32, 1.0, v32
	v_add_f32_e32 v33, 1.0, v33
	v_rcp_f32_e32 v32, v32
	v_rcp_f32_e32 v33, v33
	v_pk_mul_f32 v[16:17], v[16:17], v[30:31]
	v_pk_mul_f32 v[26:27], v[28:29], v[26:27]
	v_pk_mul_f32 v[20:21], v[16:17], v[20:21]
	v_pk_mul_f32 v[16:17], v[18:19], v[32:33]
	v_cvt_pk_bf16_f32 v18, v20, v21
	v_mul_f32_e32 v20, 0xbfb8aa3b, v12
	v_mul_f32_e32 v21, 0xbfb8aa3b, v13
	v_exp_f32_e32 v20, v20
	v_exp_f32_e32 v21, v21
	v_pk_mul_f32 v[22:23], v[16:17], v[22:23]
	v_lshl_add_u64 v[28:29], v[34:35], 0, v[112:113]
	v_cvt_pk_bf16_f32 v16, v24, v25
	v_cvt_pk_bf16_f32 v17, v26, v27
	v_cvt_pk_bf16_f32 v19, v22, v23
	global_store_dwordx4 v[28:29], v[16:19], off
	s_nop 1
	v_add_f32_e32 v16, 1.0, v20
	v_add_f32_e32 v17, 1.0, v21
	v_rcp_f32_e32 v16, v16
	v_rcp_f32_e32 v17, v17
	v_add_u32_e32 v18, 0xb0, v145
	v_mad_i64_i32 v[18:19], s[40:41], v18, s65, v[136:137]
	v_pk_mul_f32 v[12:13], v[12:13], v[16:17]
	v_mul_f32_e32 v16, 0xbfb8aa3b, v14
	v_mul_f32_e32 v17, 0xbfb8aa3b, v15
	v_exp_f32_e32 v16, v16
	v_exp_f32_e32 v17, v17
	v_pk_mul_f32 v[8:9], v[12:13], v[8:9]
	v_add_f32_e32 v12, 1.0, v16
	v_add_f32_e32 v13, 1.0, v17
	v_mul_f32_e32 v16, 0xbfb8aa3b, v0
	v_mul_f32_e32 v17, 0xbfb8aa3b, v1
	v_rcp_f32_e32 v12, v12
	v_rcp_f32_e32 v13, v13
	v_exp_f32_e32 v16, v16
	v_exp_f32_e32 v17, v17
	v_pk_mul_f32 v[12:13], v[14:15], v[12:13]
	v_add_f32_e32 v14, 1.0, v16
	v_add_f32_e32 v15, 1.0, v17
	v_mul_f32_e32 v16, 0xbfb8aa3b, v2
	v_mul_f32_e32 v17, 0xbfb8aa3b, v3
	v_exp_f32_e32 v16, v16
	v_exp_f32_e32 v17, v17
	v_rcp_f32_e32 v14, v14
	v_rcp_f32_e32 v15, v15
	v_add_f32_e32 v16, 1.0, v16
	v_add_f32_e32 v17, 1.0, v17
	v_rcp_f32_e32 v16, v16
	v_rcp_f32_e32 v17, v17
	v_pk_mul_f32 v[0:1], v[0:1], v[14:15]
	v_pk_mul_f32 v[10:11], v[12:13], v[10:11]
	v_pk_mul_f32 v[4:5], v[0:1], v[4:5]
	v_pk_mul_f32 v[0:1], v[2:3], v[16:17]
	v_lshl_add_u64 v[12:13], v[18:19], 0, v[112:113]
	v_pk_mul_f32 v[6:7], v[0:1], v[6:7]
	v_cvt_pk_bf16_f32 v0, v8, v9
	v_cvt_pk_bf16_f32 v1, v10, v11
	v_cvt_pk_bf16_f32 v2, v4, v5
	v_cvt_pk_bf16_f32 v3, v6, v7
	global_store_dwordx4 v[12:13], v[0:3], off
	s_cbranch_vccnz .LBB0_171
	s_andn2_b64 vcc, exec, s[14:15]
	s_cbranch_vccnz .LBB0_170
	s_barrier
	s_branch .LBB0_170

.LBB0_258:
	v_mov_b32_e32 v137, v139
	s_lshl_b32 s38, s69, 8
	s_add_i32 s38, s38, s60
	v_and_or_b32 v136, v137, 15, s38
	s_lshl_b32 s38, s72, 8
	v_lshrrev_b32_e32 v137, 1, v137
	v_and_or_b32 v137, v137, 24, s38
	v_or_b32_e32 v144, s61, v137
	v_ashrrev_i32_e32 v137, 31, v136
	v_ashrrev_i32_e32 v145, 31, v144
	v_lshlrev_b64 v[146:147], 11, v[136:137]
	v_lshl_add_u64 v[146:147], s[18:19], 0, v[146:147]
	v_lshlrev_b64 v[144:145], 1, v[144:145]
	v_lshl_add_u64 v[146:147], v[146:147], 0, v[144:145]
	v_cvt_pk_bf16_f32 v60, v60, v61
	v_cvt_pk_bf16_f32 v61, v62, v63
	v_cvt_pk_bf16_f32 v62, v56, v57
	v_add_co_u32_e32 v56, vcc, s65, v146
	v_cvt_pk_bf16_f32 v68, v68, v69
	v_cvt_pk_bf16_f32 v69, v70, v71
	v_cvt_pk_bf16_f32 v70, v64, v65
	v_lshl_add_u64 v[64:65], v[146:147], 0, s[30:31]
	v_addc_co_u32_e32 v57, vcc, 0, v147, vcc
	v_cvt_pk_bf16_f32 v44, v44, v45
	v_cvt_pk_bf16_f32 v45, v46, v47
	v_cvt_pk_bf16_f32 v46, v40, v41
	v_cvt_pk_bf16_f32 v47, v42, v43
	v_cvt_pk_bf16_f32 v108, v108, v109
	v_cvt_pk_bf16_f32 v109, v110, v111
	v_cvt_pk_bf16_f32 v110, v104, v105
	v_or_b32_e32 v104, 16, v136
	global_store_dwordx4 v[64:65], v[44:47], off offset:256
	v_ashrrev_i32_e32 v105, 31, v104
	v_cvt_pk_bf16_f32 v92, v92, v93
	v_add_co_u32_e32 v46, vcc, s66, v146
	v_cvt_pk_bf16_f32 v93, v94, v95
	v_cvt_pk_bf16_f32 v94, v88, v89
	v_or_b32_e32 v88, 32, v136
	v_lshl_add_u64 v[44:45], v[146:147], 0, s[34:35]
	v_addc_co_u32_e32 v47, vcc, 0, v147, vcc
	v_cvt_pk_bf16_f32 v28, v28, v29
	v_cvt_pk_bf16_f32 v29, v30, v31
	v_cvt_pk_bf16_f32 v30, v24, v25
	v_cvt_pk_bf16_f32 v31, v26, v27
	v_lshlrev_b64 v[104:105], 11, v[104:105]
	v_ashrrev_i32_e32 v89, 31, v88
	v_cvt_pk_bf16_f32 v76, v76, v77
	v_cvt_pk_bf16_f32 v77, v78, v79
	v_cvt_pk_bf16_f32 v78, v72, v73
	v_or_b32_e32 v72, 48, v136
	global_store_dwordx4 v[44:45], v[28:31], off offset:256
	v_cvt_pk_bf16_f32 v111, v106, v107
	v_lshl_add_u64 v[104:105], s[18:19], 0, v[104:105]
	v_add_co_u32_e32 v30, vcc, s67, v146
	v_lshlrev_b64 v[88:89], 11, v[88:89]
	v_ashrrev_i32_e32 v73, 31, v72
	v_lshl_add_u64 v[28:29], v[146:147], 0, s[36:37]
	v_addc_co_u32_e32 v31, vcc, 0, v147, vcc
	v_cvt_pk_bf16_f32 v12, v12, v13
	v_cvt_pk_bf16_f32 v13, v14, v15
	v_cvt_pk_bf16_f32 v14, v8, v9
	v_cvt_pk_bf16_f32 v15, v10, v11
	global_store_dwordx4 v[146:147], v[108:111], off offset:256
	v_cvt_pk_bf16_f32 v95, v90, v91
	v_lshl_add_u64 v[88:89], s[18:19], 0, v[88:89]
	v_lshl_add_u64 v[108:109], v[104:105], 0, v[144:145]
	v_lshlrev_b64 v[72:73], 11, v[72:73]
	global_store_dwordx4 v[28:29], v[12:15], off offset:256
	global_store_dwordx4 v[108:109], v[92:95], off offset:256
	v_cvt_pk_bf16_f32 v79, v74, v75
	v_add_co_u32_e32 v14, vcc, s68, v146
	v_lshl_add_u64 v[92:93], v[88:89], 0, v[144:145]
	v_lshl_add_u64 v[72:73], s[18:19], 0, v[72:73]
	v_addc_co_u32_e32 v15, vcc, 0, v147, vcc
	v_cvt_pk_bf16_f32 v124, v124, v125
	v_cvt_pk_bf16_f32 v125, v126, v127
	v_cvt_pk_bf16_f32 v126, v120, v121
	v_cvt_pk_bf16_f32 v127, v122, v123
	v_cvt_pk_bf16_f32 v104, v116, v117
	v_cvt_pk_bf16_f32 v105, v118, v119
	v_cvt_pk_bf16_f32 v106, v112, v113
	v_cvt_pk_bf16_f32 v107, v114, v115
	v_cvt_pk_bf16_f32 v88, v100, v101
	v_cvt_pk_bf16_f32 v89, v102, v103
	v_cvt_pk_bf16_f32 v90, v96, v97
	v_cvt_pk_bf16_f32 v91, v98, v99
	global_store_dwordx4 v[92:93], v[76:79], off offset:256
	v_cvt_pk_bf16_f32 v74, v80, v81
	v_cvt_pk_bf16_f32 v75, v82, v83
	v_lshl_add_u64 v[76:77], v[72:73], 0, v[144:145]
	v_cvt_pk_bf16_f32 v72, v84, v85
	v_cvt_pk_bf16_f32 v73, v86, v87
	v_cvt_pk_bf16_f32 v71, v66, v67
	v_cvt_pk_bf16_f32 v63, v58, v59
	v_cvt_pk_bf16_f32 v40, v52, v53
	v_cvt_pk_bf16_f32 v41, v54, v55
	v_cvt_pk_bf16_f32 v42, v48, v49
	v_cvt_pk_bf16_f32 v43, v50, v51
	v_cvt_pk_bf16_f32 v24, v36, v37
	v_cvt_pk_bf16_f32 v25, v38, v39
	v_cvt_pk_bf16_f32 v26, v32, v33
	v_cvt_pk_bf16_f32 v27, v34, v35
	v_lshl_add_u64 v[12:13], v[146:147], 0, s[2:3]
	v_cvt_pk_bf16_f32 v8, v20, v21
	v_cvt_pk_bf16_f32 v9, v22, v23
	v_cvt_pk_bf16_f32 v10, v16, v17
	v_cvt_pk_bf16_f32 v11, v18, v19
	v_cvt_pk_bf16_f32 v4, v4, v5
	v_cvt_pk_bf16_f32 v5, v6, v7
	v_cvt_pk_bf16_f32 v6, v0, v1
	v_cvt_pk_bf16_f32 v7, v2, v3
	s_and_b64 vcc, exec, s[4:5]
	s_mov_b64 s[4:5], -1
	global_store_dwordx4 v[146:147], v[124:127], off
	global_store_dwordx4 v[108:109], v[104:107], off
	global_store_dwordx4 v[92:93], v[88:91], off
	global_store_dwordx4 v[76:77], v[72:75], off
	global_store_dwordx4 v[76:77], v[68:71], off offset:256
	global_store_dwordx4 v[56:57], v[60:63], off
	global_store_dwordx4 v[46:47], v[40:43], off
	global_store_dwordx4 v[30:31], v[24:27], off
	global_store_dwordx4 v[14:15], v[8:11], off
	global_store_dwordx4 v[12:13], v[4:7], off offset:256
	s_cbranch_vccnz .LBB0_243
	s_andn2_b64 vcc, exec, s[16:17]
	s_cbranch_vccnz .LBB0_242
	s_barrier
	s_branch .LBB0_242

.LBB0_392:
	s_lshl_b32 s0, s38, 8
	s_and_b32 s0, s0, 0x300
	s_or_b32 s0, s0, s88
	v_or_b32_e32 v223, s0, v222
	s_cmp_gt_i32 s38, 3
	s_mov_b64 s[0:1], -1
	s_cbranch_scc0 .LBB0_414
	s_cmp_gt_u32 s38, 15
	s_cbranch_scc0 .LBB0_411
	s_cmp_gt_u32 s38, 19
	s_cbranch_scc0 .LBB0_408
	s_cmp_gt_u32 s38, 23
	s_cbranch_scc0 .LBB0_405
	v_mul_f32_e32 v128, 0xbfb8aa3b, v124
	v_exp_f32_e32 v128, v128
	s_cmp_gt_u32 s38, 27
	v_add_f32_e32 v128, 1.0, v128
	v_rcp_f32_e32 v188, v128
	s_cbranch_scc0 .LBB0_402
	v_mul_f32_e32 v129, 0xbfb8aa3b, v126
	v_mul_f32_e32 v130, 0xbfb8aa3b, v127
	v_mul_f32_e32 v131, 0xbfb8aa3b, v120
	v_mul_f32_e32 v132, 0xbfb8aa3b, v121
	v_mul_f32_e32 v133, 0xbfb8aa3b, v122
	v_mul_f32_e32 v134, 0xbfb8aa3b, v123
	v_exp_f32_e32 v129, v129
	v_exp_f32_e32 v130, v130
	v_exp_f32_e32 v131, v131
	v_exp_f32_e32 v132, v132
	v_exp_f32_e32 v133, v133
	v_exp_f32_e32 v134, v134
	v_add_f32_e32 v129, 1.0, v129
	v_add_f32_e32 v130, 1.0, v130
	v_add_f32_e32 v131, 1.0, v131
	v_add_f32_e32 v132, 1.0, v132
	v_add_f32_e32 v133, 1.0, v133
	v_add_f32_e32 v134, 1.0, v134
	v_rcp_f32_e32 v129, v129
	v_rcp_f32_e32 v130, v130
	v_rcp_f32_e32 v131, v131
	v_rcp_f32_e32 v132, v132
	v_rcp_f32_e32 v133, v133
	v_rcp_f32_e32 v134, v134
	v_cvt_pk_bf16_f32 v129, v129, v130
	v_cvt_pk_bf16_f32 v130, v131, v132
	v_mul_f32_e32 v132, 0xbfb8aa3b, v112
	v_cvt_pk_bf16_f32 v131, v133, v134
	v_mul_f32_e32 v133, 0xbfb8aa3b, v113
	v_mul_f32_e32 v134, 0xbfb8aa3b, v114
	v_mul_f32_e32 v135, 0xbfb8aa3b, v115
	v_mul_f32_e32 v138, 0xbfb8aa3b, v106
	v_mul_f32_e32 v139, 0xbfb8aa3b, v107
	v_exp_f32_e32 v132, v132
	v_exp_f32_e32 v133, v133
	v_exp_f32_e32 v134, v134
	v_exp_f32_e32 v135, v135
	v_exp_f32_e32 v138, v138
	v_exp_f32_e32 v139, v139
	v_mul_f32_e32 v136, 0xbfb8aa3b, v104
	v_mul_f32_e32 v137, 0xbfb8aa3b, v105
	v_exp_f32_e32 v136, v136
	v_exp_f32_e32 v137, v137
	v_add_f32_e32 v132, 1.0, v132
	v_add_f32_e32 v133, 1.0, v133
	v_add_f32_e32 v134, 1.0, v134
	v_add_f32_e32 v135, 1.0, v135
	v_add_f32_e32 v138, 1.0, v138
	v_add_f32_e32 v139, 1.0, v139
	v_rcp_f32_e32 v132, v132
	v_rcp_f32_e32 v133, v133
	v_rcp_f32_e32 v134, v134
	v_rcp_f32_e32 v135, v135
	v_rcp_f32_e32 v138, v138
	v_rcp_f32_e32 v139, v139
	v_add_f32_e32 v136, 1.0, v136
	v_add_f32_e32 v137, 1.0, v137
	v_rcp_f32_e32 v136, v136
	v_rcp_f32_e32 v137, v137
	v_cvt_pk_bf16_f32 v132, v132, v133
	v_cvt_pk_bf16_f32 v133, v134, v135
	v_cvt_pk_bf16_f32 v135, v138, v139
	v_mul_f32_e32 v138, 0xbfb8aa3b, v96
	v_mul_f32_e32 v139, 0xbfb8aa3b, v97
	v_exp_f32_e32 v138, v138
	v_exp_f32_e32 v139, v139
	v_cvt_pk_bf16_f32 v134, v136, v137
	v_or_b32_e32 v136, 16, v186
	v_ashrrev_i32_e32 v137, 31, v136
	v_lshlrev_b64 v[192:193], 11, v[136:137]
	v_add_f32_e32 v136, 1.0, v138
	v_add_f32_e32 v137, 1.0, v139
	v_mul_f32_e32 v138, 0xbfb8aa3b, v98
	v_mul_f32_e32 v139, 0xbfb8aa3b, v99
	v_mul_f32_e32 v142, 0xbfb8aa3b, v90
	v_mul_f32_e32 v143, 0xbfb8aa3b, v91
	v_exp_f32_e32 v138, v138
	v_exp_f32_e32 v139, v139
	v_exp_f32_e32 v142, v142
	v_exp_f32_e32 v143, v143
	v_mul_f32_e32 v140, 0xbfb8aa3b, v88
	v_mul_f32_e32 v141, 0xbfb8aa3b, v89
	v_exp_f32_e32 v140, v140
	v_exp_f32_e32 v141, v141
	v_add_f32_e32 v138, 1.0, v138
	v_add_f32_e32 v139, 1.0, v139
	v_add_f32_e32 v142, 1.0, v142
	v_add_f32_e32 v143, 1.0, v143
	v_rcp_f32_e32 v136, v136
	v_rcp_f32_e32 v137, v137
	v_rcp_f32_e32 v138, v138
	v_rcp_f32_e32 v139, v139
	v_rcp_f32_e32 v142, v142
	v_rcp_f32_e32 v143, v143
	v_add_f32_e32 v140, 1.0, v140
	v_add_f32_e32 v141, 1.0, v141
	v_rcp_f32_e32 v140, v140
	v_rcp_f32_e32 v141, v141
	v_cvt_pk_bf16_f32 v136, v136, v137
	v_cvt_pk_bf16_f32 v137, v138, v139
	v_cvt_pk_bf16_f32 v139, v142, v143
	v_mul_f32_e32 v142, 0xbfb8aa3b, v80
	v_mul_f32_e32 v143, 0xbfb8aa3b, v81
	v_exp_f32_e32 v142, v142
	v_exp_f32_e32 v143, v143
	v_cvt_pk_bf16_f32 v138, v140, v141
	v_or_b32_e32 v140, 32, v186
	v_ashrrev_i32_e32 v141, 31, v140
	v_lshlrev_b64 v[194:195], 11, v[140:141]
	v_add_f32_e32 v140, 1.0, v142
	v_add_f32_e32 v141, 1.0, v143
	v_mul_f32_e32 v142, 0xbfb8aa3b, v82
	v_mul_f32_e32 v143, 0xbfb8aa3b, v83
	v_mul_f32_e32 v146, 0xbfb8aa3b, v74
	v_mul_f32_e32 v147, 0xbfb8aa3b, v75
	v_exp_f32_e32 v142, v142
	v_exp_f32_e32 v143, v143
	v_exp_f32_e32 v146, v146
	v_exp_f32_e32 v147, v147
	v_mul_f32_e32 v144, 0xbfb8aa3b, v72
	v_mul_f32_e32 v145, 0xbfb8aa3b, v73
	v_exp_f32_e32 v144, v144
	v_exp_f32_e32 v145, v145
	v_add_f32_e32 v142, 1.0, v142
	v_add_f32_e32 v143, 1.0, v143
	v_add_f32_e32 v146, 1.0, v146
	v_add_f32_e32 v147, 1.0, v147
	v_rcp_f32_e32 v140, v140
	v_rcp_f32_e32 v141, v141
	v_rcp_f32_e32 v142, v142
	v_rcp_f32_e32 v143, v143
	v_rcp_f32_e32 v146, v146
	v_rcp_f32_e32 v147, v147
	v_add_f32_e32 v144, 1.0, v144
	v_add_f32_e32 v145, 1.0, v145
	v_rcp_f32_e32 v144, v144
	v_rcp_f32_e32 v145, v145
	v_cvt_pk_bf16_f32 v140, v140, v141
	v_cvt_pk_bf16_f32 v141, v142, v143
	v_cvt_pk_bf16_f32 v143, v146, v147
	v_mul_f32_e32 v146, 0xbfb8aa3b, v60
	v_mul_f32_e32 v147, 0xbfb8aa3b, v61
	v_exp_f32_e32 v146, v146
	v_exp_f32_e32 v147, v147
	v_cvt_pk_bf16_f32 v142, v144, v145
	v_or_b32_e32 v144, 48, v186
	v_ashrrev_i32_e32 v145, 31, v144
	v_lshlrev_b64 v[196:197], 11, v[144:145]
	v_add_f32_e32 v144, 1.0, v146
	v_add_f32_e32 v145, 1.0, v147
	v_mul_f32_e32 v146, 0xbfb8aa3b, v62
	v_mul_f32_e32 v147, 0xbfb8aa3b, v63
	v_mul_f32_e32 v148, 0xbfb8aa3b, v56
	v_mul_f32_e32 v149, 0xbfb8aa3b, v57
	v_mul_f32_e32 v150, 0xbfb8aa3b, v58
	v_mul_f32_e32 v151, 0xbfb8aa3b, v59
	v_exp_f32_e32 v146, v146
	v_exp_f32_e32 v147, v147
	v_exp_f32_e32 v148, v148
	v_exp_f32_e32 v149, v149
	v_exp_f32_e32 v150, v150
	v_exp_f32_e32 v151, v151
	v_add_f32_e32 v146, 1.0, v146
	v_add_f32_e32 v147, 1.0, v147
	v_add_f32_e32 v148, 1.0, v148
	v_add_f32_e32 v149, 1.0, v149
	v_add_f32_e32 v150, 1.0, v150
	v_add_f32_e32 v151, 1.0, v151
	v_rcp_f32_e32 v144, v144
	v_rcp_f32_e32 v145, v145
	v_rcp_f32_e32 v146, v146
	v_rcp_f32_e32 v147, v147
	v_rcp_f32_e32 v148, v148
	v_rcp_f32_e32 v149, v149
	v_rcp_f32_e32 v150, v150
	v_rcp_f32_e32 v151, v151
	v_cvt_pk_bf16_f32 v144, v144, v145
	v_cvt_pk_bf16_f32 v145, v146, v147
	v_cvt_pk_bf16_f32 v146, v148, v149
	v_cvt_pk_bf16_f32 v147, v150, v151
	v_mul_f32_e32 v148, 0xbfb8aa3b, v48
	v_mul_f32_e32 v149, 0xbfb8aa3b, v49
	v_mul_f32_e32 v150, 0xbfb8aa3b, v50
	v_mul_f32_e32 v151, 0xbfb8aa3b, v51
	v_mul_f32_e32 v152, 0xbfb8aa3b, v40
	v_mul_f32_e32 v153, 0xbfb8aa3b, v41
	v_mul_f32_e32 v154, 0xbfb8aa3b, v42
	v_mul_f32_e32 v155, 0xbfb8aa3b, v43
	v_exp_f32_e32 v148, v148
	v_exp_f32_e32 v149, v149
	v_exp_f32_e32 v150, v150
	v_exp_f32_e32 v151, v151
	v_exp_f32_e32 v152, v152
	v_exp_f32_e32 v153, v153
	v_exp_f32_e32 v154, v154
	v_exp_f32_e32 v155, v155
	v_add_f32_e32 v148, 1.0, v148
	v_add_f32_e32 v149, 1.0, v149
	v_add_f32_e32 v150, 1.0, v150
	v_add_f32_e32 v151, 1.0, v151
	v_add_f32_e32 v152, 1.0, v152
	v_add_f32_e32 v153, 1.0, v153
	v_add_f32_e32 v154, 1.0, v154
	v_add_f32_e32 v155, 1.0, v155
	v_rcp_f32_e32 v148, v148
	v_rcp_f32_e32 v149, v149
	v_rcp_f32_e32 v150, v150
	v_rcp_f32_e32 v151, v151
	v_rcp_f32_e32 v152, v152
	v_rcp_f32_e32 v153, v153
	v_rcp_f32_e32 v154, v154
	v_rcp_f32_e32 v155, v155
	v_cvt_pk_bf16_f32 v148, v148, v149
	v_cvt_pk_bf16_f32 v149, v150, v151
	v_cvt_pk_bf16_f32 v150, v152, v153
	v_cvt_pk_bf16_f32 v151, v154, v155
	v_mul_f32_e32 v152, 0xbfb8aa3b, v32
	v_mul_f32_e32 v153, 0xbfb8aa3b, v33
	v_mul_f32_e32 v154, 0xbfb8aa3b, v34
	v_mul_f32_e32 v155, 0xbfb8aa3b, v35
	v_mul_f32_e32 v156, 0xbfb8aa3b, v24
	v_mul_f32_e32 v157, 0xbfb8aa3b, v25
	v_mul_f32_e32 v158, 0xbfb8aa3b, v26
	v_mul_f32_e32 v159, 0xbfb8aa3b, v27
	v_exp_f32_e32 v152, v152
	v_exp_f32_e32 v153, v153
	v_exp_f32_e32 v154, v154
	v_exp_f32_e32 v155, v155
	v_exp_f32_e32 v156, v156
	v_exp_f32_e32 v157, v157
	v_exp_f32_e32 v158, v158
	v_exp_f32_e32 v159, v159
	v_add_f32_e32 v152, 1.0, v152
	v_add_f32_e32 v153, 1.0, v153
	v_add_f32_e32 v154, 1.0, v154
	v_add_f32_e32 v155, 1.0, v155
	v_add_f32_e32 v156, 1.0, v156
	v_add_f32_e32 v157, 1.0, v157
	v_add_f32_e32 v158, 1.0, v158
	v_add_f32_e32 v159, 1.0, v159
	v_rcp_f32_e32 v152, v152
	v_rcp_f32_e32 v153, v153
	v_rcp_f32_e32 v154, v154
	v_rcp_f32_e32 v155, v155
	v_rcp_f32_e32 v156, v156
	v_rcp_f32_e32 v157, v157
	v_rcp_f32_e32 v158, v158
	v_rcp_f32_e32 v159, v159
	v_cvt_pk_bf16_f32 v152, v152, v153
	v_cvt_pk_bf16_f32 v153, v154, v155
	v_cvt_pk_bf16_f32 v154, v156, v157
	v_cvt_pk_bf16_f32 v155, v158, v159
	v_mul_f32_e32 v156, 0xbfb8aa3b, v16
	v_mul_f32_e32 v157, 0xbfb8aa3b, v17
	v_mul_f32_e32 v158, 0xbfb8aa3b, v18
	v_mul_f32_e32 v159, 0xbfb8aa3b, v19
	v_mul_f32_e32 v160, 0xbfb8aa3b, v8
	v_mul_f32_e32 v161, 0xbfb8aa3b, v9
	v_mul_f32_e32 v162, 0xbfb8aa3b, v10
	v_mul_f32_e32 v163, 0xbfb8aa3b, v11
	v_exp_f32_e32 v156, v156
	v_exp_f32_e32 v157, v157
	v_exp_f32_e32 v158, v158
	v_exp_f32_e32 v159, v159
	v_exp_f32_e32 v160, v160
	v_exp_f32_e32 v161, v161
	v_exp_f32_e32 v162, v162
	v_exp_f32_e32 v163, v163
	v_add_f32_e32 v156, 1.0, v156
	v_add_f32_e32 v157, 1.0, v157
	v_add_f32_e32 v158, 1.0, v158
	v_add_f32_e32 v159, 1.0, v159
	v_add_f32_e32 v160, 1.0, v160
	v_add_f32_e32 v161, 1.0, v161
	v_add_f32_e32 v162, 1.0, v162
	v_add_f32_e32 v163, 1.0, v163
	v_rcp_f32_e32 v156, v156
	v_rcp_f32_e32 v157, v157
	v_rcp_f32_e32 v158, v158
	v_rcp_f32_e32 v159, v159
	v_rcp_f32_e32 v160, v160
	v_rcp_f32_e32 v161, v161
	v_rcp_f32_e32 v162, v162
	v_rcp_f32_e32 v163, v163
	v_cvt_pk_bf16_f32 v156, v156, v157
	v_cvt_pk_bf16_f32 v157, v158, v159
	v_cvt_pk_bf16_f32 v158, v160, v161
	v_cvt_pk_bf16_f32 v159, v162, v163
	v_mul_f32_e32 v160, 0xbfb8aa3b, v116
	v_mul_f32_e32 v161, 0xbfb8aa3b, v117
	v_mul_f32_e32 v162, 0xbfb8aa3b, v118
	v_mul_f32_e32 v163, 0xbfb8aa3b, v119
	v_exp_f32_e32 v160, v160
	v_exp_f32_e32 v161, v161
	v_exp_f32_e32 v162, v162
	v_exp_f32_e32 v163, v163
	v_mul_f32_e32 v164, 0xbfb8aa3b, v108
	v_mul_f32_e32 v165, 0xbfb8aa3b, v109
	v_exp_f32_e32 v164, v164
	v_exp_f32_e32 v165, v165
	v_mul_f32_e32 v166, 0xbfb8aa3b, v110
	v_mul_f32_e32 v167, 0xbfb8aa3b, v111
	v_exp_f32_e32 v166, v166
	v_exp_f32_e32 v167, v167
	v_add_f32_e32 v160, 1.0, v160
	v_add_f32_e32 v161, 1.0, v161
	v_add_f32_e32 v162, 1.0, v162
	v_add_f32_e32 v163, 1.0, v163
	v_rcp_f32_e32 v160, v160
	v_rcp_f32_e32 v161, v161
	v_rcp_f32_e32 v162, v162
	v_rcp_f32_e32 v163, v163
	v_add_f32_e32 v164, 1.0, v164
	v_add_f32_e32 v165, 1.0, v165
	v_rcp_f32_e32 v164, v164
	v_rcp_f32_e32 v165, v165
	v_add_f32_e32 v166, 1.0, v166
	v_add_f32_e32 v167, 1.0, v167
	v_rcp_f32_e32 v166, v166
	v_rcp_f32_e32 v167, v167
	v_cvt_pk_bf16_f32 v160, v160, v161
	v_cvt_pk_bf16_f32 v161, v162, v163
	v_mul_f32_e32 v163, 0xbfb8aa3b, v100
	v_ashrrev_i32_e32 v187, 31, v186
	v_cvt_pk_bf16_f32 v162, v164, v165
	v_exp_f32_e32 v164, v163
	v_mul_f32_e32 v163, 0xbfb8aa3b, v101
	v_mul_f32_e32 v128, 0xbfb8aa3b, v125
	v_lshlrev_b64 v[190:191], 11, v[186:187]
	v_exp_f32_e32 v165, v163
	v_cvt_pk_bf16_f32 v163, v166, v167
	v_mul_f32_e32 v166, 0xbfb8aa3b, v102
	v_mul_f32_e32 v167, 0xbfb8aa3b, v103
	v_mul_f32_e32 v172, 0xbfb8aa3b, v92
	v_mul_f32_e32 v187, 0xbfb8aa3b, v93
	v_mul_f32_e32 v189, 0xbfb8aa3b, v94
	v_mul_f32_e32 v206, 0xbfb8aa3b, v95
	v_exp_f32_e32 v128, v128
	v_exp_f32_e32 v166, v166
	v_exp_f32_e32 v167, v167
	v_exp_f32_e32 v172, v172
	v_exp_f32_e32 v187, v187
	v_exp_f32_e32 v189, v189
	v_exp_f32_e32 v206, v206
	v_add_f32_e32 v128, 1.0, v128
	v_add_f32_e32 v164, 1.0, v164
	v_add_f32_e32 v165, 1.0, v165
	v_add_f32_e32 v166, 1.0, v166
	v_add_f32_e32 v167, 1.0, v167
	v_add_f32_e32 v172, 1.0, v172
	v_add_f32_e32 v187, 1.0, v187
	v_add_f32_e32 v189, 1.0, v189
	v_add_f32_e32 v206, 1.0, v206
	v_rcp_f32_e32 v128, v128
	v_rcp_f32_e32 v164, v164
	v_rcp_f32_e32 v165, v165
	v_rcp_f32_e32 v166, v166
	v_rcp_f32_e32 v167, v167
	v_rcp_f32_e32 v172, v172
	v_rcp_f32_e32 v187, v187
	v_rcp_f32_e32 v189, v189
	v_rcp_f32_e32 v206, v206
	s_mov_b64 s[0:1], 0x48000
	v_lshl_add_u64 v[200:201], v[190:191], 0, s[0:1]
	s_mov_b64 s[0:1], 0x50000
	v_lshl_add_u64 v[202:203], v[190:191], 0, s[0:1]
	s_mov_b64 s[0:1], 0x58000
	s_cmp_gt_u32 s38, 31
	v_cvt_pk_bf16_f32 v128, v188, v128
	v_lshl_add_u64 v[198:199], v[190:191], 0, s[4:5]
	v_lshl_add_u64 v[204:205], v[190:191], 0, s[0:1]
	v_cvt_pk_bf16_f32 v164, v164, v165
	v_cvt_pk_bf16_f32 v165, v166, v167
	v_cvt_pk_bf16_f32 v166, v172, v187
	v_cvt_pk_bf16_f32 v167, v189, v206
	s_mov_b64 s[0:1], -1
	s_cbranch_scc0 .LBB0_399
	v_readlane_b32 s0, v250, 2
	v_lshlrev_b32_e32 v172, 1, v223
	v_readlane_b32 s1, v250, 3
	v_mul_f32_e32 v187, 0xbfb8aa3b, v85
	v_mul_f32_e32 v189, 0xbfb8aa3b, v86
	v_lshl_add_u64 v[206:207], s[0:1], 0, v[172:173]
	v_lshl_add_u64 v[224:225], v[206:207], 0, v[190:191]
	v_lshl_add_u64 v[226:227], v[206:207], 0, v[192:193]
	v_lshl_add_u64 v[228:229], v[206:207], 0, v[194:195]
	v_lshl_add_u64 v[230:231], v[206:207], 0, v[196:197]
	v_lshl_add_u64 v[232:233], v[206:207], 0, v[198:199]
	v_lshl_add_u64 v[234:235], v[206:207], 0, v[200:201]
	v_lshl_add_u64 v[208:209], v[206:207], 0, v[202:203]
	v_lshl_add_u64 v[206:207], v[206:207], 0, v[204:205]
	global_store_dwordx4 v[224:225], v[128:131], off
	global_store_dwordx4 v[226:227], v[132:135], off
	global_store_dwordx4 v[228:229], v[136:139], off
	global_store_dwordx4 v[230:231], v[140:143], off
	global_store_dwordx4 v[232:233], v[144:147], off
	global_store_dwordx4 v[234:235], v[148:151], off
	global_store_dwordx4 v[208:209], v[152:155], off
	global_store_dwordx4 v[206:207], v[156:159], off
	global_store_dwordx4 v[224:225], v[160:163], off offset:256
	v_mul_f32_e32 v224, 0xbfb8aa3b, v87
	v_exp_f32_e32 v224, v224
	v_mul_f32_e32 v225, 0xbfb8aa3b, v76
	global_store_dwordx4 v[226:227], v[164:167], off offset:256
	v_exp_f32_e32 v225, v225
	v_mul_f32_e32 v226, 0xbfb8aa3b, v77
	v_exp_f32_e32 v226, v226
	v_add_f32_e32 v224, 1.0, v224
	v_rcp_f32_e32 v227, v224
	v_add_f32_e32 v224, 1.0, v225
	v_mul_f32_e32 v225, 0xbfb8aa3b, v78
	v_mul_f32_e32 v172, 0xbfb8aa3b, v84
	v_rcp_f32_e32 v236, v224
	v_add_f32_e32 v224, 1.0, v226
	v_exp_f32_e32 v225, v225
	v_mul_f32_e32 v226, 0xbfb8aa3b, v79
	v_exp_f32_e32 v172, v172
	v_exp_f32_e32 v187, v187
	v_exp_f32_e32 v189, v189
	v_exp_f32_e32 v226, v226
	v_rcp_f32_e32 v237, v224
	v_add_f32_e32 v224, 1.0, v225
	v_add_f32_e32 v172, 1.0, v172
	v_add_f32_e32 v187, 1.0, v187
	v_add_f32_e32 v189, 1.0, v189
	v_rcp_f32_e32 v238, v224
	v_add_f32_e32 v224, 1.0, v226
	v_rcp_f32_e32 v172, v172
	v_rcp_f32_e32 v187, v187
	v_rcp_f32_e32 v189, v189
	v_rcp_f32_e32 v239, v224
	v_cvt_pk_bf16_f32 v226, v236, v237
	v_cvt_pk_bf16_f32 v224, v172, v187
	v_cvt_pk_bf16_f32 v225, v189, v227
	v_cvt_pk_bf16_f32 v227, v238, v239
	global_store_dwordx4 v[228:229], v[224:227], off offset:256
	v_mul_f32_e32 v172, 0xbfb8aa3b, v68
	v_mul_f32_e32 v187, 0xbfb8aa3b, v69
	v_mul_f32_e32 v224, 0xbfb8aa3b, v71
	v_exp_f32_e32 v224, v224
	v_mul_f32_e32 v225, 0xbfb8aa3b, v64
	v_exp_f32_e32 v225, v225
	v_mul_f32_e32 v226, 0xbfb8aa3b, v65
	v_exp_f32_e32 v226, v226
	v_add_f32_e32 v224, 1.0, v224
	v_rcp_f32_e32 v227, v224
	v_add_f32_e32 v224, 1.0, v225
	v_mul_f32_e32 v225, 0xbfb8aa3b, v66
	v_mul_f32_e32 v189, 0xbfb8aa3b, v70
	v_rcp_f32_e32 v228, v224
	v_add_f32_e32 v224, 1.0, v226
	v_exp_f32_e32 v225, v225
	v_mul_f32_e32 v226, 0xbfb8aa3b, v67
	v_exp_f32_e32 v172, v172
	v_exp_f32_e32 v187, v187
	v_exp_f32_e32 v189, v189
	v_exp_f32_e32 v226, v226
	v_rcp_f32_e32 v229, v224
	v_add_f32_e32 v224, 1.0, v225
	v_add_f32_e32 v172, 1.0, v172
	v_add_f32_e32 v187, 1.0, v187
	v_add_f32_e32 v189, 1.0, v189
	v_rcp_f32_e32 v236, v224
	v_add_f32_e32 v224, 1.0, v226
	v_rcp_f32_e32 v172, v172
	v_rcp_f32_e32 v187, v187
	v_rcp_f32_e32 v189, v189
	v_rcp_f32_e32 v237, v224
	v_cvt_pk_bf16_f32 v226, v228, v229
	v_cvt_pk_bf16_f32 v224, v172, v187
	v_cvt_pk_bf16_f32 v225, v189, v227
	v_cvt_pk_bf16_f32 v227, v236, v237
	global_store_dwordx4 v[230:231], v[224:227], off offset:256
	v_mul_f32_e32 v172, 0xbfb8aa3b, v52
	v_mul_f32_e32 v187, 0xbfb8aa3b, v53
	v_mul_f32_e32 v224, 0xbfb8aa3b, v55
	v_exp_f32_e32 v224, v224
	v_mul_f32_e32 v225, 0xbfb8aa3b, v44
	v_exp_f32_e32 v225, v225
	v_mul_f32_e32 v226, 0xbfb8aa3b, v45
	v_exp_f32_e32 v226, v226
	v_add_f32_e32 v224, 1.0, v224
	v_rcp_f32_e32 v227, v224
	v_add_f32_e32 v224, 1.0, v225
	v_mul_f32_e32 v225, 0xbfb8aa3b, v46
	v_mul_f32_e32 v189, 0xbfb8aa3b, v54
	v_rcp_f32_e32 v228, v224
	v_add_f32_e32 v224, 1.0, v226
	v_exp_f32_e32 v225, v225
	v_mul_f32_e32 v226, 0xbfb8aa3b, v47
	v_exp_f32_e32 v172, v172
	v_exp_f32_e32 v187, v187
	v_exp_f32_e32 v189, v189
	v_exp_f32_e32 v226, v226
	v_rcp_f32_e32 v229, v224
	v_add_f32_e32 v224, 1.0, v225
	v_add_f32_e32 v172, 1.0, v172
	v_add_f32_e32 v187, 1.0, v187
	v_add_f32_e32 v189, 1.0, v189
	v_rcp_f32_e32 v230, v224
	v_add_f32_e32 v224, 1.0, v226
	v_rcp_f32_e32 v172, v172
	v_rcp_f32_e32 v187, v187
	v_rcp_f32_e32 v189, v189
	v_rcp_f32_e32 v231, v224
	v_cvt_pk_bf16_f32 v226, v228, v229
	v_cvt_pk_bf16_f32 v224, v172, v187
	v_cvt_pk_bf16_f32 v225, v189, v227
	v_cvt_pk_bf16_f32 v227, v230, v231
	global_store_dwordx4 v[232:233], v[224:227], off offset:256
	v_mul_f32_e32 v172, 0xbfb8aa3b, v36
	v_mul_f32_e32 v187, 0xbfb8aa3b, v37
	v_mul_f32_e32 v224, 0xbfb8aa3b, v39
	v_exp_f32_e32 v224, v224
	v_mul_f32_e32 v225, 0xbfb8aa3b, v28
	v_exp_f32_e32 v225, v225
	v_mul_f32_e32 v226, 0xbfb8aa3b, v29
	v_exp_f32_e32 v226, v226
	v_add_f32_e32 v224, 1.0, v224
	v_rcp_f32_e32 v227, v224
	v_add_f32_e32 v224, 1.0, v225
	v_mul_f32_e32 v225, 0xbfb8aa3b, v30
	v_mul_f32_e32 v189, 0xbfb8aa3b, v38
	v_rcp_f32_e32 v228, v224
	v_add_f32_e32 v224, 1.0, v226
	v_exp_f32_e32 v225, v225
	v_mul_f32_e32 v226, 0xbfb8aa3b, v31
	v_exp_f32_e32 v172, v172
	v_exp_f32_e32 v187, v187
	v_exp_f32_e32 v189, v189
	v_exp_f32_e32 v226, v226
	v_rcp_f32_e32 v229, v224
	v_add_f32_e32 v224, 1.0, v225
	v_add_f32_e32 v172, 1.0, v172
	v_add_f32_e32 v187, 1.0, v187
	v_add_f32_e32 v189, 1.0, v189
	v_rcp_f32_e32 v230, v224
	v_add_f32_e32 v224, 1.0, v226
	v_rcp_f32_e32 v172, v172
	v_rcp_f32_e32 v187, v187
	v_rcp_f32_e32 v189, v189
	v_rcp_f32_e32 v231, v224
	v_cvt_pk_bf16_f32 v226, v228, v229
	v_cvt_pk_bf16_f32 v224, v172, v187
	v_cvt_pk_bf16_f32 v225, v189, v227
	v_cvt_pk_bf16_f32 v227, v230, v231
	global_store_dwordx4 v[234:235], v[224:227], off offset:256
	v_mul_f32_e32 v172, 0xbfb8aa3b, v20
	v_mul_f32_e32 v187, 0xbfb8aa3b, v21
	v_mul_f32_e32 v224, 0xbfb8aa3b, v23
	v_exp_f32_e32 v224, v224
	v_mul_f32_e32 v225, 0xbfb8aa3b, v12
	v_exp_f32_e32 v225, v225
	v_mul_f32_e32 v226, 0xbfb8aa3b, v13
	v_exp_f32_e32 v226, v226
	v_add_f32_e32 v224, 1.0, v224
	v_rcp_f32_e32 v227, v224
	v_add_f32_e32 v224, 1.0, v225
	v_mul_f32_e32 v225, 0xbfb8aa3b, v14
	v_mul_f32_e32 v189, 0xbfb8aa3b, v22
	v_rcp_f32_e32 v228, v224
	v_add_f32_e32 v224, 1.0, v226
	v_exp_f32_e32 v225, v225
	v_mul_f32_e32 v226, 0xbfb8aa3b, v15
	v_exp_f32_e32 v172, v172
	v_exp_f32_e32 v187, v187
	v_exp_f32_e32 v189, v189
	v_exp_f32_e32 v226, v226
	v_rcp_f32_e32 v229, v224
	v_add_f32_e32 v224, 1.0, v225
	v_add_f32_e32 v172, 1.0, v172
	v_add_f32_e32 v187, 1.0, v187
	v_add_f32_e32 v189, 1.0, v189
	v_rcp_f32_e32 v230, v224
	v_add_f32_e32 v224, 1.0, v226
	v_rcp_f32_e32 v172, v172
	v_rcp_f32_e32 v187, v187
	v_rcp_f32_e32 v189, v189
	v_rcp_f32_e32 v231, v224
	v_cvt_pk_bf16_f32 v226, v228, v229
	v_cvt_pk_bf16_f32 v224, v172, v187
	v_cvt_pk_bf16_f32 v225, v189, v227
	v_cvt_pk_bf16_f32 v227, v230, v231
	global_store_dwordx4 v[208:209], v[224:227], off offset:256
	v_mul_f32_e32 v172, 0xbfb8aa3b, v4
	v_mul_f32_e32 v187, 0xbfb8aa3b, v5
	v_mul_f32_e32 v224, 0xbfb8aa3b, v1
	v_exp_f32_e32 v224, v224
	v_mul_f32_e32 v225, 0xbfb8aa3b, v2
	v_mul_f32_e32 v189, 0xbfb8aa3b, v6
	v_mul_f32_e32 v208, 0xbfb8aa3b, v7
	v_mul_f32_e32 v209, 0xbfb8aa3b, v0
	v_exp_f32_e32 v225, v225
	v_mul_f32_e32 v226, 0xbfb8aa3b, v3
	v_exp_f32_e32 v172, v172
	v_exp_f32_e32 v187, v187
	v_exp_f32_e32 v189, v189
	v_exp_f32_e32 v208, v208
	v_exp_f32_e32 v209, v209
	v_exp_f32_e32 v226, v226
	v_add_f32_e32 v224, 1.0, v224
	v_rcp_f32_e32 v227, v224
	v_add_f32_e32 v224, 1.0, v225
	v_add_f32_e32 v172, 1.0, v172
	v_add_f32_e32 v187, 1.0, v187
	v_add_f32_e32 v189, 1.0, v189
	v_add_f32_e32 v208, 1.0, v208
	v_add_f32_e32 v209, 1.0, v209
	v_rcp_f32_e32 v228, v224
	v_add_f32_e32 v224, 1.0, v226
	v_rcp_f32_e32 v172, v172
	v_rcp_f32_e32 v187, v187
	v_rcp_f32_e32 v189, v189
	v_rcp_f32_e32 v208, v208
	v_rcp_f32_e32 v209, v209
	v_rcp_f32_e32 v229, v224
	v_cvt_pk_bf16_f32 v224, v172, v187
	v_cvt_pk_bf16_f32 v225, v189, v208
	v_cvt_pk_bf16_f32 v226, v209, v227
	v_cvt_pk_bf16_f32 v227, v228, v229
	global_store_dwordx4 v[206:207], v[224:227], off offset:256
	s_mov_b64 s[0:1], 0
.LBB0_399:
	s_andn2_b64 vcc, exec, s[0:1]
	s_cbranch_vccnz .LBB0_401
	v_readlane_b32 s0, v250, 0
	v_lshlrev_b32_e32 v172, 1, v223
	v_readlane_b32 s1, v250, 1
	s_nop 1
	v_lshl_add_u64 v[206:207], s[0:1], 0, v[172:173]
	v_lshl_add_u64 v[194:195], v[206:207], 0, v[194:195]
	v_lshl_add_u64 v[192:193], v[206:207], 0, v[192:193]
	global_store_dwordx4 v[194:195], v[136:139], off
	global_store_dwordx4 v[192:193], v[132:135], off
	v_lshl_add_u64 v[190:191], v[206:207], 0, v[190:191]
	v_lshl_add_u64 v[136:137], v[206:207], 0, v[196:197]
	global_store_dwordx4 v[136:137], v[140:143], off
	v_mul_f32_e32 v132, 0xbfb8aa3b, v84
	v_mul_f32_e32 v133, 0xbfb8aa3b, v85
	v_mul_f32_e32 v134, 0xbfb8aa3b, v86
	v_mul_f32_e32 v135, 0xbfb8aa3b, v87
	v_mul_f32_e32 v142, 0xbfb8aa3b, v76
	v_mul_f32_e32 v143, 0xbfb8aa3b, v77
	v_exp_f32_e32 v132, v132
	v_exp_f32_e32 v133, v133
	v_exp_f32_e32 v134, v134
	v_exp_f32_e32 v135, v135
	v_exp_f32_e32 v142, v142
	v_exp_f32_e32 v143, v143
	v_lshl_add_u64 v[138:139], v[206:207], 0, v[198:199]
	global_store_dwordx4 v[138:139], v[144:147], off
	v_add_f32_e32 v132, 1.0, v132
	v_add_f32_e32 v133, 1.0, v133
	v_mul_f32_e32 v144, 0xbfb8aa3b, v78
	v_mul_f32_e32 v145, 0xbfb8aa3b, v79
	v_add_f32_e32 v134, 1.0, v134
	v_add_f32_e32 v135, 1.0, v135
	v_add_f32_e32 v142, 1.0, v142
	v_add_f32_e32 v143, 1.0, v143
	v_exp_f32_e32 v144, v144
	v_exp_f32_e32 v145, v145
	v_rcp_f32_e32 v132, v132
	v_rcp_f32_e32 v133, v133
	v_rcp_f32_e32 v134, v134
	v_rcp_f32_e32 v135, v135
	v_rcp_f32_e32 v142, v142
	v_rcp_f32_e32 v143, v143
	v_add_f32_e32 v144, 1.0, v144
	v_add_f32_e32 v145, 1.0, v145
	v_rcp_f32_e32 v144, v144
	v_rcp_f32_e32 v145, v145
	v_cvt_pk_bf16_f32 v132, v132, v133
	v_cvt_pk_bf16_f32 v133, v134, v135
	v_cvt_pk_bf16_f32 v134, v142, v143
	v_mul_f32_e32 v142, 0xbfb8aa3b, v68
	v_mul_f32_e32 v143, 0xbfb8aa3b, v69
	v_exp_f32_e32 v142, v142
	v_exp_f32_e32 v143, v143
	global_store_dwordx4 v[190:191], v[128:131], off
	v_lshl_add_u64 v[140:141], v[206:207], 0, v[200:201]
	v_cvt_pk_bf16_f32 v135, v144, v145
	v_lshl_add_u64 v[130:131], v[206:207], 0, v[202:203]
	v_lshl_add_u64 v[128:129], v[206:207], 0, v[204:205]
	global_store_dwordx4 v[140:141], v[148:151], off
	global_store_dwordx4 v[130:131], v[152:155], off
	global_store_dwordx4 v[128:129], v[156:159], off
	global_store_dwordx4 v[190:191], v[160:163], off offset:256
	global_store_dwordx4 v[194:195], v[132:135], off offset:256
	v_mul_f32_e32 v144, 0xbfb8aa3b, v66
	v_mul_f32_e32 v145, 0xbfb8aa3b, v67
	v_add_f32_e32 v132, 1.0, v142
	v_add_f32_e32 v133, 1.0, v143
	v_mul_f32_e32 v134, 0xbfb8aa3b, v70
	v_mul_f32_e32 v135, 0xbfb8aa3b, v71
	v_mul_f32_e32 v142, 0xbfb8aa3b, v64
	v_mul_f32_e32 v143, 0xbfb8aa3b, v65
	v_exp_f32_e32 v134, v134
	v_exp_f32_e32 v135, v135
	v_exp_f32_e32 v142, v142
	v_exp_f32_e32 v143, v143
	v_exp_f32_e32 v144, v144
	v_exp_f32_e32 v145, v145
	v_add_f32_e32 v134, 1.0, v134
	v_add_f32_e32 v135, 1.0, v135
	v_add_f32_e32 v142, 1.0, v142
	v_add_f32_e32 v143, 1.0, v143
	v_add_f32_e32 v144, 1.0, v144
	v_add_f32_e32 v145, 1.0, v145
	v_rcp_f32_e32 v132, v132
	v_rcp_f32_e32 v133, v133
	v_rcp_f32_e32 v134, v134
	v_rcp_f32_e32 v135, v135
	v_rcp_f32_e32 v142, v142
	v_rcp_f32_e32 v143, v143
	v_rcp_f32_e32 v144, v144
	v_rcp_f32_e32 v145, v145
	v_cvt_pk_bf16_f32 v132, v132, v133
	v_cvt_pk_bf16_f32 v133, v134, v135
	v_cvt_pk_bf16_f32 v134, v142, v143
	v_cvt_pk_bf16_f32 v135, v144, v145
	v_mul_f32_e32 v142, 0xbfb8aa3b, v52
	v_mul_f32_e32 v143, 0xbfb8aa3b, v53
	v_exp_f32_e32 v142, v142
	v_exp_f32_e32 v143, v143
	global_store_dwordx4 v[136:137], v[132:135], off offset:256
	v_mul_f32_e32 v136, 0xbfb8aa3b, v44
	v_mul_f32_e32 v137, 0xbfb8aa3b, v45
	v_mul_f32_e32 v134, 0xbfb8aa3b, v54
	v_mul_f32_e32 v135, 0xbfb8aa3b, v55
	v_exp_f32_e32 v134, v134
	v_exp_f32_e32 v135, v135
	v_exp_f32_e32 v136, v136
	v_exp_f32_e32 v137, v137
	v_add_f32_e32 v132, 1.0, v142
	v_add_f32_e32 v133, 1.0, v143
	v_mul_f32_e32 v142, 0xbfb8aa3b, v46
	v_mul_f32_e32 v143, 0xbfb8aa3b, v47
	v_add_f32_e32 v134, 1.0, v134
	v_add_f32_e32 v135, 1.0, v135
	v_add_f32_e32 v136, 1.0, v136
	v_add_f32_e32 v137, 1.0, v137
	v_exp_f32_e32 v142, v142
	v_exp_f32_e32 v143, v143
	v_rcp_f32_e32 v132, v132
	v_rcp_f32_e32 v133, v133
	v_rcp_f32_e32 v134, v134
	v_rcp_f32_e32 v135, v135
	v_rcp_f32_e32 v136, v136
	v_rcp_f32_e32 v137, v137
	v_add_f32_e32 v142, 1.0, v142
	v_add_f32_e32 v143, 1.0, v143
	v_rcp_f32_e32 v142, v142
	v_rcp_f32_e32 v143, v143
	v_cvt_pk_bf16_f32 v132, v132, v133
	v_cvt_pk_bf16_f32 v133, v134, v135
	v_cvt_pk_bf16_f32 v134, v136, v137
	v_mul_f32_e32 v136, 0xbfb8aa3b, v36
	v_mul_f32_e32 v137, 0xbfb8aa3b, v37
	v_exp_f32_e32 v136, v136
	v_exp_f32_e32 v137, v137
	v_cvt_pk_bf16_f32 v135, v142, v143
	global_store_dwordx4 v[138:139], v[132:135], off offset:256
	v_mul_f32_e32 v138, 0xbfb8aa3b, v30
	v_mul_f32_e32 v139, 0xbfb8aa3b, v31
	v_add_f32_e32 v132, 1.0, v136
	v_add_f32_e32 v133, 1.0, v137
	v_mul_f32_e32 v134, 0xbfb8aa3b, v38
	v_mul_f32_e32 v135, 0xbfb8aa3b, v39
	v_mul_f32_e32 v136, 0xbfb8aa3b, v28
	v_mul_f32_e32 v137, 0xbfb8aa3b, v29
	v_exp_f32_e32 v134, v134
	v_exp_f32_e32 v135, v135
	v_exp_f32_e32 v136, v136
	v_exp_f32_e32 v137, v137
	v_add_f32_e32 v134, 1.0, v134
	v_add_f32_e32 v135, 1.0, v135
	v_add_f32_e32 v136, 1.0, v136
	v_add_f32_e32 v137, 1.0, v137
	v_exp_f32_e32 v138, v138
	v_exp_f32_e32 v139, v139
	v_rcp_f32_e32 v132, v132
	v_rcp_f32_e32 v133, v133
	v_rcp_f32_e32 v134, v134
	v_rcp_f32_e32 v135, v135
	v_rcp_f32_e32 v136, v136
	v_rcp_f32_e32 v137, v137
	v_add_f32_e32 v138, 1.0, v138
	v_add_f32_e32 v139, 1.0, v139
	v_rcp_f32_e32 v138, v138
	v_rcp_f32_e32 v139, v139
	v_cvt_pk_bf16_f32 v132, v132, v133
	v_cvt_pk_bf16_f32 v133, v134, v135
	v_cvt_pk_bf16_f32 v134, v136, v137
	v_mul_f32_e32 v136, 0xbfb8aa3b, v20
	v_mul_f32_e32 v137, 0xbfb8aa3b, v21
	v_exp_f32_e32 v136, v136
	v_exp_f32_e32 v137, v137
	v_cvt_pk_bf16_f32 v135, v138, v139
	global_store_dwordx4 v[140:141], v[132:135], off offset:256
	v_mul_f32_e32 v138, 0xbfb8aa3b, v14
	v_mul_f32_e32 v139, 0xbfb8aa3b, v15
	v_add_f32_e32 v132, 1.0, v136
	v_add_f32_e32 v133, 1.0, v137
	v_mul_f32_e32 v134, 0xbfb8aa3b, v22
	v_mul_f32_e32 v135, 0xbfb8aa3b, v23
	v_mul_f32_e32 v136, 0xbfb8aa3b, v12
	v_mul_f32_e32 v137, 0xbfb8aa3b, v13
	v_exp_f32_e32 v134, v134
	v_exp_f32_e32 v135, v135
	v_exp_f32_e32 v136, v136
	v_exp_f32_e32 v137, v137
	v_add_f32_e32 v134, 1.0, v134
	v_add_f32_e32 v135, 1.0, v135
	v_add_f32_e32 v136, 1.0, v136
	v_add_f32_e32 v137, 1.0, v137
	v_exp_f32_e32 v138, v138
	v_exp_f32_e32 v139, v139
	v_rcp_f32_e32 v132, v132
	v_rcp_f32_e32 v133, v133
	v_rcp_f32_e32 v134, v134
	v_rcp_f32_e32 v135, v135
	v_rcp_f32_e32 v136, v136
	v_rcp_f32_e32 v137, v137
	v_add_f32_e32 v138, 1.0, v138
	v_add_f32_e32 v139, 1.0, v139
	v_rcp_f32_e32 v138, v138
	v_rcp_f32_e32 v139, v139
	v_cvt_pk_bf16_f32 v132, v132, v133
	v_cvt_pk_bf16_f32 v133, v134, v135
	v_cvt_pk_bf16_f32 v134, v136, v137
	v_mul_f32_e32 v136, 0xbfb8aa3b, v4
	v_mul_f32_e32 v137, 0xbfb8aa3b, v5
	v_exp_f32_e32 v136, v136
	v_exp_f32_e32 v137, v137
	v_cvt_pk_bf16_f32 v135, v138, v139
	global_store_dwordx4 v[130:131], v[132:135], off offset:256
	v_add_f32_e32 v130, 1.0, v136
	v_add_f32_e32 v131, 1.0, v137
	v_mul_f32_e32 v132, 0xbfb8aa3b, v6
	v_mul_f32_e32 v133, 0xbfb8aa3b, v7
	v_mul_f32_e32 v134, 0xbfb8aa3b, v0
	v_mul_f32_e32 v135, 0xbfb8aa3b, v1
	v_mul_f32_e32 v136, 0xbfb8aa3b, v2
	v_mul_f32_e32 v137, 0xbfb8aa3b, v3
	v_exp_f32_e32 v132, v132
	v_exp_f32_e32 v133, v133
	v_exp_f32_e32 v134, v134
	v_exp_f32_e32 v135, v135
	v_exp_f32_e32 v136, v136
	v_exp_f32_e32 v137, v137
	v_add_f32_e32 v132, 1.0, v132
	v_add_f32_e32 v133, 1.0, v133
	v_add_f32_e32 v134, 1.0, v134
	v_add_f32_e32 v135, 1.0, v135
	v_add_f32_e32 v136, 1.0, v136
	v_add_f32_e32 v137, 1.0, v137
	v_rcp_f32_e32 v130, v130
	v_rcp_f32_e32 v131, v131
	v_rcp_f32_e32 v132, v132
	v_rcp_f32_e32 v133, v133
	v_rcp_f32_e32 v134, v134
	v_rcp_f32_e32 v135, v135
	v_rcp_f32_e32 v136, v136
	v_rcp_f32_e32 v137, v137
	v_cvt_pk_bf16_f32 v130, v130, v131
	v_cvt_pk_bf16_f32 v131, v132, v133
	v_cvt_pk_bf16_f32 v132, v134, v135
	v_cvt_pk_bf16_f32 v133, v136, v137
	global_store_dwordx4 v[192:193], v[164:167], off offset:256
	global_store_dwordx4 v[128:129], v[130:133], off offset:256

.LBB0_402:
	s_andn2_b64 vcc, exec, s[0:1]
	s_cbranch_vccnz .LBB0_404
	v_mul_f32_e32 v128, 0xbfb8aa3b, v125
	v_exp_f32_e32 v128, v128
	v_mul_f32_e32 v129, 0xbfb8aa3b, v126
	v_mul_f32_e32 v130, 0xbfb8aa3b, v127
	v_exp_f32_e32 v129, v129
	v_exp_f32_e32 v130, v130
	v_add_f32_e32 v128, 1.0, v128
	v_rcp_f32_e32 v189, v128
	v_add_f32_e32 v128, 1.0, v129
	v_add_f32_e32 v129, 1.0, v130
	v_mul_f32_e32 v130, 0xbfb8aa3b, v120
	v_mul_f32_e32 v131, 0xbfb8aa3b, v121
	v_exp_f32_e32 v130, v130
	v_exp_f32_e32 v131, v131
	v_mul_f32_e32 v132, 0xbfb8aa3b, v122
	v_mul_f32_e32 v133, 0xbfb8aa3b, v123
	v_exp_f32_e32 v132, v132
	v_exp_f32_e32 v133, v133
	v_add_f32_e32 v130, 1.0, v130
	v_add_f32_e32 v131, 1.0, v131
	v_rcp_f32_e32 v130, v130
	v_rcp_f32_e32 v131, v131
	v_rcp_f32_e32 v128, v128
	v_rcp_f32_e32 v129, v129
	v_add_f32_e32 v132, 1.0, v132
	v_add_f32_e32 v133, 1.0, v133
	v_rcp_f32_e32 v132, v132
	v_rcp_f32_e32 v133, v133
	v_pk_mul_f32 v[136:137], v[124:125], v[188:189]
	v_pk_mul_f32 v[138:139], v[120:121], v[130:131]
	v_cvt_pk_bf16_f32 v130, v136, v137
	v_mul_f32_e32 v136, 0xbfb8aa3b, v112
	v_mul_f32_e32 v137, 0xbfb8aa3b, v113
	v_readlane_b32 s0, v251, 62
	v_exp_f32_e32 v136, v136
	v_exp_f32_e32 v137, v137
	v_lshlrev_b32_e32 v172, 1, v223
	v_readlane_b32 s1, v251, 63
	v_pk_mul_f32 v[128:129], v[126:127], v[128:129]
	v_ashrrev_i32_e32 v187, 31, v186
	v_lshl_add_u64 v[134:135], s[0:1], 0, v[172:173]
	v_pk_mul_f32 v[140:141], v[122:123], v[132:133]
	v_cvt_pk_bf16_f32 v131, v128, v129
	v_lshlrev_b64 v[128:129], 11, v[186:187]
	v_cvt_pk_bf16_f32 v132, v138, v139
	v_cvt_pk_bf16_f32 v133, v140, v141
	v_lshl_add_u64 v[128:129], v[134:135], 0, v[128:129]
	global_store_dwordx4 v[128:129], v[130:133], off
	v_mul_f32_e32 v138, 0xbfb8aa3b, v106
	v_mul_f32_e32 v139, 0xbfb8aa3b, v107
	v_add_f32_e32 v130, 1.0, v136
	v_add_f32_e32 v131, 1.0, v137
	v_mul_f32_e32 v136, 0xbfb8aa3b, v104
	v_mul_f32_e32 v137, 0xbfb8aa3b, v105
	v_exp_f32_e32 v136, v136
	v_exp_f32_e32 v137, v137
	v_mul_f32_e32 v132, 0xbfb8aa3b, v114
	v_mul_f32_e32 v133, 0xbfb8aa3b, v115
	v_exp_f32_e32 v132, v132
	v_exp_f32_e32 v133, v133
	v_exp_f32_e32 v138, v138
	v_exp_f32_e32 v139, v139
	v_rcp_f32_e32 v130, v130
	v_rcp_f32_e32 v131, v131
	v_add_f32_e32 v136, 1.0, v136
	v_add_f32_e32 v137, 1.0, v137
	v_rcp_f32_e32 v136, v136
	v_rcp_f32_e32 v137, v137
	v_add_f32_e32 v132, 1.0, v132
	v_add_f32_e32 v133, 1.0, v133
	v_add_f32_e32 v138, 1.0, v138
	v_add_f32_e32 v139, 1.0, v139
	v_rcp_f32_e32 v132, v132
	v_rcp_f32_e32 v133, v133
	v_rcp_f32_e32 v138, v138
	v_rcp_f32_e32 v139, v139
	v_pk_mul_f32 v[130:131], v[112:113], v[130:131]
	v_pk_mul_f32 v[140:141], v[104:105], v[136:137]
	v_cvt_pk_bf16_f32 v136, v130, v131
	v_or_b32_e32 v130, 16, v186
	v_ashrrev_i32_e32 v131, 31, v130
	v_pk_mul_f32 v[132:133], v[114:115], v[132:133]
	v_pk_mul_f32 v[142:143], v[106:107], v[138:139]
	v_lshlrev_b64 v[130:131], 11, v[130:131]
	v_cvt_pk_bf16_f32 v137, v132, v133
	v_cvt_pk_bf16_f32 v138, v140, v141
	v_cvt_pk_bf16_f32 v139, v142, v143
	v_lshl_add_u64 v[130:131], v[134:135], 0, v[130:131]
	global_store_dwordx4 v[130:131], v[136:139], off
	v_mul_f32_e32 v140, 0xbfb8aa3b, v90
	v_mul_f32_e32 v141, 0xbfb8aa3b, v91
	v_mul_f32_e32 v138, 0xbfb8aa3b, v88
	v_mul_f32_e32 v139, 0xbfb8aa3b, v89
	v_mul_f32_e32 v132, 0xbfb8aa3b, v96
	v_mul_f32_e32 v133, 0xbfb8aa3b, v97
	v_exp_f32_e32 v138, v138
	v_exp_f32_e32 v139, v139
	v_exp_f32_e32 v140, v140
	v_exp_f32_e32 v141, v141
	v_exp_f32_e32 v132, v132
	v_exp_f32_e32 v133, v133
	v_mul_f32_e32 v136, 0xbfb8aa3b, v98
	v_mul_f32_e32 v137, 0xbfb8aa3b, v99
	v_exp_f32_e32 v136, v136
	v_exp_f32_e32 v137, v137
	v_add_f32_e32 v138, 1.0, v138
	v_add_f32_e32 v139, 1.0, v139
	v_add_f32_e32 v140, 1.0, v140
	v_add_f32_e32 v141, 1.0, v141
	v_add_f32_e32 v132, 1.0, v132
	v_add_f32_e32 v133, 1.0, v133
	v_rcp_f32_e32 v138, v138
	v_rcp_f32_e32 v139, v139
	v_rcp_f32_e32 v140, v140
	v_rcp_f32_e32 v141, v141
	v_rcp_f32_e32 v132, v132
	v_rcp_f32_e32 v133, v133
	v_add_f32_e32 v136, 1.0, v136
	v_add_f32_e32 v137, 1.0, v137
	v_rcp_f32_e32 v136, v136
	v_rcp_f32_e32 v137, v137
	v_pk_mul_f32 v[138:139], v[88:89], v[138:139]
	v_pk_mul_f32 v[140:141], v[90:91], v[140:141]
	v_pk_mul_f32 v[132:133], v[96:97], v[132:133]
	v_cvt_pk_bf16_f32 v138, v138, v139
	v_cvt_pk_bf16_f32 v139, v140, v141
	v_mul_f32_e32 v140, 0xbfb8aa3b, v80
	v_mul_f32_e32 v141, 0xbfb8aa3b, v81
	v_pk_mul_f32 v[142:143], v[98:99], v[136:137]
	v_cvt_pk_bf16_f32 v136, v132, v133
	v_or_b32_e32 v132, 32, v186
	v_exp_f32_e32 v140, v140
	v_exp_f32_e32 v141, v141
	v_ashrrev_i32_e32 v133, 31, v132
	v_lshlrev_b64 v[132:133], 11, v[132:133]
	v_cvt_pk_bf16_f32 v137, v142, v143
	v_lshl_add_u64 v[132:133], v[134:135], 0, v[132:133]
	global_store_dwordx4 v[132:133], v[136:139], off
	v_mul_f32_e32 v142, 0xbfb8aa3b, v74
	v_mul_f32_e32 v143, 0xbfb8aa3b, v75
	v_add_f32_e32 v136, 1.0, v140
	v_add_f32_e32 v137, 1.0, v141
	v_mul_f32_e32 v138, 0xbfb8aa3b, v82
	v_mul_f32_e32 v139, 0xbfb8aa3b, v83
	v_mul_f32_e32 v140, 0xbfb8aa3b, v72
	v_mul_f32_e32 v141, 0xbfb8aa3b, v73
	v_exp_f32_e32 v138, v138
	v_exp_f32_e32 v139, v139
	v_exp_f32_e32 v140, v140
	v_exp_f32_e32 v141, v141
	v_add_f32_e32 v138, 1.0, v138
	v_add_f32_e32 v139, 1.0, v139
	v_add_f32_e32 v140, 1.0, v140
	v_add_f32_e32 v141, 1.0, v141
	v_exp_f32_e32 v142, v142
	v_exp_f32_e32 v143, v143
	v_rcp_f32_e32 v136, v136
	v_rcp_f32_e32 v137, v137
	v_rcp_f32_e32 v138, v138
	v_rcp_f32_e32 v139, v139
	v_rcp_f32_e32 v140, v140
	v_rcp_f32_e32 v141, v141
	v_add_f32_e32 v142, 1.0, v142
	v_add_f32_e32 v143, 1.0, v143
	v_rcp_f32_e32 v142, v142
	v_rcp_f32_e32 v143, v143
	v_pk_mul_f32 v[136:137], v[80:81], v[136:137]
	v_pk_mul_f32 v[138:139], v[82:83], v[138:139]
	v_pk_mul_f32 v[140:141], v[72:73], v[140:141]
	v_cvt_pk_bf16_f32 v136, v136, v137
	v_cvt_pk_bf16_f32 v137, v138, v139
	v_cvt_pk_bf16_f32 v138, v140, v141
	v_or_b32_e32 v140, 48, v186
	v_ashrrev_i32_e32 v141, 31, v140
	v_lshlrev_b64 v[140:141], 11, v[140:141]
	v_pk_mul_f32 v[142:143], v[74:75], v[142:143]
	v_lshl_add_u64 v[134:135], v[134:135], 0, v[140:141]
	v_mul_f32_e32 v140, 0xbfb8aa3b, v60
	v_mul_f32_e32 v141, 0xbfb8aa3b, v61
	v_cvt_pk_bf16_f32 v139, v142, v143
	v_exp_f32_e32 v140, v140
	v_exp_f32_e32 v141, v141
	global_store_dwordx4 v[134:135], v[136:139], off
	v_mul_f32_e32 v142, 0xbfb8aa3b, v58
	v_mul_f32_e32 v143, 0xbfb8aa3b, v59
	v_mul_f32_e32 v138, 0xbfb8aa3b, v62
	v_mul_f32_e32 v139, 0xbfb8aa3b, v63
	v_exp_f32_e32 v138, v138
	v_exp_f32_e32 v139, v139
	v_add_f32_e32 v136, 1.0, v140
	v_add_f32_e32 v137, 1.0, v141
	v_mul_f32_e32 v140, 0xbfb8aa3b, v56
	v_mul_f32_e32 v141, 0xbfb8aa3b, v57
	v_exp_f32_e32 v140, v140
	v_exp_f32_e32 v141, v141
	v_exp_f32_e32 v142, v142
	v_exp_f32_e32 v143, v143
	v_add_f32_e32 v138, 1.0, v138
	v_add_f32_e32 v139, 1.0, v139
	v_rcp_f32_e32 v138, v138
	v_rcp_f32_e32 v139, v139
	v_add_f32_e32 v140, 1.0, v140
	v_add_f32_e32 v141, 1.0, v141
	v_add_f32_e32 v142, 1.0, v142
	v_add_f32_e32 v143, 1.0, v143
	v_rcp_f32_e32 v140, v140
	v_rcp_f32_e32 v141, v141
	v_rcp_f32_e32 v142, v142
	v_rcp_f32_e32 v143, v143
	v_rcp_f32_e32 v136, v136
	v_rcp_f32_e32 v137, v137
	v_pk_mul_f32 v[144:145], v[62:63], v[138:139]
	v_pk_mul_f32 v[140:141], v[56:57], v[140:141]
	v_cvt_pk_bf16_f32 v139, v144, v145
	v_mul_f32_e32 v144, 0xbfb8aa3b, v48
	v_mul_f32_e32 v145, 0xbfb8aa3b, v49
	v_exp_f32_e32 v144, v144
	v_exp_f32_e32 v145, v145
	v_pk_mul_f32 v[142:143], v[58:59], v[142:143]
	v_pk_mul_f32 v[136:137], v[60:61], v[136:137]
	v_cvt_pk_bf16_f32 v140, v140, v141
	v_cvt_pk_bf16_f32 v141, v142, v143
	v_add_co_u32_e32 v142, vcc, s93, v128
	v_cvt_pk_bf16_f32 v138, v136, v137
	s_nop 0
	v_addc_co_u32_e32 v143, vcc, 0, v129, vcc
	global_store_dwordx4 v[142:143], v[138:141], off
	v_mul_f32_e32 v142, 0xbfb8aa3b, v40
	v_mul_f32_e32 v143, 0xbfb8aa3b, v41
	v_add_f32_e32 v138, 1.0, v144
	v_add_f32_e32 v139, 1.0, v145
	v_mul_f32_e32 v140, 0xbfb8aa3b, v50
	v_mul_f32_e32 v141, 0xbfb8aa3b, v51
	v_mul_f32_e32 v144, 0xbfb8aa3b, v42
	v_mul_f32_e32 v145, 0xbfb8aa3b, v43
	v_exp_f32_e32 v140, v140
	v_exp_f32_e32 v141, v141
	v_exp_f32_e32 v142, v142
	v_exp_f32_e32 v143, v143
	v_exp_f32_e32 v144, v144
	v_exp_f32_e32 v145, v145
	v_add_f32_e32 v140, 1.0, v140
	v_add_f32_e32 v141, 1.0, v141
	v_add_f32_e32 v142, 1.0, v142
	v_add_f32_e32 v143, 1.0, v143
	v_add_f32_e32 v144, 1.0, v144
	v_add_f32_e32 v145, 1.0, v145
	v_rcp_f32_e32 v140, v140
	v_rcp_f32_e32 v141, v141
	v_rcp_f32_e32 v142, v142
	v_rcp_f32_e32 v143, v143
	v_rcp_f32_e32 v144, v144
	v_rcp_f32_e32 v145, v145
	v_rcp_f32_e32 v138, v138
	v_rcp_f32_e32 v139, v139
	v_pk_mul_f32 v[146:147], v[50:51], v[140:141]
	v_pk_mul_f32 v[142:143], v[40:41], v[142:143]
	v_pk_mul_f32 v[144:145], v[42:43], v[144:145]
	v_pk_mul_f32 v[138:139], v[48:49], v[138:139]
	v_cvt_pk_bf16_f32 v141, v146, v147
	v_cvt_pk_bf16_f32 v142, v142, v143
	v_cvt_pk_bf16_f32 v143, v144, v145
	v_add_co_u32_e32 v144, vcc, s96, v128
	v_mul_f32_e32 v146, 0xbfb8aa3b, v32
	v_mul_f32_e32 v147, 0xbfb8aa3b, v33
	v_cvt_pk_bf16_f32 v140, v138, v139
	v_addc_co_u32_e32 v145, vcc, 0, v129, vcc
	v_exp_f32_e32 v146, v146
	v_exp_f32_e32 v147, v147
	global_store_dwordx4 v[144:145], v[140:143], off
	v_mul_f32_e32 v144, 0xbfb8aa3b, v24
	v_mul_f32_e32 v145, 0xbfb8aa3b, v25
	v_mul_f32_e32 v142, 0xbfb8aa3b, v34
	v_mul_f32_e32 v143, 0xbfb8aa3b, v35
	v_exp_f32_e32 v142, v142
	v_exp_f32_e32 v143, v143
	v_add_f32_e32 v140, 1.0, v146
	v_add_f32_e32 v141, 1.0, v147
	v_mul_f32_e32 v146, 0xbfb8aa3b, v26
	v_mul_f32_e32 v147, 0xbfb8aa3b, v27
	v_exp_f32_e32 v144, v144
	v_exp_f32_e32 v145, v145
	v_exp_f32_e32 v146, v146
	v_exp_f32_e32 v147, v147
	v_add_f32_e32 v142, 1.0, v142
	v_add_f32_e32 v143, 1.0, v143
	v_rcp_f32_e32 v142, v142
	v_rcp_f32_e32 v143, v143
	v_rcp_f32_e32 v140, v140
	v_rcp_f32_e32 v141, v141
	v_add_f32_e32 v144, 1.0, v144
	v_add_f32_e32 v145, 1.0, v145
	v_add_f32_e32 v146, 1.0, v146
	v_add_f32_e32 v147, 1.0, v147
	v_rcp_f32_e32 v144, v144
	v_rcp_f32_e32 v145, v145
	v_rcp_f32_e32 v146, v146
	v_rcp_f32_e32 v147, v147
	v_pk_mul_f32 v[148:149], v[34:35], v[142:143]
	s_mov_b64 s[0:1], 0x48000
	v_cvt_pk_bf16_f32 v143, v148, v149
	v_mul_f32_e32 v148, 0xbfb8aa3b, v16
	v_mul_f32_e32 v149, 0xbfb8aa3b, v17
	v_lshl_add_u64 v[138:139], v[128:129], 0, s[0:1]
	v_pk_mul_f32 v[140:141], v[32:33], v[140:141]
	s_mov_b64 s[0:1], 0x50000
	v_exp_f32_e32 v148, v148
	v_exp_f32_e32 v149, v149
	v_pk_mul_f32 v[144:145], v[24:25], v[144:145]
	v_pk_mul_f32 v[146:147], v[26:27], v[146:147]
	v_cvt_pk_bf16_f32 v142, v140, v141
	v_lshl_add_u64 v[140:141], v[128:129], 0, s[0:1]
	s_mov_b32 s0, 0x50000
	v_cvt_pk_bf16_f32 v144, v144, v145
	v_cvt_pk_bf16_f32 v145, v146, v147
	v_add_co_u32_e32 v146, vcc, s0, v128
	s_mov_b64 s[0:1], 0x58000
	s_nop 0
	v_addc_co_u32_e32 v147, vcc, 0, v129, vcc
	global_store_dwordx4 v[146:147], v[142:145], off
	v_mul_f32_e32 v146, 0xbfb8aa3b, v8
	v_mul_f32_e32 v147, 0xbfb8aa3b, v9
	v_add_f32_e32 v142, 1.0, v148
	v_add_f32_e32 v143, 1.0, v149
	v_mul_f32_e32 v144, 0xbfb8aa3b, v18
	v_mul_f32_e32 v145, 0xbfb8aa3b, v19
	v_mul_f32_e32 v148, 0xbfb8aa3b, v10
	v_mul_f32_e32 v149, 0xbfb8aa3b, v11
	v_exp_f32_e32 v144, v144
	v_exp_f32_e32 v145, v145
	v_exp_f32_e32 v146, v146
	v_exp_f32_e32 v147, v147
	v_exp_f32_e32 v148, v148
	v_exp_f32_e32 v149, v149
	v_rcp_f32_e32 v142, v142
	v_rcp_f32_e32 v143, v143
	v_add_f32_e32 v144, 1.0, v144
	v_add_f32_e32 v145, 1.0, v145
	v_add_f32_e32 v146, 1.0, v146
	v_add_f32_e32 v147, 1.0, v147
	v_add_f32_e32 v148, 1.0, v148
	v_add_f32_e32 v149, 1.0, v149
	v_rcp_f32_e32 v144, v144
	v_rcp_f32_e32 v145, v145
	v_rcp_f32_e32 v146, v146
	v_rcp_f32_e32 v147, v147
	v_rcp_f32_e32 v148, v148
	v_rcp_f32_e32 v149, v149
	v_pk_mul_f32 v[142:143], v[16:17], v[142:143]
	v_pk_mul_f32 v[150:151], v[18:19], v[144:145]
	v_pk_mul_f32 v[146:147], v[8:9], v[146:147]
	v_pk_mul_f32 v[148:149], v[10:11], v[148:149]
	v_cvt_pk_bf16_f32 v144, v142, v143
	v_lshl_add_u64 v[142:143], v[128:129], 0, s[0:1]
	s_mov_b32 s0, 0x58000
	v_cvt_pk_bf16_f32 v146, v146, v147
	v_cvt_pk_bf16_f32 v147, v148, v149
	v_add_co_u32_e32 v148, vcc, s0, v128
	v_cvt_pk_bf16_f32 v145, v150, v151
	s_nop 0
	v_addc_co_u32_e32 v149, vcc, 0, v129, vcc
	v_mul_f32_e32 v150, 0xbfb8aa3b, v116
	v_mul_f32_e32 v151, 0xbfb8aa3b, v117
	v_exp_f32_e32 v150, v150
	v_exp_f32_e32 v151, v151
	global_store_dwordx4 v[148:149], v[144:147], off
	v_mul_f32_e32 v148, 0xbfb8aa3b, v108
	v_mul_f32_e32 v149, 0xbfb8aa3b, v109
	v_mul_f32_e32 v146, 0xbfb8aa3b, v118
	v_mul_f32_e32 v147, 0xbfb8aa3b, v119
	v_exp_f32_e32 v146, v146
	v_exp_f32_e32 v147, v147
	v_exp_f32_e32 v148, v148
	v_exp_f32_e32 v149, v149
	v_add_f32_e32 v144, 1.0, v150
	v_add_f32_e32 v145, 1.0, v151
	v_mul_f32_e32 v150, 0xbfb8aa3b, v110
	v_mul_f32_e32 v151, 0xbfb8aa3b, v111
	v_add_f32_e32 v146, 1.0, v146
	v_add_f32_e32 v147, 1.0, v147
	v_add_f32_e32 v148, 1.0, v148
	v_add_f32_e32 v149, 1.0, v149
	v_exp_f32_e32 v150, v150
	v_exp_f32_e32 v151, v151
	v_rcp_f32_e32 v144, v144
	v_rcp_f32_e32 v145, v145
	v_rcp_f32_e32 v146, v146
	v_rcp_f32_e32 v147, v147
	v_rcp_f32_e32 v148, v148
	v_rcp_f32_e32 v149, v149
	v_add_f32_e32 v150, 1.0, v150
	v_add_f32_e32 v151, 1.0, v151
	v_rcp_f32_e32 v150, v150
	v_rcp_f32_e32 v151, v151
	v_pk_mul_f32 v[144:145], v[116:117], v[144:145]
	v_pk_mul_f32 v[146:147], v[118:119], v[146:147]
	v_pk_mul_f32 v[148:149], v[108:109], v[148:149]
	v_cvt_pk_bf16_f32 v144, v144, v145
	v_cvt_pk_bf16_f32 v145, v146, v147
	v_cvt_pk_bf16_f32 v146, v148, v149
	v_mul_f32_e32 v148, 0xbfb8aa3b, v100
	v_mul_f32_e32 v149, 0xbfb8aa3b, v101
	v_exp_f32_e32 v148, v148
	v_exp_f32_e32 v149, v149
	v_pk_mul_f32 v[150:151], v[110:111], v[150:151]
	v_lshl_add_u64 v[136:137], v[128:129], 0, s[4:5]
	v_cvt_pk_bf16_f32 v147, v150, v151
	global_store_dwordx4 v[128:129], v[144:147], off offset:256
	v_add_f32_e32 v128, 1.0, v148
	v_add_f32_e32 v129, 1.0, v149
	v_mul_f32_e32 v144, 0xbfb8aa3b, v102
	v_mul_f32_e32 v145, 0xbfb8aa3b, v103
	v_mul_f32_e32 v146, 0xbfb8aa3b, v92
	v_mul_f32_e32 v147, 0xbfb8aa3b, v93
	v_mul_f32_e32 v148, 0xbfb8aa3b, v94
	v_mul_f32_e32 v149, 0xbfb8aa3b, v95
	v_exp_f32_e32 v144, v144
	v_exp_f32_e32 v145, v145
	v_exp_f32_e32 v146, v146
	v_exp_f32_e32 v147, v147
	v_exp_f32_e32 v148, v148
	v_exp_f32_e32 v149, v149
	v_add_f32_e32 v144, 1.0, v144
	v_add_f32_e32 v145, 1.0, v145
	v_add_f32_e32 v146, 1.0, v146
	v_add_f32_e32 v147, 1.0, v147
	v_add_f32_e32 v148, 1.0, v148
	v_add_f32_e32 v149, 1.0, v149
	v_rcp_f32_e32 v128, v128
	v_rcp_f32_e32 v129, v129
	v_rcp_f32_e32 v144, v144
	v_rcp_f32_e32 v145, v145
	v_rcp_f32_e32 v146, v146
	v_rcp_f32_e32 v147, v147
	v_rcp_f32_e32 v148, v148
	v_rcp_f32_e32 v149, v149
	v_pk_mul_f32 v[128:129], v[100:101], v[128:129]
	v_pk_mul_f32 v[150:151], v[102:103], v[144:145]
	v_pk_mul_f32 v[146:147], v[92:93], v[146:147]
	v_pk_mul_f32 v[148:149], v[94:95], v[148:149]
	v_cvt_pk_bf16_f32 v144, v128, v129
	v_cvt_pk_bf16_f32 v145, v150, v151
	v_cvt_pk_bf16_f32 v146, v146, v147
	v_cvt_pk_bf16_f32 v147, v148, v149
	v_mul_f32_e32 v128, 0xbfb8aa3b, v84
	v_mul_f32_e32 v129, 0xbfb8aa3b, v85
	global_store_dwordx4 v[130:131], v[144:147], off offset:256
	v_mul_f32_e32 v130, 0xbfb8aa3b, v86
	v_mul_f32_e32 v131, 0xbfb8aa3b, v87
	v_mul_f32_e32 v144, 0xbfb8aa3b, v76
	v_mul_f32_e32 v145, 0xbfb8aa3b, v77
	v_mul_f32_e32 v146, 0xbfb8aa3b, v78
	v_mul_f32_e32 v147, 0xbfb8aa3b, v79
	v_exp_f32_e32 v128, v128
	v_exp_f32_e32 v129, v129
	v_exp_f32_e32 v130, v130
	v_exp_f32_e32 v131, v131
	v_exp_f32_e32 v144, v144
	v_exp_f32_e32 v145, v145
	v_exp_f32_e32 v146, v146
	v_exp_f32_e32 v147, v147
	v_add_f32_e32 v128, 1.0, v128
	v_add_f32_e32 v129, 1.0, v129
	v_add_f32_e32 v130, 1.0, v130
	v_add_f32_e32 v131, 1.0, v131
	v_add_f32_e32 v144, 1.0, v144
	v_add_f32_e32 v145, 1.0, v145
	v_add_f32_e32 v146, 1.0, v146
	v_add_f32_e32 v147, 1.0, v147
	v_rcp_f32_e32 v128, v128
	v_rcp_f32_e32 v129, v129
	v_rcp_f32_e32 v130, v130
	v_rcp_f32_e32 v131, v131
	v_rcp_f32_e32 v144, v144
	v_rcp_f32_e32 v145, v145
	v_rcp_f32_e32 v146, v146
	v_rcp_f32_e32 v147, v147
	v_pk_mul_f32 v[128:129], v[84:85], v[128:129]
	v_pk_mul_f32 v[130:131], v[86:87], v[130:131]
	v_pk_mul_f32 v[144:145], v[76:77], v[144:145]
	v_pk_mul_f32 v[146:147], v[78:79], v[146:147]
	v_cvt_pk_bf16_f32 v128, v128, v129
	v_cvt_pk_bf16_f32 v129, v130, v131
	v_cvt_pk_bf16_f32 v130, v144, v145
	v_cvt_pk_bf16_f32 v131, v146, v147
	v_mul_f32_e32 v144, 0xbfb8aa3b, v68
	v_mul_f32_e32 v145, 0xbfb8aa3b, v69
	v_exp_f32_e32 v144, v144
	v_exp_f32_e32 v145, v145
	global_store_dwordx4 v[132:133], v[128:131], off offset:256
	v_mul_f32_e32 v132, 0xbfb8aa3b, v64
	v_mul_f32_e32 v133, 0xbfb8aa3b, v65
	v_mul_f32_e32 v130, 0xbfb8aa3b, v70
	v_mul_f32_e32 v131, 0xbfb8aa3b, v71
	v_exp_f32_e32 v130, v130
	v_exp_f32_e32 v131, v131
	v_exp_f32_e32 v132, v132
	v_exp_f32_e32 v133, v133
	v_add_f32_e32 v128, 1.0, v144
	v_add_f32_e32 v129, 1.0, v145
	v_mul_f32_e32 v144, 0xbfb8aa3b, v66
	v_mul_f32_e32 v145, 0xbfb8aa3b, v67
	v_add_f32_e32 v130, 1.0, v130
	v_add_f32_e32 v131, 1.0, v131
	v_add_f32_e32 v132, 1.0, v132
	v_add_f32_e32 v133, 1.0, v133
	v_exp_f32_e32 v144, v144
	v_exp_f32_e32 v145, v145
	v_rcp_f32_e32 v128, v128
	v_rcp_f32_e32 v129, v129
	v_rcp_f32_e32 v130, v130
	v_rcp_f32_e32 v131, v131
	v_rcp_f32_e32 v132, v132
	v_rcp_f32_e32 v133, v133
	v_add_f32_e32 v144, 1.0, v144
	v_add_f32_e32 v145, 1.0, v145
	v_rcp_f32_e32 v144, v144
	v_rcp_f32_e32 v145, v145
	v_pk_mul_f32 v[128:129], v[68:69], v[128:129]
	v_pk_mul_f32 v[130:131], v[70:71], v[130:131]
	v_pk_mul_f32 v[132:133], v[64:65], v[132:133]
	v_cvt_pk_bf16_f32 v128, v128, v129
	v_cvt_pk_bf16_f32 v129, v130, v131
	v_cvt_pk_bf16_f32 v130, v132, v133
	v_mul_f32_e32 v132, 0xbfb8aa3b, v52
	v_mul_f32_e32 v133, 0xbfb8aa3b, v53
	v_exp_f32_e32 v132, v132
	v_exp_f32_e32 v133, v133
	v_pk_mul_f32 v[144:145], v[66:67], v[144:145]
	s_nop 0
	v_cvt_pk_bf16_f32 v131, v144, v145
	global_store_dwordx4 v[134:135], v[128:131], off offset:256
	v_mul_f32_e32 v134, 0xbfb8aa3b, v46
	v_mul_f32_e32 v135, 0xbfb8aa3b, v47
	v_add_f32_e32 v128, 1.0, v132
	v_add_f32_e32 v129, 1.0, v133
	v_mul_f32_e32 v130, 0xbfb8aa3b, v54
	v_mul_f32_e32 v131, 0xbfb8aa3b, v55
	v_mul_f32_e32 v132, 0xbfb8aa3b, v44
	v_mul_f32_e32 v133, 0xbfb8aa3b, v45
	v_exp_f32_e32 v130, v130
	v_exp_f32_e32 v131, v131
	v_exp_f32_e32 v132, v132
	v_exp_f32_e32 v133, v133
	v_add_f32_e32 v130, 1.0, v130
	v_add_f32_e32 v131, 1.0, v131
	v_add_f32_e32 v132, 1.0, v132
	v_add_f32_e32 v133, 1.0, v133
	v_exp_f32_e32 v134, v134
	v_exp_f32_e32 v135, v135
	v_rcp_f32_e32 v128, v128
	v_rcp_f32_e32 v129, v129
	v_rcp_f32_e32 v130, v130
	v_rcp_f32_e32 v131, v131
	v_rcp_f32_e32 v132, v132
	v_rcp_f32_e32 v133, v133
	v_add_f32_e32 v134, 1.0, v134
	v_add_f32_e32 v135, 1.0, v135
	v_rcp_f32_e32 v134, v134
	v_rcp_f32_e32 v135, v135
	v_pk_mul_f32 v[128:129], v[52:53], v[128:129]
	v_pk_mul_f32 v[130:131], v[54:55], v[130:131]
	v_pk_mul_f32 v[132:133], v[44:45], v[132:133]
	v_cvt_pk_bf16_f32 v128, v128, v129
	v_cvt_pk_bf16_f32 v129, v130, v131
	v_cvt_pk_bf16_f32 v130, v132, v133
	v_mul_f32_e32 v132, 0xbfb8aa3b, v36
	v_mul_f32_e32 v133, 0xbfb8aa3b, v37
	v_exp_f32_e32 v132, v132
	v_exp_f32_e32 v133, v133
	v_pk_mul_f32 v[134:135], v[46:47], v[134:135]
	s_nop 0
	v_cvt_pk_bf16_f32 v131, v134, v135
	global_store_dwordx4 v[136:137], v[128:131], off offset:256
	v_mul_f32_e32 v134, 0xbfb8aa3b, v30
	v_mul_f32_e32 v135, 0xbfb8aa3b, v31
	v_add_f32_e32 v128, 1.0, v132
	v_add_f32_e32 v129, 1.0, v133
	v_mul_f32_e32 v130, 0xbfb8aa3b, v38
	v_mul_f32_e32 v131, 0xbfb8aa3b, v39
	v_mul_f32_e32 v132, 0xbfb8aa3b, v28
	v_mul_f32_e32 v133, 0xbfb8aa3b, v29
	v_exp_f32_e32 v130, v130
	v_exp_f32_e32 v131, v131
	v_exp_f32_e32 v132, v132
	v_exp_f32_e32 v133, v133
	v_add_f32_e32 v130, 1.0, v130
	v_add_f32_e32 v131, 1.0, v131
	v_add_f32_e32 v132, 1.0, v132
	v_add_f32_e32 v133, 1.0, v133
	v_exp_f32_e32 v134, v134
	v_exp_f32_e32 v135, v135
	v_rcp_f32_e32 v128, v128
	v_rcp_f32_e32 v129, v129
	v_rcp_f32_e32 v130, v130
	v_rcp_f32_e32 v131, v131
	v_rcp_f32_e32 v132, v132
	v_rcp_f32_e32 v133, v133
	v_add_f32_e32 v134, 1.0, v134
	v_add_f32_e32 v135, 1.0, v135
	v_rcp_f32_e32 v134, v134
	v_rcp_f32_e32 v135, v135
	v_pk_mul_f32 v[128:129], v[36:37], v[128:129]
	v_pk_mul_f32 v[130:131], v[38:39], v[130:131]
	v_pk_mul_f32 v[132:133], v[28:29], v[132:133]
	v_cvt_pk_bf16_f32 v128, v128, v129
	v_cvt_pk_bf16_f32 v129, v130, v131
	v_cvt_pk_bf16_f32 v130, v132, v133
	v_mul_f32_e32 v132, 0xbfb8aa3b, v20
	v_mul_f32_e32 v133, 0xbfb8aa3b, v21
	v_exp_f32_e32 v132, v132
	v_exp_f32_e32 v133, v133
	v_pk_mul_f32 v[134:135], v[30:31], v[134:135]
	s_nop 0
	v_cvt_pk_bf16_f32 v131, v134, v135
	global_store_dwordx4 v[138:139], v[128:131], off offset:256
	v_mul_f32_e32 v134, 0xbfb8aa3b, v14
	v_mul_f32_e32 v135, 0xbfb8aa3b, v15
	v_add_f32_e32 v128, 1.0, v132
	v_add_f32_e32 v129, 1.0, v133
	v_mul_f32_e32 v130, 0xbfb8aa3b, v22
	v_mul_f32_e32 v131, 0xbfb8aa3b, v23
	v_mul_f32_e32 v132, 0xbfb8aa3b, v12
	v_mul_f32_e32 v133, 0xbfb8aa3b, v13
	v_exp_f32_e32 v130, v130
	v_exp_f32_e32 v131, v131
	v_exp_f32_e32 v132, v132
	v_exp_f32_e32 v133, v133
	v_add_f32_e32 v130, 1.0, v130
	v_add_f32_e32 v131, 1.0, v131
	v_add_f32_e32 v132, 1.0, v132
	v_add_f32_e32 v133, 1.0, v133
	v_exp_f32_e32 v134, v134
	v_exp_f32_e32 v135, v135
	v_rcp_f32_e32 v128, v128
	v_rcp_f32_e32 v129, v129
	v_rcp_f32_e32 v130, v130
	v_rcp_f32_e32 v131, v131
	v_rcp_f32_e32 v132, v132
	v_rcp_f32_e32 v133, v133
	v_add_f32_e32 v134, 1.0, v134
	v_add_f32_e32 v135, 1.0, v135
	v_rcp_f32_e32 v134, v134
	v_rcp_f32_e32 v135, v135
	v_pk_mul_f32 v[128:129], v[20:21], v[128:129]
	v_pk_mul_f32 v[130:131], v[22:23], v[130:131]
	v_pk_mul_f32 v[132:133], v[12:13], v[132:133]
	v_cvt_pk_bf16_f32 v128, v128, v129
	v_cvt_pk_bf16_f32 v129, v130, v131
	v_cvt_pk_bf16_f32 v130, v132, v133
	v_mul_f32_e32 v132, 0xbfb8aa3b, v4
	v_mul_f32_e32 v133, 0xbfb8aa3b, v5
	v_exp_f32_e32 v132, v132
	v_exp_f32_e32 v133, v133
	v_pk_mul_f32 v[134:135], v[14:15], v[134:135]
	s_nop 0
	v_cvt_pk_bf16_f32 v131, v134, v135
	global_store_dwordx4 v[140:141], v[128:131], off offset:256
	v_mul_f32_e32 v134, 0xbfb8aa3b, v2
	v_mul_f32_e32 v135, 0xbfb8aa3b, v3
	v_add_f32_e32 v128, 1.0, v132
	v_add_f32_e32 v129, 1.0, v133
	v_mul_f32_e32 v130, 0xbfb8aa3b, v6
	v_mul_f32_e32 v131, 0xbfb8aa3b, v7
	v_mul_f32_e32 v132, 0xbfb8aa3b, v0
	v_mul_f32_e32 v133, 0xbfb8aa3b, v1
	v_exp_f32_e32 v130, v130
	v_exp_f32_e32 v131, v131
	v_exp_f32_e32 v132, v132
	v_exp_f32_e32 v133, v133
	v_exp_f32_e32 v134, v134
	v_exp_f32_e32 v135, v135
	v_add_f32_e32 v130, 1.0, v130
	v_add_f32_e32 v131, 1.0, v131
	v_add_f32_e32 v132, 1.0, v132
	v_add_f32_e32 v133, 1.0, v133
	v_add_f32_e32 v134, 1.0, v134
	v_add_f32_e32 v135, 1.0, v135
	v_rcp_f32_e32 v128, v128
	v_rcp_f32_e32 v129, v129
	v_rcp_f32_e32 v130, v130
	v_rcp_f32_e32 v131, v131
	v_rcp_f32_e32 v132, v132
	v_rcp_f32_e32 v133, v133
	v_rcp_f32_e32 v134, v134
	v_rcp_f32_e32 v135, v135
	v_pk_mul_f32 v[128:129], v[4:5], v[128:129]
	v_pk_mul_f32 v[130:131], v[6:7], v[130:131]
	v_pk_mul_f32 v[132:133], v[0:1], v[132:133]
	v_pk_mul_f32 v[134:135], v[2:3], v[134:135]
	v_cvt_pk_bf16_f32 v128, v128, v129
	v_cvt_pk_bf16_f32 v129, v130, v131
	v_cvt_pk_bf16_f32 v130, v132, v133
	v_cvt_pk_bf16_f32 v131, v134, v135
	global_store_dwordx4 v[142:143], v[128:131], off offset:256

.LBB0_405:
	s_andn2_b64 vcc, exec, s[0:1]
	s_cbranch_vccnz .LBB0_407
	v_readlane_b32 s0, v251, 60
	v_lshlrev_b32_e32 v172, 1, v223
	v_readlane_b32 s1, v251, 61
	v_ashrrev_i32_e32 v187, 31, v186
	v_or_b32_e32 v136, 16, v186
	v_lshl_add_u64 v[132:133], s[0:1], 0, v[172:173]
	v_lshlrev_b64 v[134:135], 11, v[186:187]
	v_ashrrev_i32_e32 v137, 31, v136
	v_or_b32_e32 v138, 32, v186
	v_cvt_pk_bf16_f32 v128, v124, v125
	v_cvt_pk_bf16_f32 v129, v126, v127
	v_cvt_pk_bf16_f32 v130, v120, v121
	v_cvt_pk_bf16_f32 v131, v122, v123
	v_lshl_add_u64 v[134:135], v[132:133], 0, v[134:135]
	v_lshlrev_b64 v[136:137], 11, v[136:137]
	v_ashrrev_i32_e32 v139, 31, v138
	v_or_b32_e32 v140, 48, v186
	global_store_dwordx4 v[134:135], v[128:131], off
	v_lshl_add_u64 v[136:137], v[132:133], 0, v[136:137]
	v_lshlrev_b64 v[138:139], 11, v[138:139]
	v_cvt_pk_bf16_f32 v128, v112, v113
	v_cvt_pk_bf16_f32 v129, v114, v115
	v_cvt_pk_bf16_f32 v130, v104, v105
	v_cvt_pk_bf16_f32 v131, v106, v107
	v_ashrrev_i32_e32 v141, 31, v140
	global_store_dwordx4 v[136:137], v[128:131], off
	v_lshl_add_u64 v[138:139], v[132:133], 0, v[138:139]
	v_lshlrev_b64 v[140:141], 11, v[140:141]
	v_cvt_pk_bf16_f32 v128, v96, v97
	v_cvt_pk_bf16_f32 v129, v98, v99
	v_cvt_pk_bf16_f32 v130, v88, v89
	v_cvt_pk_bf16_f32 v131, v90, v91
	v_add_co_u32_e32 v142, vcc, s93, v134
	global_store_dwordx4 v[138:139], v[128:131], off
	v_lshl_add_u64 v[132:133], v[132:133], 0, v[140:141]
	v_addc_co_u32_e32 v143, vcc, 0, v135, vcc
	v_cvt_pk_bf16_f32 v128, v80, v81
	v_cvt_pk_bf16_f32 v129, v82, v83
	v_cvt_pk_bf16_f32 v130, v72, v73
	v_cvt_pk_bf16_f32 v131, v74, v75
	global_store_dwordx4 v[132:133], v[128:131], off
	s_mov_b64 s[0:1], 0x48000
	v_add_co_u32_e32 v144, vcc, s96, v134
	v_cvt_pk_bf16_f32 v128, v60, v61
	v_cvt_pk_bf16_f32 v129, v62, v63
	v_cvt_pk_bf16_f32 v130, v56, v57
	v_cvt_pk_bf16_f32 v131, v58, v59
	global_store_dwordx4 v[142:143], v[128:131], off
	v_lshl_add_u64 v[142:143], v[134:135], 0, s[0:1]
	v_addc_co_u32_e32 v145, vcc, 0, v135, vcc
	v_cvt_pk_bf16_f32 v128, v48, v49
	v_cvt_pk_bf16_f32 v129, v50, v51
	v_cvt_pk_bf16_f32 v130, v40, v41
	v_cvt_pk_bf16_f32 v131, v42, v43
	s_mov_b64 s[0:1], 0x50000
	global_store_dwordx4 v[144:145], v[128:131], off
	v_lshl_add_u64 v[144:145], v[134:135], 0, s[0:1]
	s_mov_b32 s0, 0x50000
	v_add_co_u32_e32 v146, vcc, s0, v134
	v_cvt_pk_bf16_f32 v128, v32, v33
	v_cvt_pk_bf16_f32 v129, v34, v35
	v_cvt_pk_bf16_f32 v130, v24, v25
	v_cvt_pk_bf16_f32 v131, v26, v27
	v_addc_co_u32_e32 v147, vcc, 0, v135, vcc
	s_mov_b64 s[0:1], 0x58000
	global_store_dwordx4 v[146:147], v[128:131], off
	v_lshl_add_u64 v[146:147], v[134:135], 0, s[0:1]
	s_mov_b32 s0, 0x58000
	v_add_co_u32_e32 v148, vcc, s0, v134
	v_cvt_pk_bf16_f32 v128, v16, v17
	v_cvt_pk_bf16_f32 v129, v18, v19
	v_cvt_pk_bf16_f32 v130, v8, v9
	v_cvt_pk_bf16_f32 v131, v10, v11
	v_addc_co_u32_e32 v149, vcc, 0, v135, vcc
	global_store_dwordx4 v[148:149], v[128:131], off
	v_lshl_add_u64 v[140:141], v[134:135], 0, s[4:5]
	s_nop 0
	v_cvt_pk_bf16_f32 v128, v116, v117
	v_cvt_pk_bf16_f32 v129, v118, v119
	v_cvt_pk_bf16_f32 v130, v108, v109
	v_cvt_pk_bf16_f32 v131, v110, v111
	global_store_dwordx4 v[134:135], v[128:131], off offset:256
	s_nop 1
	v_cvt_pk_bf16_f32 v128, v100, v101
	v_cvt_pk_bf16_f32 v129, v102, v103
	v_cvt_pk_bf16_f32 v130, v92, v93
	v_cvt_pk_bf16_f32 v131, v94, v95
	global_store_dwordx4 v[136:137], v[128:131], off offset:256
	s_nop 1
	v_cvt_pk_bf16_f32 v128, v84, v85
	v_cvt_pk_bf16_f32 v129, v86, v87
	v_cvt_pk_bf16_f32 v130, v76, v77
	v_cvt_pk_bf16_f32 v131, v78, v79
	global_store_dwordx4 v[138:139], v[128:131], off offset:256
	s_nop 1
	v_cvt_pk_bf16_f32 v128, v68, v69
	v_cvt_pk_bf16_f32 v129, v70, v71
	v_cvt_pk_bf16_f32 v130, v64, v65
	v_cvt_pk_bf16_f32 v131, v66, v67
	global_store_dwordx4 v[132:133], v[128:131], off offset:256
	s_nop 1
	v_cvt_pk_bf16_f32 v128, v52, v53
	v_cvt_pk_bf16_f32 v129, v54, v55
	v_cvt_pk_bf16_f32 v130, v44, v45
	v_cvt_pk_bf16_f32 v131, v46, v47
	global_store_dwordx4 v[140:141], v[128:131], off offset:256
	s_nop 1
	v_cvt_pk_bf16_f32 v128, v36, v37
	v_cvt_pk_bf16_f32 v129, v38, v39
	v_cvt_pk_bf16_f32 v130, v28, v29
	v_cvt_pk_bf16_f32 v131, v30, v31
	global_store_dwordx4 v[142:143], v[128:131], off offset:256
	s_nop 1
	v_cvt_pk_bf16_f32 v128, v20, v21
	v_cvt_pk_bf16_f32 v129, v22, v23
	v_cvt_pk_bf16_f32 v130, v12, v13
	v_cvt_pk_bf16_f32 v131, v14, v15
	global_store_dwordx4 v[144:145], v[128:131], off offset:256
	s_nop 1
	v_cvt_pk_bf16_f32 v128, v4, v5
	v_cvt_pk_bf16_f32 v129, v6, v7
	v_cvt_pk_bf16_f32 v130, v0, v1
	v_cvt_pk_bf16_f32 v131, v2, v3
	global_store_dwordx4 v[146:147], v[128:131], off offset:256

.LBB0_408:
	s_andn2_b64 vcc, exec, s[0:1]
	s_cbranch_vccnz .LBB0_410
	v_readlane_b32 s42, v250, 4
	v_lshlrev_b32_e32 v132, 2, v223
	v_readlane_b32 s43, v250, 5
	s_nop 4
	global_load_dwordx4 v[128:131], v132, s[42:43] offset:16
	s_nop 0
	global_load_dwordx4 v[132:135], v132, s[42:43]
	v_mul_f32_e32 v138, 0xbfb8aa3b, v124
	v_exp_f32_e32 v138, v138
	s_mov_b32 s2, 0x7f800000
	v_readlane_b32 s8, v251, 58
	v_lshlrev_b32_e32 v172, 1, v223
	v_add_f32_e32 v138, 1.0, v138
	v_rcp_f32_e32 v138, v138
	v_readlane_b32 s9, v251, 59
	v_ashrrev_i32_e32 v187, 31, v186
	s_waitcnt vmcnt(0)
	v_sub_f32_e32 v156, 1.0, v128
	v_sub_f32_e32 v150, 1.0, v132
	v_fma_f32 v138, v138, v150, v132
	v_cmp_gt_f32_e32 vcc, s33, v138
	v_sub_f32_e32 v151, 1.0, v133
	v_sub_f32_e32 v154, 1.0, v134
	v_cndmask_b32_e64 v139, 0, 32, vcc
	v_ldexp_f32 v138, v138, v139
	v_log_f32_e32 v138, v138
	v_sub_f32_e32 v155, 1.0, v135
	v_sub_f32_e32 v157, 1.0, v129
	v_sub_f32_e32 v159, 1.0, v130
	v_mul_f32_e32 v139, 0x3f317217, v138
	v_fma_f32 v139, v138, s97, -v139
	v_fmac_f32_e32 v139, 0x3377d1cf, v138
	v_fmac_f32_e32 v139, 0x3f317217, v138
	v_cmp_lt_f32_e64 s[0:1], |v138|, s2
	v_sub_f32_e32 v158, 1.0, v131
	v_lshl_add_u64 v[136:137], s[8:9], 0, v[172:173]
	v_cndmask_b32_e64 v138, v138, v139, s[0:1]
	v_cndmask_b32_e32 v139, 0, v213, vcc
	v_sub_f32_e32 v138, v138, v139
	v_mul_f32_e32 v139, 0xbfb8aa3b, v125
	v_exp_f32_e32 v139, v139
	s_nop 0
	v_add_f32_e32 v139, 1.0, v139
	v_rcp_f32_e32 v139, v139
	s_nop 0
	v_fma_f32 v139, v139, v151, v133
	v_cmp_gt_f32_e32 vcc, s33, v139
	s_nop 1
	v_cndmask_b32_e64 v140, 0, 32, vcc
	v_ldexp_f32 v139, v139, v140
	v_log_f32_e32 v139, v139
	s_nop 0
	v_mul_f32_e32 v140, 0x3f317217, v139
	v_fma_f32 v140, v139, s97, -v140
	v_fmac_f32_e32 v140, 0x3377d1cf, v139
	v_fmac_f32_e32 v140, 0x3f317217, v139
	v_cmp_lt_f32_e64 s[0:1], |v139|, s2
	s_nop 1
	v_cndmask_b32_e64 v139, v139, v140, s[0:1]
	v_cndmask_b32_e32 v140, 0, v213, vcc
	v_sub_f32_e32 v139, v139, v140
	v_mul_f32_e32 v140, 0xbfb8aa3b, v126
	v_exp_f32_e32 v140, v140
	s_nop 0
	v_add_f32_e32 v140, 1.0, v140
	v_rcp_f32_e32 v140, v140
	s_nop 0
	v_fma_f32 v140, v140, v154, v134
	v_cmp_gt_f32_e32 vcc, s33, v140
	s_nop 1
	v_cndmask_b32_e64 v141, 0, 32, vcc
	v_ldexp_f32 v140, v140, v141
	v_log_f32_e32 v140, v140
	s_nop 0
	v_mul_f32_e32 v141, 0x3f317217, v140
	v_fma_f32 v141, v140, s97, -v141
	v_fmac_f32_e32 v141, 0x3377d1cf, v140
	v_fmac_f32_e32 v141, 0x3f317217, v140
	v_cmp_lt_f32_e64 s[0:1], |v140|, s2
	s_nop 1
	v_cndmask_b32_e64 v140, v140, v141, s[0:1]
	v_cndmask_b32_e32 v141, 0, v213, vcc
	v_sub_f32_e32 v140, v140, v141
	v_mul_f32_e32 v141, 0xbfb8aa3b, v127
	v_exp_f32_e32 v141, v141
	s_nop 0
	v_add_f32_e32 v141, 1.0, v141
	v_rcp_f32_e32 v141, v141
	s_nop 0
	v_fma_f32 v141, v141, v155, v135
	v_cmp_gt_f32_e32 vcc, s33, v141
	s_nop 1
	v_cndmask_b32_e64 v142, 0, 32, vcc
	v_ldexp_f32 v141, v141, v142
	v_log_f32_e32 v141, v141
	s_nop 0
	v_mul_f32_e32 v142, 0x3f317217, v141
	v_fma_f32 v142, v141, s97, -v142
	v_fmac_f32_e32 v142, 0x3377d1cf, v141
	v_fmac_f32_e32 v142, 0x3f317217, v141
	v_cmp_lt_f32_e64 s[0:1], |v141|, s2
	s_nop 1
	v_cndmask_b32_e64 v141, v141, v142, s[0:1]
	v_cndmask_b32_e32 v142, 0, v213, vcc
	v_sub_f32_e32 v141, v141, v142
	v_mul_f32_e32 v142, 0xbfb8aa3b, v120
	v_exp_f32_e32 v142, v142
	s_nop 0
	v_add_f32_e32 v142, 1.0, v142
	v_rcp_f32_e32 v142, v142
	s_nop 0
	v_fma_f32 v142, v142, v156, v128
	v_cmp_gt_f32_e32 vcc, s33, v142
	s_nop 1
	v_cndmask_b32_e64 v143, 0, 32, vcc
	v_ldexp_f32 v142, v142, v143
	v_log_f32_e32 v142, v142
	s_nop 0
	v_mul_f32_e32 v143, 0x3f317217, v142
	v_fma_f32 v143, v142, s97, -v143
	v_fmac_f32_e32 v143, 0x3377d1cf, v142
	v_fmac_f32_e32 v143, 0x3f317217, v142
	v_cmp_lt_f32_e64 s[0:1], |v142|, s2
	s_nop 1
	v_cndmask_b32_e64 v142, v142, v143, s[0:1]
	v_cndmask_b32_e32 v143, 0, v213, vcc
	v_sub_f32_e32 v142, v142, v143
	v_mul_f32_e32 v143, 0xbfb8aa3b, v121
	v_exp_f32_e32 v143, v143
	s_nop 0
	v_add_f32_e32 v143, 1.0, v143
	v_rcp_f32_e32 v143, v143
	s_nop 0
	v_fma_f32 v143, v143, v157, v129
	v_cmp_gt_f32_e32 vcc, s33, v143
	s_nop 1
	v_cndmask_b32_e64 v144, 0, 32, vcc
	v_ldexp_f32 v143, v143, v144
	v_log_f32_e32 v143, v143
	s_nop 0
	v_mul_f32_e32 v144, 0x3f317217, v143
	v_fma_f32 v144, v143, s97, -v144
	v_fmac_f32_e32 v144, 0x3377d1cf, v143
	v_fmac_f32_e32 v144, 0x3f317217, v143
	v_cmp_lt_f32_e64 s[0:1], |v143|, s2
	s_nop 1
	v_cndmask_b32_e64 v143, v143, v144, s[0:1]
	v_cndmask_b32_e32 v144, 0, v213, vcc
	v_sub_f32_e32 v143, v143, v144
	v_mul_f32_e32 v144, 0xbfb8aa3b, v122
	v_exp_f32_e32 v144, v144
	v_cvt_pk_bf16_f32 v146, v142, v143
	v_add_f32_e32 v144, 1.0, v144
	v_rcp_f32_e32 v144, v144
	s_nop 0
	v_fma_f32 v144, v144, v159, v130
	v_cmp_gt_f32_e32 vcc, s33, v144
	s_nop 1
	v_cndmask_b32_e64 v145, 0, 32, vcc
	v_ldexp_f32 v144, v144, v145
	v_log_f32_e32 v144, v144
	s_nop 0
	v_mul_f32_e32 v145, 0x3f317217, v144
	v_fma_f32 v145, v144, s97, -v145
	v_fmac_f32_e32 v145, 0x3377d1cf, v144
	v_fmac_f32_e32 v145, 0x3f317217, v144
	v_cmp_lt_f32_e64 s[0:1], |v144|, s2
	s_nop 1
	v_cndmask_b32_e64 v144, v144, v145, s[0:1]
	v_cndmask_b32_e32 v145, 0, v213, vcc
	v_sub_f32_e32 v147, v144, v145
	v_mul_f32_e32 v144, 0xbfb8aa3b, v123
	v_exp_f32_e32 v144, v144
	s_nop 0
	v_add_f32_e32 v144, 1.0, v144
	v_rcp_f32_e32 v144, v144
	s_nop 0
	v_fma_f32 v144, v144, v158, v131
	v_cmp_gt_f32_e32 vcc, s33, v144
	s_nop 1
	v_cndmask_b32_e64 v145, 0, 32, vcc
	v_ldexp_f32 v144, v144, v145
	v_log_f32_e32 v144, v144
	s_nop 0
	v_mul_f32_e32 v145, 0x3f317217, v144
	v_fma_f32 v145, v144, s97, -v145
	v_fmac_f32_e32 v145, 0x3377d1cf, v144
	v_fmac_f32_e32 v145, 0x3f317217, v144
	v_cmp_lt_f32_e64 s[0:1], |v144|, s2
	s_nop 1
	v_cndmask_b32_e64 v144, v144, v145, s[0:1]
	v_cndmask_b32_e32 v145, 0, v213, vcc
	v_sub_f32_e32 v148, v144, v145
	v_cvt_pk_bf16_f32 v144, v138, v139
	v_lshlrev_b64 v[138:139], 11, v[186:187]
	v_cvt_pk_bf16_f32 v145, v140, v141
	v_cvt_pk_bf16_f32 v147, v147, v148
	v_lshl_add_u64 v[140:141], v[136:137], 0, v[138:139]
	global_store_dwordx4 v[140:141], v[144:147], off
	v_mul_f32_e32 v140, 0xbfb8aa3b, v112
	v_exp_f32_e32 v140, v140
	s_nop 0
	v_add_f32_e32 v140, 1.0, v140
	v_rcp_f32_e32 v140, v140
	s_nop 0
	v_fma_f32 v140, v140, v150, v132
	v_cmp_gt_f32_e32 vcc, s33, v140
	s_nop 1
	v_cndmask_b32_e64 v141, 0, 32, vcc
	v_ldexp_f32 v140, v140, v141
	v_log_f32_e32 v140, v140
	s_nop 0
	v_mul_f32_e32 v141, 0x3f317217, v140
	v_fma_f32 v141, v140, s97, -v141
	v_fmac_f32_e32 v141, 0x3377d1cf, v140
	v_fmac_f32_e32 v141, 0x3f317217, v140
	v_cmp_lt_f32_e64 s[0:1], |v140|, s2
	s_nop 1
	v_cndmask_b32_e64 v140, v140, v141, s[0:1]
	v_cndmask_b32_e32 v141, 0, v213, vcc
	v_sub_f32_e32 v140, v140, v141
	v_mul_f32_e32 v141, 0xbfb8aa3b, v113
	v_exp_f32_e32 v141, v141
	s_nop 0
	v_add_f32_e32 v141, 1.0, v141
	v_rcp_f32_e32 v141, v141
	s_nop 0
	v_fma_f32 v141, v141, v151, v133
	v_cmp_gt_f32_e32 vcc, s33, v141
	s_nop 1
	v_cndmask_b32_e64 v142, 0, 32, vcc
	v_ldexp_f32 v141, v141, v142
	v_log_f32_e32 v141, v141
	s_nop 0
	v_mul_f32_e32 v142, 0x3f317217, v141
	v_fma_f32 v142, v141, s97, -v142
	v_fmac_f32_e32 v142, 0x3377d1cf, v141
	v_fmac_f32_e32 v142, 0x3f317217, v141
	v_cmp_lt_f32_e64 s[0:1], |v141|, s2
	s_nop 1
	v_cndmask_b32_e64 v141, v141, v142, s[0:1]
	v_cndmask_b32_e32 v142, 0, v213, vcc
	v_sub_f32_e32 v141, v141, v142
	v_mul_f32_e32 v142, 0xbfb8aa3b, v114
	v_exp_f32_e32 v142, v142
	s_nop 0
	v_add_f32_e32 v142, 1.0, v142
	v_rcp_f32_e32 v142, v142
	s_nop 0
	v_fma_f32 v142, v142, v154, v134
	v_cmp_gt_f32_e32 vcc, s33, v142
	s_nop 1
	v_cndmask_b32_e64 v143, 0, 32, vcc
	v_ldexp_f32 v142, v142, v143
	v_log_f32_e32 v142, v142
	s_nop 0
	v_mul_f32_e32 v143, 0x3f317217, v142
	v_fma_f32 v143, v142, s97, -v143
	v_fmac_f32_e32 v143, 0x3377d1cf, v142
	v_fmac_f32_e32 v143, 0x3f317217, v142
	v_cmp_lt_f32_e64 s[0:1], |v142|, s2
	s_nop 1
	v_cndmask_b32_e64 v142, v142, v143, s[0:1]
	v_cndmask_b32_e32 v143, 0, v213, vcc
	v_sub_f32_e32 v143, v142, v143
	v_mul_f32_e32 v142, 0xbfb8aa3b, v115
	v_exp_f32_e32 v142, v142
	s_nop 0
	v_add_f32_e32 v142, 1.0, v142
	v_rcp_f32_e32 v142, v142
	s_nop 0
	v_fma_f32 v142, v142, v155, v135
	v_cmp_gt_f32_e32 vcc, s33, v142
	s_nop 1
	v_cndmask_b32_e64 v144, 0, 32, vcc
	v_ldexp_f32 v142, v142, v144
	v_log_f32_e32 v142, v142
	s_nop 0
	v_mul_f32_e32 v144, 0x3f317217, v142
	v_fma_f32 v144, v142, s97, -v144
	v_fmac_f32_e32 v144, 0x3377d1cf, v142
	v_fmac_f32_e32 v144, 0x3f317217, v142
	v_cmp_lt_f32_e64 s[0:1], |v142|, s2
	s_nop 1
	v_cndmask_b32_e64 v142, v142, v144, s[0:1]
	v_cndmask_b32_e32 v144, 0, v213, vcc
	v_sub_f32_e32 v144, v142, v144
	v_mul_f32_e32 v142, 0xbfb8aa3b, v104
	v_exp_f32_e32 v142, v142
	v_cvt_pk_bf16_f32 v143, v143, v144
	v_add_f32_e32 v142, 1.0, v142
	v_rcp_f32_e32 v142, v142
	s_nop 0
	v_fma_f32 v142, v142, v156, v128
	v_cmp_gt_f32_e32 vcc, s33, v142
	s_nop 1
	v_cndmask_b32_e64 v145, 0, 32, vcc
	v_ldexp_f32 v142, v142, v145
	v_log_f32_e32 v142, v142
	s_nop 0
	v_mul_f32_e32 v145, 0x3f317217, v142
	v_fma_f32 v145, v142, s97, -v145
	v_fmac_f32_e32 v145, 0x3377d1cf, v142
	v_fmac_f32_e32 v145, 0x3f317217, v142
	v_cmp_lt_f32_e64 s[0:1], |v142|, s2
	s_nop 1
	v_cndmask_b32_e64 v142, v142, v145, s[0:1]
	v_cndmask_b32_e32 v145, 0, v213, vcc
	v_sub_f32_e32 v145, v142, v145
	v_mul_f32_e32 v142, 0xbfb8aa3b, v105
	v_exp_f32_e32 v142, v142
	s_nop 0
	v_add_f32_e32 v142, 1.0, v142
	v_rcp_f32_e32 v142, v142
	s_nop 0
	v_fma_f32 v142, v142, v157, v129
	v_cmp_gt_f32_e32 vcc, s33, v142
	s_nop 1
	v_cndmask_b32_e64 v146, 0, 32, vcc
	v_ldexp_f32 v142, v142, v146
	v_log_f32_e32 v142, v142
	s_nop 0
	v_mul_f32_e32 v146, 0x3f317217, v142
	v_fma_f32 v146, v142, s97, -v146
	v_fmac_f32_e32 v146, 0x3377d1cf, v142
	v_fmac_f32_e32 v146, 0x3f317217, v142
	v_cmp_lt_f32_e64 s[0:1], |v142|, s2
	s_nop 1
	v_cndmask_b32_e64 v142, v142, v146, s[0:1]
	v_cndmask_b32_e32 v146, 0, v213, vcc
	v_sub_f32_e32 v146, v142, v146
	v_mul_f32_e32 v142, 0xbfb8aa3b, v106
	v_exp_f32_e32 v142, v142
	v_cvt_pk_bf16_f32 v144, v145, v146
	v_add_f32_e32 v142, 1.0, v142
	v_rcp_f32_e32 v142, v142
	s_nop 0
	v_fma_f32 v142, v142, v159, v130
	v_cmp_gt_f32_e32 vcc, s33, v142
	s_nop 1
	v_cndmask_b32_e64 v147, 0, 32, vcc
	v_ldexp_f32 v142, v142, v147
	v_log_f32_e32 v142, v142
	s_nop 0
	v_mul_f32_e32 v147, 0x3f317217, v142
	v_fma_f32 v147, v142, s97, -v147
	v_fmac_f32_e32 v147, 0x3377d1cf, v142
	v_fmac_f32_e32 v147, 0x3f317217, v142
	v_cmp_lt_f32_e64 s[0:1], |v142|, s2
	s_nop 1
	v_cndmask_b32_e64 v142, v142, v147, s[0:1]
	v_cndmask_b32_e32 v147, 0, v213, vcc
	v_sub_f32_e32 v147, v142, v147
	v_mul_f32_e32 v142, 0xbfb8aa3b, v107
	v_exp_f32_e32 v142, v142
	s_nop 0
	v_add_f32_e32 v142, 1.0, v142
	v_rcp_f32_e32 v142, v142
	s_nop 0
	v_fma_f32 v142, v142, v158, v131
	v_cmp_gt_f32_e32 vcc, s33, v142
	s_nop 1
	v_cndmask_b32_e64 v148, 0, 32, vcc
	v_ldexp_f32 v142, v142, v148
	v_log_f32_e32 v142, v142
	s_nop 0
	v_mul_f32_e32 v148, 0x3f317217, v142
	v_fma_f32 v148, v142, s97, -v148
	v_fmac_f32_e32 v148, 0x3377d1cf, v142
	v_fmac_f32_e32 v148, 0x3f317217, v142
	v_cmp_lt_f32_e64 s[0:1], |v142|, s2
	s_nop 1
	v_cndmask_b32_e64 v142, v142, v148, s[0:1]
	v_cndmask_b32_e32 v148, 0, v213, vcc
	v_sub_f32_e32 v148, v142, v148
	v_cvt_pk_bf16_f32 v142, v140, v141
	v_or_b32_e32 v140, 16, v186
	v_ashrrev_i32_e32 v141, 31, v140
	v_lshlrev_b64 v[140:141], 11, v[140:141]
	v_cvt_pk_bf16_f32 v145, v147, v148
	v_lshl_add_u64 v[146:147], v[136:137], 0, v[140:141]
	global_store_dwordx4 v[146:147], v[142:145], off
	s_nop 1
	v_mul_f32_e32 v142, 0xbfb8aa3b, v96
	v_exp_f32_e32 v142, v142
	s_nop 0
	v_add_f32_e32 v142, 1.0, v142
	v_rcp_f32_e32 v142, v142
	s_nop 0
	v_fma_f32 v142, v142, v150, v132
	v_cmp_gt_f32_e32 vcc, s33, v142
	s_nop 1
	v_cndmask_b32_e64 v143, 0, 32, vcc
	v_ldexp_f32 v142, v142, v143
	v_log_f32_e32 v142, v142
	s_nop 0
	v_mul_f32_e32 v143, 0x3f317217, v142
	v_fma_f32 v143, v142, s97, -v143
	v_fmac_f32_e32 v143, 0x3377d1cf, v142
	v_fmac_f32_e32 v143, 0x3f317217, v142
	v_cmp_lt_f32_e64 s[0:1], |v142|, s2
	s_nop 1
	v_cndmask_b32_e64 v142, v142, v143, s[0:1]
	v_cndmask_b32_e32 v143, 0, v213, vcc
	v_sub_f32_e32 v142, v142, v143
	v_mul_f32_e32 v143, 0xbfb8aa3b, v97
	v_exp_f32_e32 v143, v143
	s_nop 0
	v_add_f32_e32 v143, 1.0, v143
	v_rcp_f32_e32 v143, v143
	s_nop 0
	v_fma_f32 v143, v143, v151, v133
	v_cmp_gt_f32_e32 vcc, s33, v143
	s_nop 1
	v_cndmask_b32_e64 v144, 0, 32, vcc
	v_ldexp_f32 v143, v143, v144
	v_log_f32_e32 v143, v143
	s_nop 0
	v_mul_f32_e32 v144, 0x3f317217, v143
	v_fma_f32 v144, v143, s97, -v144
	v_fmac_f32_e32 v144, 0x3377d1cf, v143
	v_fmac_f32_e32 v144, 0x3f317217, v143
	v_cmp_lt_f32_e64 s[0:1], |v143|, s2
	s_nop 1
	v_cndmask_b32_e64 v143, v143, v144, s[0:1]
	v_cndmask_b32_e32 v144, 0, v213, vcc
	v_sub_f32_e32 v143, v143, v144
	v_mul_f32_e32 v144, 0xbfb8aa3b, v98
	v_exp_f32_e32 v144, v144
	s_nop 0
	v_add_f32_e32 v144, 1.0, v144
	v_rcp_f32_e32 v144, v144
	s_nop 0
	v_fma_f32 v144, v144, v154, v134
	v_cmp_gt_f32_e32 vcc, s33, v144
	s_nop 1
	v_cndmask_b32_e64 v145, 0, 32, vcc
	v_ldexp_f32 v144, v144, v145
	v_log_f32_e32 v144, v144
	s_nop 0
	v_mul_f32_e32 v145, 0x3f317217, v144
	v_fma_f32 v145, v144, s97, -v145
	v_fmac_f32_e32 v145, 0x3377d1cf, v144
	v_fmac_f32_e32 v145, 0x3f317217, v144
	v_cmp_lt_f32_e64 s[0:1], |v144|, s2
	s_nop 1
	v_cndmask_b32_e64 v144, v144, v145, s[0:1]
	v_cndmask_b32_e32 v145, 0, v213, vcc
	v_sub_f32_e32 v145, v144, v145
	v_mul_f32_e32 v144, 0xbfb8aa3b, v99
	v_exp_f32_e32 v144, v144
	s_nop 0
	v_add_f32_e32 v144, 1.0, v144
	v_rcp_f32_e32 v144, v144
	s_nop 0
	v_fma_f32 v144, v144, v155, v135
	v_cmp_gt_f32_e32 vcc, s33, v144
	s_nop 1
	v_cndmask_b32_e64 v146, 0, 32, vcc
	v_ldexp_f32 v144, v144, v146
	v_log_f32_e32 v144, v144
	s_nop 0
	v_mul_f32_e32 v146, 0x3f317217, v144
	v_fma_f32 v146, v144, s97, -v146
	v_fmac_f32_e32 v146, 0x3377d1cf, v144
	v_fmac_f32_e32 v146, 0x3f317217, v144
	v_cmp_lt_f32_e64 s[0:1], |v144|, s2
	s_nop 1
	v_cndmask_b32_e64 v144, v144, v146, s[0:1]
	v_cndmask_b32_e32 v146, 0, v213, vcc
	v_sub_f32_e32 v146, v144, v146
	v_mul_f32_e32 v144, 0xbfb8aa3b, v88
	v_exp_f32_e32 v144, v144
	v_cvt_pk_bf16_f32 v145, v145, v146
	v_add_f32_e32 v144, 1.0, v144
	v_rcp_f32_e32 v144, v144
	s_nop 0
	v_fma_f32 v144, v144, v156, v128
	v_cmp_gt_f32_e32 vcc, s33, v144
	s_nop 1
	v_cndmask_b32_e64 v147, 0, 32, vcc
	v_ldexp_f32 v144, v144, v147
	v_log_f32_e32 v144, v144
	s_nop 0
	v_mul_f32_e32 v147, 0x3f317217, v144
	v_fma_f32 v147, v144, s97, -v147
	v_fmac_f32_e32 v147, 0x3377d1cf, v144
	v_fmac_f32_e32 v147, 0x3f317217, v144
	v_cmp_lt_f32_e64 s[0:1], |v144|, s2
	s_nop 1
	v_cndmask_b32_e64 v144, v144, v147, s[0:1]
	v_cndmask_b32_e32 v147, 0, v213, vcc
	v_sub_f32_e32 v147, v144, v147
	v_mul_f32_e32 v144, 0xbfb8aa3b, v89
	v_exp_f32_e32 v144, v144
	s_nop 0
	v_add_f32_e32 v144, 1.0, v144
	v_rcp_f32_e32 v144, v144
	s_nop 0
	v_fma_f32 v144, v144, v157, v129
	v_cmp_gt_f32_e32 vcc, s33, v144
	s_nop 1
	v_cndmask_b32_e64 v148, 0, 32, vcc
	v_ldexp_f32 v144, v144, v148
	v_log_f32_e32 v144, v144
	s_nop 0
	v_mul_f32_e32 v148, 0x3f317217, v144
	v_fma_f32 v148, v144, s97, -v148
	v_fmac_f32_e32 v148, 0x3377d1cf, v144
	v_fmac_f32_e32 v148, 0x3f317217, v144
	v_cmp_lt_f32_e64 s[0:1], |v144|, s2
	s_nop 1
	v_cndmask_b32_e64 v144, v144, v148, s[0:1]
	v_cndmask_b32_e32 v148, 0, v213, vcc
	v_sub_f32_e32 v148, v144, v148
	v_mul_f32_e32 v144, 0xbfb8aa3b, v90
	v_exp_f32_e32 v144, v144
	v_cvt_pk_bf16_f32 v146, v147, v148
	v_add_f32_e32 v144, 1.0, v144
	v_rcp_f32_e32 v144, v144
	s_nop 0
	v_fma_f32 v144, v144, v159, v130
	v_cmp_gt_f32_e32 vcc, s33, v144
	s_nop 1
	v_cndmask_b32_e64 v149, 0, 32, vcc
	v_ldexp_f32 v144, v144, v149
	v_log_f32_e32 v144, v144
	s_nop 0
	v_mul_f32_e32 v149, 0x3f317217, v144
	v_fma_f32 v149, v144, s97, -v149
	v_fmac_f32_e32 v149, 0x3377d1cf, v144
	v_fmac_f32_e32 v149, 0x3f317217, v144
	v_cmp_lt_f32_e64 s[0:1], |v144|, s2
	s_nop 1
	v_cndmask_b32_e64 v144, v144, v149, s[0:1]
	v_cndmask_b32_e32 v149, 0, v213, vcc
	v_sub_f32_e32 v149, v144, v149
	v_mul_f32_e32 v144, 0xbfb8aa3b, v91
	v_exp_f32_e32 v144, v144
	s_nop 0
	v_add_f32_e32 v144, 1.0, v144
	v_rcp_f32_e32 v144, v144
	s_nop 0
	v_fma_f32 v144, v144, v158, v131
	v_cmp_gt_f32_e32 vcc, s33, v144
	s_nop 1
	v_cndmask_b32_e64 v152, 0, 32, vcc
	v_ldexp_f32 v144, v144, v152
	v_log_f32_e32 v144, v144
	s_nop 0
	v_mul_f32_e32 v152, 0x3f317217, v144
	v_fma_f32 v152, v144, s97, -v152
	v_fmac_f32_e32 v152, 0x3377d1cf, v144
	v_fmac_f32_e32 v152, 0x3f317217, v144
	v_cmp_lt_f32_e64 s[0:1], |v144|, s2
	s_nop 1
	v_cndmask_b32_e64 v144, v144, v152, s[0:1]
	v_cndmask_b32_e32 v152, 0, v213, vcc
	v_sub_f32_e32 v152, v144, v152
	v_cvt_pk_bf16_f32 v144, v142, v143
	v_or_b32_e32 v142, 32, v186
	v_ashrrev_i32_e32 v143, 31, v142
	v_lshlrev_b64 v[142:143], 11, v[142:143]
	v_cvt_pk_bf16_f32 v147, v149, v152
	v_lshl_add_u64 v[148:149], v[136:137], 0, v[142:143]
	global_store_dwordx4 v[148:149], v[144:147], off
	v_lshl_add_u64 v[142:143], s[8:9], 0, v[142:143]
	s_nop 0
	v_mul_f32_e32 v144, 0xbfb8aa3b, v80
	v_exp_f32_e32 v144, v144
	s_nop 0
	v_add_f32_e32 v144, 1.0, v144
	v_rcp_f32_e32 v144, v144
	s_nop 0
	v_fma_f32 v144, v144, v150, v132
	v_cmp_gt_f32_e32 vcc, s33, v144
	s_nop 1
	v_cndmask_b32_e64 v145, 0, 32, vcc
	v_ldexp_f32 v144, v144, v145
	v_log_f32_e32 v144, v144
	s_nop 0
	v_mul_f32_e32 v145, 0x3f317217, v144
	v_fma_f32 v145, v144, s97, -v145
	v_fmac_f32_e32 v145, 0x3377d1cf, v144
	v_fmac_f32_e32 v145, 0x3f317217, v144
	v_cmp_lt_f32_e64 s[0:1], |v144|, s2
	s_nop 1
	v_cndmask_b32_e64 v144, v144, v145, s[0:1]
	v_cndmask_b32_e32 v145, 0, v213, vcc
	v_sub_f32_e32 v144, v144, v145
	v_mul_f32_e32 v145, 0xbfb8aa3b, v81
	v_exp_f32_e32 v145, v145
	s_nop 0
	v_add_f32_e32 v145, 1.0, v145
	v_rcp_f32_e32 v145, v145
	s_nop 0
	v_fma_f32 v145, v145, v151, v133
	v_cmp_gt_f32_e32 vcc, s33, v145
	s_nop 1
	v_cndmask_b32_e64 v146, 0, 32, vcc
	v_ldexp_f32 v145, v145, v146
	v_log_f32_e32 v145, v145
	s_nop 0
	v_mul_f32_e32 v146, 0x3f317217, v145
	v_fma_f32 v146, v145, s97, -v146
	v_fmac_f32_e32 v146, 0x3377d1cf, v145
	v_fmac_f32_e32 v146, 0x3f317217, v145
	v_cmp_lt_f32_e64 s[0:1], |v145|, s2
	s_nop 1
	v_cndmask_b32_e64 v145, v145, v146, s[0:1]
	v_cndmask_b32_e32 v146, 0, v213, vcc
	v_sub_f32_e32 v145, v145, v146
	v_mul_f32_e32 v146, 0xbfb8aa3b, v82
	v_exp_f32_e32 v146, v146
	s_nop 0
	v_add_f32_e32 v146, 1.0, v146
	v_rcp_f32_e32 v146, v146
	s_nop 0
	v_fma_f32 v146, v146, v154, v134
	v_cmp_gt_f32_e32 vcc, s33, v146
	s_nop 1
	v_cndmask_b32_e64 v147, 0, 32, vcc
	v_ldexp_f32 v146, v146, v147
	v_log_f32_e32 v146, v146
	s_nop 0
	v_mul_f32_e32 v147, 0x3f317217, v146
	v_fma_f32 v147, v146, s97, -v147
	v_fmac_f32_e32 v147, 0x3377d1cf, v146
	v_fmac_f32_e32 v147, 0x3f317217, v146
	v_cmp_lt_f32_e64 s[0:1], |v146|, s2
	s_nop 1
	v_cndmask_b32_e64 v146, v146, v147, s[0:1]
	v_cndmask_b32_e32 v147, 0, v213, vcc
	v_sub_f32_e32 v147, v146, v147
	v_mul_f32_e32 v146, 0xbfb8aa3b, v83
	v_exp_f32_e32 v146, v146
	s_nop 0
	v_add_f32_e32 v146, 1.0, v146
	v_rcp_f32_e32 v146, v146
	s_nop 0
	v_fma_f32 v146, v146, v155, v135
	v_cmp_gt_f32_e32 vcc, s33, v146
	s_nop 1
	v_cndmask_b32_e64 v148, 0, 32, vcc
	v_ldexp_f32 v146, v146, v148
	v_log_f32_e32 v146, v146
	s_nop 0
	v_mul_f32_e32 v148, 0x3f317217, v146
	v_fma_f32 v148, v146, s97, -v148
	v_fmac_f32_e32 v148, 0x3377d1cf, v146
	v_fmac_f32_e32 v148, 0x3f317217, v146
	v_cmp_lt_f32_e64 s[0:1], |v146|, s2
	s_nop 1
	v_cndmask_b32_e64 v146, v146, v148, s[0:1]
	v_cndmask_b32_e32 v148, 0, v213, vcc
	v_sub_f32_e32 v148, v146, v148
	v_mul_f32_e32 v146, 0xbfb8aa3b, v72
	v_exp_f32_e32 v146, v146
	v_cvt_pk_bf16_f32 v147, v147, v148
	v_add_f32_e32 v146, 1.0, v146
	v_rcp_f32_e32 v146, v146
	s_nop 0
	v_fma_f32 v146, v146, v156, v128
	v_cmp_gt_f32_e32 vcc, s33, v146
	s_nop 1
	v_cndmask_b32_e64 v149, 0, 32, vcc
	v_ldexp_f32 v146, v146, v149
	v_log_f32_e32 v146, v146
	s_nop 0
	v_mul_f32_e32 v149, 0x3f317217, v146
	v_fma_f32 v149, v146, s97, -v149
	v_fmac_f32_e32 v149, 0x3377d1cf, v146
	v_fmac_f32_e32 v149, 0x3f317217, v146
	v_cmp_lt_f32_e64 s[0:1], |v146|, s2
	s_nop 1
	v_cndmask_b32_e64 v146, v146, v149, s[0:1]
	v_cndmask_b32_e32 v149, 0, v213, vcc
	v_sub_f32_e32 v149, v146, v149
	v_mul_f32_e32 v146, 0xbfb8aa3b, v73
	v_exp_f32_e32 v146, v146
	s_nop 0
	v_add_f32_e32 v146, 1.0, v146
	v_rcp_f32_e32 v146, v146
	s_nop 0
	v_fma_f32 v146, v146, v157, v129
	v_cmp_gt_f32_e32 vcc, s33, v146
	s_nop 1
	v_cndmask_b32_e64 v152, 0, 32, vcc
	v_ldexp_f32 v146, v146, v152
	v_log_f32_e32 v146, v146
	s_nop 0
	v_mul_f32_e32 v152, 0x3f317217, v146
	v_fma_f32 v152, v146, s97, -v152
	v_fmac_f32_e32 v152, 0x3377d1cf, v146
	v_fmac_f32_e32 v152, 0x3f317217, v146
	v_cmp_lt_f32_e64 s[0:1], |v146|, s2
	s_nop 1
	v_cndmask_b32_e64 v146, v146, v152, s[0:1]
	v_cndmask_b32_e32 v152, 0, v213, vcc
	v_sub_f32_e32 v152, v146, v152
	v_mul_f32_e32 v146, 0xbfb8aa3b, v74
	v_exp_f32_e32 v146, v146
	v_cvt_pk_bf16_f32 v148, v149, v152
	v_add_f32_e32 v146, 1.0, v146
	v_rcp_f32_e32 v146, v146
	s_nop 0
	v_fma_f32 v146, v146, v159, v130
	v_cmp_gt_f32_e32 vcc, s33, v146
	s_nop 1
	v_cndmask_b32_e64 v153, 0, 32, vcc
	v_ldexp_f32 v146, v146, v153
	v_log_f32_e32 v146, v146
	s_nop 0
	v_mul_f32_e32 v153, 0x3f317217, v146
	v_fma_f32 v153, v146, s97, -v153
	v_fmac_f32_e32 v153, 0x3377d1cf, v146
	v_fmac_f32_e32 v153, 0x3f317217, v146
	v_cmp_lt_f32_e64 s[0:1], |v146|, s2
	s_nop 1
	v_cndmask_b32_e64 v146, v146, v153, s[0:1]
	v_cndmask_b32_e32 v153, 0, v213, vcc
	v_sub_f32_e32 v153, v146, v153
	v_mul_f32_e32 v146, 0xbfb8aa3b, v75
	v_exp_f32_e32 v146, v146
	s_nop 0
	v_add_f32_e32 v146, 1.0, v146
	v_rcp_f32_e32 v146, v146
	s_nop 0
	v_fma_f32 v146, v146, v158, v131
	v_cmp_gt_f32_e32 vcc, s33, v146
	s_nop 1
	v_cndmask_b32_e64 v160, 0, 32, vcc
	v_ldexp_f32 v146, v146, v160
	v_log_f32_e32 v146, v146
	s_nop 0
	v_mul_f32_e32 v160, 0x3f317217, v146
	v_fma_f32 v160, v146, s97, -v160
	v_fmac_f32_e32 v160, 0x3377d1cf, v146
	v_fmac_f32_e32 v160, 0x3f317217, v146
	v_cmp_lt_f32_e64 s[0:1], |v146|, s2
	s_nop 1
	v_cndmask_b32_e64 v146, v146, v160, s[0:1]
	v_cndmask_b32_e32 v160, 0, v213, vcc
	v_sub_f32_e32 v160, v146, v160
	v_cvt_pk_bf16_f32 v146, v144, v145
	v_or_b32_e32 v144, 48, v186
	v_ashrrev_i32_e32 v145, 31, v144
	v_lshlrev_b64 v[144:145], 11, v[144:145]
	v_cvt_pk_bf16_f32 v149, v153, v160
	v_lshl_add_u64 v[152:153], v[136:137], 0, v[144:145]
	global_store_dwordx4 v[152:153], v[146:149], off
	s_nop 1
	v_mul_f32_e32 v146, 0xbfb8aa3b, v60
	v_exp_f32_e32 v146, v146
	s_nop 0
	v_add_f32_e32 v146, 1.0, v146
	v_rcp_f32_e32 v146, v146
	s_nop 0
	v_fma_f32 v146, v146, v150, v132
	v_cmp_gt_f32_e32 vcc, s33, v146
	s_nop 1
	v_cndmask_b32_e64 v147, 0, 32, vcc
	v_ldexp_f32 v146, v146, v147
	v_log_f32_e32 v146, v146
	s_nop 0
	v_mul_f32_e32 v147, 0x3f317217, v146
	v_fma_f32 v147, v146, s97, -v147
	v_fmac_f32_e32 v147, 0x3377d1cf, v146
	v_fmac_f32_e32 v147, 0x3f317217, v146
	v_cmp_lt_f32_e64 s[0:1], |v146|, s2
	s_nop 1
	v_cndmask_b32_e64 v146, v146, v147, s[0:1]
	v_cndmask_b32_e32 v147, 0, v213, vcc
	v_sub_f32_e32 v146, v146, v147
	v_mul_f32_e32 v147, 0xbfb8aa3b, v61
	v_exp_f32_e32 v147, v147
	s_nop 0
	v_add_f32_e32 v147, 1.0, v147
	v_rcp_f32_e32 v147, v147
	s_nop 0
	v_fma_f32 v147, v147, v151, v133
	v_cmp_gt_f32_e32 vcc, s33, v147
	s_nop 1
	v_cndmask_b32_e64 v148, 0, 32, vcc
	v_ldexp_f32 v147, v147, v148
	v_log_f32_e32 v147, v147
	s_nop 0
	v_mul_f32_e32 v148, 0x3f317217, v147
	v_fma_f32 v148, v147, s97, -v148
	v_fmac_f32_e32 v148, 0x3377d1cf, v147
	v_fmac_f32_e32 v148, 0x3f317217, v147
	v_cmp_lt_f32_e64 s[0:1], |v147|, s2
	s_nop 1
	v_cndmask_b32_e64 v147, v147, v148, s[0:1]
	v_cndmask_b32_e32 v148, 0, v213, vcc
	v_sub_f32_e32 v147, v147, v148
	v_mul_f32_e32 v148, 0xbfb8aa3b, v62
	v_exp_f32_e32 v148, v148
	s_nop 0
	v_add_f32_e32 v148, 1.0, v148
	v_rcp_f32_e32 v148, v148
	s_nop 0
	v_fma_f32 v148, v148, v154, v134
	v_cmp_gt_f32_e32 vcc, s33, v148
	s_nop 1
	v_cndmask_b32_e64 v149, 0, 32, vcc
	v_ldexp_f32 v148, v148, v149
	v_log_f32_e32 v148, v148
	s_nop 0
	v_mul_f32_e32 v149, 0x3f317217, v148
	v_fma_f32 v149, v148, s97, -v149
	v_fmac_f32_e32 v149, 0x3377d1cf, v148
	v_fmac_f32_e32 v149, 0x3f317217, v148
	v_cmp_lt_f32_e64 s[0:1], |v148|, s2
	s_nop 1
	v_cndmask_b32_e64 v148, v148, v149, s[0:1]
	v_cndmask_b32_e32 v149, 0, v213, vcc
	v_sub_f32_e32 v148, v148, v149
	v_mul_f32_e32 v149, 0xbfb8aa3b, v63
	v_exp_f32_e32 v149, v149
	s_nop 0
	v_add_f32_e32 v149, 1.0, v149
	v_rcp_f32_e32 v149, v149
	s_nop 0
	v_fma_f32 v149, v149, v155, v135
	v_cmp_gt_f32_e32 vcc, s33, v149
	s_nop 1
	v_cndmask_b32_e64 v152, 0, 32, vcc
	v_ldexp_f32 v149, v149, v152
	v_log_f32_e32 v149, v149
	s_nop 0
	v_mul_f32_e32 v152, 0x3f317217, v149
	v_fma_f32 v152, v149, s97, -v152
	v_fmac_f32_e32 v152, 0x3377d1cf, v149
	v_fmac_f32_e32 v152, 0x3f317217, v149
	v_cmp_lt_f32_e64 s[0:1], |v149|, s2
	s_nop 1
	v_cndmask_b32_e64 v149, v149, v152, s[0:1]
	v_cndmask_b32_e32 v152, 0, v213, vcc
	v_sub_f32_e32 v149, v149, v152
	v_mul_f32_e32 v152, 0xbfb8aa3b, v56
	v_exp_f32_e32 v152, v152
	s_nop 0
	v_add_f32_e32 v152, 1.0, v152
	v_rcp_f32_e32 v152, v152
	s_nop 0
	v_fma_f32 v152, v152, v156, v128
	v_cmp_gt_f32_e32 vcc, s33, v152
	s_nop 1
	v_cndmask_b32_e64 v153, 0, 32, vcc
	v_ldexp_f32 v152, v152, v153
	v_log_f32_e32 v152, v152
	s_nop 0
	v_mul_f32_e32 v153, 0x3f317217, v152
	v_fma_f32 v153, v152, s97, -v153
	v_fmac_f32_e32 v153, 0x3377d1cf, v152
	v_fmac_f32_e32 v153, 0x3f317217, v152
	v_cmp_lt_f32_e64 s[0:1], |v152|, s2
	s_nop 1
	v_cndmask_b32_e64 v152, v152, v153, s[0:1]
	v_cndmask_b32_e32 v153, 0, v213, vcc
	v_sub_f32_e32 v152, v152, v153
	v_mul_f32_e32 v153, 0xbfb8aa3b, v57
	v_exp_f32_e32 v153, v153
	s_nop 0
	v_add_f32_e32 v153, 1.0, v153
	v_rcp_f32_e32 v153, v153
	s_nop 0
	v_fma_f32 v153, v153, v157, v129
	v_cmp_gt_f32_e32 vcc, s33, v153
	s_nop 1
	v_cndmask_b32_e64 v160, 0, 32, vcc
	v_ldexp_f32 v153, v153, v160
	v_log_f32_e32 v153, v153
	s_nop 0
	v_mul_f32_e32 v160, 0x3f317217, v153
	v_fma_f32 v160, v153, s97, -v160
	v_fmac_f32_e32 v160, 0x3377d1cf, v153
	v_fmac_f32_e32 v160, 0x3f317217, v153
	v_cmp_lt_f32_e64 s[0:1], |v153|, s2
	s_nop 1
	v_cndmask_b32_e64 v153, v153, v160, s[0:1]
	v_cndmask_b32_e32 v160, 0, v213, vcc
	v_sub_f32_e32 v153, v153, v160
	v_mul_f32_e32 v160, 0xbfb8aa3b, v58
	v_exp_f32_e32 v160, v160
	v_cvt_pk_bf16_f32 v162, v152, v153
	v_add_f32_e32 v160, 1.0, v160
	v_rcp_f32_e32 v160, v160
	s_nop 0
	v_fma_f32 v160, v160, v159, v130
	v_cmp_gt_f32_e32 vcc, s33, v160
	s_nop 1
	v_cndmask_b32_e64 v161, 0, 32, vcc
	v_ldexp_f32 v160, v160, v161
	v_log_f32_e32 v160, v160
	s_nop 0
	v_mul_f32_e32 v161, 0x3f317217, v160
	v_fma_f32 v161, v160, s97, -v161
	v_fmac_f32_e32 v161, 0x3377d1cf, v160
	v_fmac_f32_e32 v161, 0x3f317217, v160
	v_cmp_lt_f32_e64 s[0:1], |v160|, s2
	s_nop 1
	v_cndmask_b32_e64 v160, v160, v161, s[0:1]
	v_cndmask_b32_e32 v161, 0, v213, vcc
	v_sub_f32_e32 v163, v160, v161
	v_mul_f32_e32 v160, 0xbfb8aa3b, v59
	v_exp_f32_e32 v160, v160
	s_nop 0
	v_add_f32_e32 v160, 1.0, v160
	v_rcp_f32_e32 v160, v160
	s_nop 0
	v_fma_f32 v160, v160, v158, v131
	v_cmp_gt_f32_e32 vcc, s33, v160
	s_nop 1
	v_cndmask_b32_e64 v161, 0, 32, vcc
	v_ldexp_f32 v160, v160, v161
	v_log_f32_e32 v160, v160
	s_nop 0
	v_mul_f32_e32 v161, 0x3f317217, v160
	v_fma_f32 v161, v160, s97, -v161
	v_fmac_f32_e32 v161, 0x3377d1cf, v160
	v_fmac_f32_e32 v161, 0x3f317217, v160
	v_cmp_lt_f32_e64 s[0:1], |v160|, s2
	s_nop 1
	v_cndmask_b32_e64 v160, v160, v161, s[0:1]
	v_cndmask_b32_e32 v161, 0, v213, vcc
	v_sub_f32_e32 v164, v160, v161
	v_cvt_pk_bf16_f32 v160, v146, v147
	v_lshl_add_u64 v[146:147], v[138:139], 0, s[4:5]
	v_cvt_pk_bf16_f32 v161, v148, v149
	v_cvt_pk_bf16_f32 v163, v163, v164
	v_lshl_add_u64 v[148:149], v[136:137], 0, v[146:147]
	global_store_dwordx4 v[148:149], v[160:163], off
	v_mul_f32_e32 v148, 0xbfb8aa3b, v48
	v_exp_f32_e32 v148, v148
	s_nop 0
	v_add_f32_e32 v148, 1.0, v148
	v_rcp_f32_e32 v148, v148
	s_nop 0
	v_fma_f32 v148, v148, v150, v132
	v_cmp_gt_f32_e32 vcc, s33, v148
	s_nop 1
	v_cndmask_b32_e64 v149, 0, 32, vcc
	v_ldexp_f32 v148, v148, v149
	v_log_f32_e32 v148, v148
	s_nop 0
	v_mul_f32_e32 v149, 0x3f317217, v148
	v_fma_f32 v149, v148, s97, -v149
	v_fmac_f32_e32 v149, 0x3377d1cf, v148
	v_fmac_f32_e32 v149, 0x3f317217, v148
	v_cmp_lt_f32_e64 s[0:1], |v148|, s2
	s_nop 1
	v_cndmask_b32_e64 v148, v148, v149, s[0:1]
	v_cndmask_b32_e32 v149, 0, v213, vcc
	v_sub_f32_e32 v148, v148, v149
	v_mul_f32_e32 v149, 0xbfb8aa3b, v49
	v_exp_f32_e32 v149, v149
	s_nop 0
	v_add_f32_e32 v149, 1.0, v149
	v_rcp_f32_e32 v149, v149
	s_nop 0
	v_fma_f32 v149, v149, v151, v133
	v_cmp_gt_f32_e32 vcc, s33, v149
	s_nop 1
	v_cndmask_b32_e64 v152, 0, 32, vcc
	v_ldexp_f32 v149, v149, v152
	v_log_f32_e32 v149, v149
	s_nop 0
	v_mul_f32_e32 v152, 0x3f317217, v149
	v_fma_f32 v152, v149, s97, -v152
	v_fmac_f32_e32 v152, 0x3377d1cf, v149
	v_fmac_f32_e32 v152, 0x3f317217, v149
	v_cmp_lt_f32_e64 s[0:1], |v149|, s2
	s_nop 1
	v_cndmask_b32_e64 v149, v149, v152, s[0:1]
	v_cndmask_b32_e32 v152, 0, v213, vcc
	v_sub_f32_e32 v149, v149, v152
	v_mul_f32_e32 v152, 0xbfb8aa3b, v50
	v_exp_f32_e32 v152, v152
	s_nop 0
	v_add_f32_e32 v152, 1.0, v152
	v_rcp_f32_e32 v152, v152
	s_nop 0
	v_fma_f32 v152, v152, v154, v134
	v_cmp_gt_f32_e32 vcc, s33, v152
	s_nop 1
	v_cndmask_b32_e64 v153, 0, 32, vcc
	v_ldexp_f32 v152, v152, v153
	v_log_f32_e32 v152, v152
	s_nop 0
	v_mul_f32_e32 v153, 0x3f317217, v152
	v_fma_f32 v153, v152, s97, -v153
	v_fmac_f32_e32 v153, 0x3377d1cf, v152
	v_fmac_f32_e32 v153, 0x3f317217, v152
	v_cmp_lt_f32_e64 s[0:1], |v152|, s2
	s_nop 1
	v_cndmask_b32_e64 v152, v152, v153, s[0:1]
	v_cndmask_b32_e32 v153, 0, v213, vcc
	v_sub_f32_e32 v152, v152, v153
	v_mul_f32_e32 v153, 0xbfb8aa3b, v51
	v_exp_f32_e32 v153, v153
	s_nop 0
	v_add_f32_e32 v153, 1.0, v153
	v_rcp_f32_e32 v153, v153
	s_nop 0
	v_fma_f32 v153, v153, v155, v135
	v_cmp_gt_f32_e32 vcc, s33, v153
	s_nop 1
	v_cndmask_b32_e64 v160, 0, 32, vcc
	v_ldexp_f32 v153, v153, v160
	v_log_f32_e32 v153, v153
	s_nop 0
	v_mul_f32_e32 v160, 0x3f317217, v153
	v_fma_f32 v160, v153, s97, -v160
	v_fmac_f32_e32 v160, 0x3377d1cf, v153
	v_fmac_f32_e32 v160, 0x3f317217, v153
	v_cmp_lt_f32_e64 s[0:1], |v153|, s2
	s_nop 1
	v_cndmask_b32_e64 v153, v153, v160, s[0:1]
	v_cndmask_b32_e32 v160, 0, v213, vcc
	v_sub_f32_e32 v153, v153, v160
	v_mul_f32_e32 v160, 0xbfb8aa3b, v40
	v_exp_f32_e32 v160, v160
	s_nop 0
	v_add_f32_e32 v160, 1.0, v160
	v_rcp_f32_e32 v160, v160
	s_nop 0
	v_fma_f32 v160, v160, v156, v128
	v_cmp_gt_f32_e32 vcc, s33, v160
	s_nop 1
	v_cndmask_b32_e64 v161, 0, 32, vcc
	v_ldexp_f32 v160, v160, v161
	v_log_f32_e32 v160, v160
	s_nop 0
	v_mul_f32_e32 v161, 0x3f317217, v160
	v_fma_f32 v161, v160, s97, -v161
	v_fmac_f32_e32 v161, 0x3377d1cf, v160
	v_fmac_f32_e32 v161, 0x3f317217, v160
	v_cmp_lt_f32_e64 s[0:1], |v160|, s2
	s_nop 1
	v_cndmask_b32_e64 v160, v160, v161, s[0:1]
	v_cndmask_b32_e32 v161, 0, v213, vcc
	v_sub_f32_e32 v162, v160, v161
	v_mul_f32_e32 v160, 0xbfb8aa3b, v41
	v_exp_f32_e32 v160, v160
	s_nop 0
	v_add_f32_e32 v160, 1.0, v160
	v_rcp_f32_e32 v160, v160
	s_nop 0
	v_fma_f32 v160, v160, v157, v129
	v_cmp_gt_f32_e32 vcc, s33, v160
	s_nop 1
	v_cndmask_b32_e64 v161, 0, 32, vcc
	v_ldexp_f32 v160, v160, v161
	v_log_f32_e32 v160, v160
	s_nop 0
	v_mul_f32_e32 v161, 0x3f317217, v160
	v_fma_f32 v161, v160, s97, -v161
	v_fmac_f32_e32 v161, 0x3377d1cf, v160
	v_fmac_f32_e32 v161, 0x3f317217, v160
	v_cmp_lt_f32_e64 s[0:1], |v160|, s2
	s_nop 1
	v_cndmask_b32_e64 v160, v160, v161, s[0:1]
	v_cndmask_b32_e32 v161, 0, v213, vcc
	v_sub_f32_e32 v163, v160, v161
	v_mul_f32_e32 v160, 0xbfb8aa3b, v42
	v_exp_f32_e32 v160, v160
	v_cvt_pk_bf16_f32 v162, v162, v163
	v_add_f32_e32 v160, 1.0, v160
	v_rcp_f32_e32 v160, v160
	s_nop 0
	v_fma_f32 v160, v160, v159, v130
	v_cmp_gt_f32_e32 vcc, s33, v160
	s_nop 1
	v_cndmask_b32_e64 v161, 0, 32, vcc
	v_ldexp_f32 v160, v160, v161
	v_log_f32_e32 v160, v160
	s_nop 0
	v_mul_f32_e32 v161, 0x3f317217, v160
	v_fma_f32 v161, v160, s97, -v161
	v_fmac_f32_e32 v161, 0x3377d1cf, v160
	v_fmac_f32_e32 v161, 0x3f317217, v160
	v_cmp_lt_f32_e64 s[0:1], |v160|, s2
	s_nop 1
	v_cndmask_b32_e64 v160, v160, v161, s[0:1]
	v_cndmask_b32_e32 v161, 0, v213, vcc
	v_sub_f32_e32 v164, v160, v161
	v_mul_f32_e32 v160, 0xbfb8aa3b, v43
	v_exp_f32_e32 v160, v160
	s_nop 0
	v_add_f32_e32 v160, 1.0, v160
	v_rcp_f32_e32 v160, v160
	s_nop 0
	v_fma_f32 v160, v160, v158, v131
	v_cmp_gt_f32_e32 vcc, s33, v160
	s_nop 1
	v_cndmask_b32_e64 v161, 0, 32, vcc
	v_ldexp_f32 v160, v160, v161
	v_log_f32_e32 v160, v160
	s_nop 0
	v_mul_f32_e32 v161, 0x3f317217, v160
	v_fma_f32 v161, v160, s97, -v161
	v_fmac_f32_e32 v161, 0x3377d1cf, v160
	v_fmac_f32_e32 v161, 0x3f317217, v160
	v_cmp_lt_f32_e64 s[0:1], |v160|, s2
	s_nop 1
	v_cndmask_b32_e64 v160, v160, v161, s[0:1]
	v_cndmask_b32_e32 v161, 0, v213, vcc
	s_mov_b64 s[0:1], 0x48000
	v_sub_f32_e32 v165, v160, v161
	v_cvt_pk_bf16_f32 v160, v148, v149
	v_lshl_add_u64 v[148:149], v[138:139], 0, s[0:1]
	v_cvt_pk_bf16_f32 v161, v152, v153
	v_cvt_pk_bf16_f32 v163, v164, v165
	v_lshl_add_u64 v[152:153], v[136:137], 0, v[148:149]
	global_store_dwordx4 v[152:153], v[160:163], off
	v_mul_f32_e32 v152, 0xbfb8aa3b, v32
	v_exp_f32_e32 v152, v152
	s_nop 0
	v_add_f32_e32 v152, 1.0, v152
	v_rcp_f32_e32 v152, v152
	s_nop 0
	v_fma_f32 v152, v152, v150, v132
	v_cmp_gt_f32_e32 vcc, s33, v152
	s_nop 1
	v_cndmask_b32_e64 v153, 0, 32, vcc
	v_ldexp_f32 v152, v152, v153
	v_log_f32_e32 v152, v152
	s_nop 0
	v_mul_f32_e32 v153, 0x3f317217, v152
	v_fma_f32 v153, v152, s97, -v153
	v_fmac_f32_e32 v153, 0x3377d1cf, v152
	v_fmac_f32_e32 v153, 0x3f317217, v152
	v_cmp_lt_f32_e64 s[0:1], |v152|, s2
	s_nop 1
	v_cndmask_b32_e64 v152, v152, v153, s[0:1]
	v_cndmask_b32_e32 v153, 0, v213, vcc
	v_sub_f32_e32 v152, v152, v153
	v_mul_f32_e32 v153, 0xbfb8aa3b, v33
	v_exp_f32_e32 v153, v153
	s_nop 0
	v_add_f32_e32 v153, 1.0, v153
	v_rcp_f32_e32 v153, v153
	s_nop 0
	v_fma_f32 v153, v153, v151, v133
	v_cmp_gt_f32_e32 vcc, s33, v153
	s_nop 1
	v_cndmask_b32_e64 v160, 0, 32, vcc
	v_ldexp_f32 v153, v153, v160
	v_log_f32_e32 v153, v153
	s_nop 0
	v_mul_f32_e32 v160, 0x3f317217, v153
	v_fma_f32 v160, v153, s97, -v160
	v_fmac_f32_e32 v160, 0x3377d1cf, v153
	v_fmac_f32_e32 v160, 0x3f317217, v153
	v_cmp_lt_f32_e64 s[0:1], |v153|, s2
	s_nop 1
	v_cndmask_b32_e64 v153, v153, v160, s[0:1]
	v_cndmask_b32_e32 v160, 0, v213, vcc
	v_sub_f32_e32 v153, v153, v160
	v_mul_f32_e32 v160, 0xbfb8aa3b, v34
	v_exp_f32_e32 v160, v160
	s_nop 0
	v_add_f32_e32 v160, 1.0, v160
	v_rcp_f32_e32 v160, v160
	s_nop 0
	v_fma_f32 v160, v160, v154, v134
	v_cmp_gt_f32_e32 vcc, s33, v160
	s_nop 1
	v_cndmask_b32_e64 v161, 0, 32, vcc
	v_ldexp_f32 v160, v160, v161
	v_log_f32_e32 v160, v160
	s_nop 0
	v_mul_f32_e32 v161, 0x3f317217, v160
	v_fma_f32 v161, v160, s97, -v161
	v_fmac_f32_e32 v161, 0x3377d1cf, v160
	v_fmac_f32_e32 v161, 0x3f317217, v160
	v_cmp_lt_f32_e64 s[0:1], |v160|, s2
	s_nop 1
	v_cndmask_b32_e64 v160, v160, v161, s[0:1]
	v_cndmask_b32_e32 v161, 0, v213, vcc
	v_sub_f32_e32 v161, v160, v161
	v_mul_f32_e32 v160, 0xbfb8aa3b, v35
	v_exp_f32_e32 v160, v160
	s_nop 0
	v_add_f32_e32 v160, 1.0, v160
	v_rcp_f32_e32 v160, v160
	s_nop 0
	v_fma_f32 v160, v160, v155, v135
	v_cmp_gt_f32_e32 vcc, s33, v160
	s_nop 1
	v_cndmask_b32_e64 v162, 0, 32, vcc
	v_ldexp_f32 v160, v160, v162
	v_log_f32_e32 v160, v160
	s_nop 0
	v_mul_f32_e32 v162, 0x3f317217, v160
	v_fma_f32 v162, v160, s97, -v162
	v_fmac_f32_e32 v162, 0x3377d1cf, v160
	v_fmac_f32_e32 v162, 0x3f317217, v160
	v_cmp_lt_f32_e64 s[0:1], |v160|, s2
	s_nop 1
	v_cndmask_b32_e64 v160, v160, v162, s[0:1]
	v_cndmask_b32_e32 v162, 0, v213, vcc
	v_sub_f32_e32 v162, v160, v162
	v_mul_f32_e32 v160, 0xbfb8aa3b, v24
	v_exp_f32_e32 v160, v160
	v_cvt_pk_bf16_f32 v161, v161, v162
	v_add_f32_e32 v160, 1.0, v160
	v_rcp_f32_e32 v160, v160
	s_nop 0
	v_fma_f32 v160, v160, v156, v128
	v_cmp_gt_f32_e32 vcc, s33, v160
	s_nop 1
	v_cndmask_b32_e64 v163, 0, 32, vcc
	v_ldexp_f32 v160, v160, v163
	v_log_f32_e32 v160, v160
	s_nop 0
	v_mul_f32_e32 v163, 0x3f317217, v160
	v_fma_f32 v163, v160, s97, -v163
	v_fmac_f32_e32 v163, 0x3377d1cf, v160
	v_fmac_f32_e32 v163, 0x3f317217, v160
	v_cmp_lt_f32_e64 s[0:1], |v160|, s2
	s_nop 1
	v_cndmask_b32_e64 v160, v160, v163, s[0:1]
	v_cndmask_b32_e32 v163, 0, v213, vcc
	v_sub_f32_e32 v163, v160, v163
	v_mul_f32_e32 v160, 0xbfb8aa3b, v25
	v_exp_f32_e32 v160, v160
	s_nop 0
	v_add_f32_e32 v160, 1.0, v160
	v_rcp_f32_e32 v160, v160
	s_nop 0
	v_fma_f32 v160, v160, v157, v129
	v_cmp_gt_f32_e32 vcc, s33, v160
	s_nop 1
	v_cndmask_b32_e64 v164, 0, 32, vcc
	v_ldexp_f32 v160, v160, v164
	v_log_f32_e32 v160, v160
	s_nop 0
	v_mul_f32_e32 v164, 0x3f317217, v160
	v_fma_f32 v164, v160, s97, -v164
	v_fmac_f32_e32 v164, 0x3377d1cf, v160
	v_fmac_f32_e32 v164, 0x3f317217, v160
	v_cmp_lt_f32_e64 s[0:1], |v160|, s2
	s_nop 1
	v_cndmask_b32_e64 v160, v160, v164, s[0:1]
	v_cndmask_b32_e32 v164, 0, v213, vcc
	v_sub_f32_e32 v164, v160, v164
	v_mul_f32_e32 v160, 0xbfb8aa3b, v26
	v_exp_f32_e32 v160, v160
	v_cvt_pk_bf16_f32 v162, v163, v164
	v_add_f32_e32 v160, 1.0, v160
	v_rcp_f32_e32 v160, v160
	s_nop 0
	v_fma_f32 v160, v160, v159, v130
	v_cmp_gt_f32_e32 vcc, s33, v160
	s_nop 1
	v_cndmask_b32_e64 v165, 0, 32, vcc
	v_ldexp_f32 v160, v160, v165
	v_log_f32_e32 v160, v160
	s_nop 0
	v_mul_f32_e32 v165, 0x3f317217, v160
	v_fma_f32 v165, v160, s97, -v165
	v_fmac_f32_e32 v165, 0x3377d1cf, v160
	v_fmac_f32_e32 v165, 0x3f317217, v160
	v_cmp_lt_f32_e64 s[0:1], |v160|, s2
	s_nop 1
	v_cndmask_b32_e64 v160, v160, v165, s[0:1]
	v_cndmask_b32_e32 v165, 0, v213, vcc
	v_sub_f32_e32 v165, v160, v165
	v_mul_f32_e32 v160, 0xbfb8aa3b, v27
	v_exp_f32_e32 v160, v160
	s_nop 0
	v_add_f32_e32 v160, 1.0, v160
	v_rcp_f32_e32 v160, v160
	s_nop 0
	v_fma_f32 v160, v160, v158, v131
	v_cmp_gt_f32_e32 vcc, s33, v160
	s_nop 1
	v_cndmask_b32_e64 v166, 0, 32, vcc
	v_ldexp_f32 v160, v160, v166
	v_log_f32_e32 v160, v160
	s_nop 0
	v_mul_f32_e32 v166, 0x3f317217, v160
	v_fma_f32 v166, v160, s97, -v166
	v_fmac_f32_e32 v166, 0x3377d1cf, v160
	v_fmac_f32_e32 v166, 0x3f317217, v160
	v_cmp_lt_f32_e64 s[0:1], |v160|, s2
	s_nop 1
	v_cndmask_b32_e64 v160, v160, v166, s[0:1]
	v_cndmask_b32_e32 v166, 0, v213, vcc
	s_mov_b64 s[0:1], 0x50000
	v_sub_f32_e32 v166, v160, v166
	v_cvt_pk_bf16_f32 v160, v152, v153
	v_lshl_add_u64 v[152:153], v[138:139], 0, s[0:1]
	v_cvt_pk_bf16_f32 v163, v165, v166
	v_lshl_add_u64 v[164:165], v[136:137], 0, v[152:153]
	global_store_dwordx4 v[164:165], v[160:163], off
	s_nop 1
	v_mul_f32_e32 v160, 0xbfb8aa3b, v16
	v_exp_f32_e32 v160, v160
	s_nop 0
	v_add_f32_e32 v160, 1.0, v160
	v_rcp_f32_e32 v160, v160
	s_nop 0
	v_fma_f32 v132, v160, v150, v132
	v_cmp_gt_f32_e32 vcc, s33, v132
	v_or_b32_e32 v160, 0x80, v223
	s_nop 0
	v_cndmask_b32_e64 v150, 0, 32, vcc
	v_ldexp_f32 v132, v132, v150
	v_log_f32_e32 v132, v132
	s_nop 0
	v_mul_f32_e32 v150, 0x3f317217, v132
	v_fma_f32 v150, v132, s97, -v150
	v_fmac_f32_e32 v150, 0x3377d1cf, v132
	v_fmac_f32_e32 v150, 0x3f317217, v132
	v_cmp_lt_f32_e64 s[0:1], |v132|, s2
	s_nop 1
	v_cndmask_b32_e64 v132, v132, v150, s[0:1]
	v_cndmask_b32_e32 v150, 0, v213, vcc
	v_sub_f32_e32 v132, v132, v150
	v_mul_f32_e32 v150, 0xbfb8aa3b, v17
	v_exp_f32_e32 v150, v150
	s_nop 0
	v_add_f32_e32 v150, 1.0, v150
	v_rcp_f32_e32 v150, v150
	s_nop 0
	v_fma_f32 v133, v150, v151, v133
	v_cmp_gt_f32_e32 vcc, s33, v133
	s_nop 1
	v_cndmask_b32_e64 v150, 0, 32, vcc
	v_ldexp_f32 v133, v133, v150
	v_log_f32_e32 v133, v133
	s_nop 0
	v_mul_f32_e32 v150, 0x3f317217, v133
	v_fma_f32 v150, v133, s97, -v150
	v_fmac_f32_e32 v150, 0x3377d1cf, v133
	v_fmac_f32_e32 v150, 0x3f317217, v133
	v_cmp_lt_f32_e64 s[0:1], |v133|, s2
	s_nop 1
	v_cndmask_b32_e64 v133, v133, v150, s[0:1]
	v_cndmask_b32_e32 v150, 0, v213, vcc
	v_sub_f32_e32 v133, v133, v150
	v_mul_f32_e32 v150, 0xbfb8aa3b, v18
	v_exp_f32_e32 v150, v150
	s_nop 0
	v_add_f32_e32 v150, 1.0, v150
	v_rcp_f32_e32 v150, v150
	s_nop 0
	v_fma_f32 v134, v150, v154, v134
	v_cmp_gt_f32_e32 vcc, s33, v134
	s_nop 1
	v_cndmask_b32_e64 v150, 0, 32, vcc
	v_ldexp_f32 v134, v134, v150
	v_log_f32_e32 v134, v134
	s_nop 0
	v_mul_f32_e32 v150, 0x3f317217, v134
	v_fma_f32 v150, v134, s97, -v150
	v_fmac_f32_e32 v150, 0x3377d1cf, v134
	v_fmac_f32_e32 v150, 0x3f317217, v134
	v_cmp_lt_f32_e64 s[0:1], |v134|, s2
	s_nop 1
	v_cndmask_b32_e64 v134, v134, v150, s[0:1]
	v_cndmask_b32_e32 v150, 0, v213, vcc
	v_sub_f32_e32 v134, v134, v150
	v_mul_f32_e32 v150, 0xbfb8aa3b, v19
	v_exp_f32_e32 v150, v150
	s_nop 0
	v_add_f32_e32 v150, 1.0, v150
	v_rcp_f32_e32 v150, v150
	s_nop 0
	v_fmac_f32_e32 v135, v150, v155
	v_cmp_gt_f32_e32 vcc, s33, v135
	s_nop 1
	v_cndmask_b32_e64 v150, 0, 32, vcc
	v_ldexp_f32 v135, v135, v150
	v_log_f32_e32 v135, v135
	s_nop 0
	v_mul_f32_e32 v150, 0x3f317217, v135
	v_fma_f32 v150, v135, s97, -v150
	v_fmac_f32_e32 v150, 0x3377d1cf, v135
	v_fmac_f32_e32 v150, 0x3f317217, v135
	v_cmp_lt_f32_e64 s[0:1], |v135|, s2
	s_nop 1
	v_cndmask_b32_e64 v135, v135, v150, s[0:1]
	v_cndmask_b32_e32 v150, 0, v213, vcc
	v_sub_f32_e32 v135, v135, v150
	v_mul_f32_e32 v150, 0xbfb8aa3b, v8
	v_exp_f32_e32 v150, v150
	s_nop 0
	v_add_f32_e32 v150, 1.0, v150
	v_rcp_f32_e32 v150, v150
	s_nop 0
	v_fma_f32 v128, v150, v156, v128
	v_cmp_gt_f32_e32 vcc, s33, v128
	s_nop 1
	v_cndmask_b32_e64 v150, 0, 32, vcc
	v_ldexp_f32 v128, v128, v150
	v_log_f32_e32 v128, v128
	s_nop 0
	v_mul_f32_e32 v150, 0x3f317217, v128
	v_fma_f32 v150, v128, s97, -v150
	v_fmac_f32_e32 v150, 0x3377d1cf, v128
	v_fmac_f32_e32 v150, 0x3f317217, v128
	v_cmp_lt_f32_e64 s[0:1], |v128|, s2
	s_nop 1
	v_cndmask_b32_e64 v128, v128, v150, s[0:1]
	v_cndmask_b32_e32 v150, 0, v213, vcc
	v_sub_f32_e32 v150, v128, v150
	v_mul_f32_e32 v128, 0xbfb8aa3b, v9
	v_exp_f32_e32 v128, v128
	s_nop 0
	v_add_f32_e32 v128, 1.0, v128
	v_rcp_f32_e32 v128, v128
	s_nop 0
	v_fma_f32 v128, v128, v157, v129
	v_cmp_gt_f32_e32 vcc, s33, v128
	s_nop 1
	v_cndmask_b32_e64 v129, 0, 32, vcc
	v_ldexp_f32 v128, v128, v129
	v_log_f32_e32 v128, v128
	s_nop 0
	v_mul_f32_e32 v129, 0x3f317217, v128
	v_fma_f32 v129, v128, s97, -v129
	v_fmac_f32_e32 v129, 0x3377d1cf, v128
	v_fmac_f32_e32 v129, 0x3f317217, v128
	v_cmp_lt_f32_e64 s[0:1], |v128|, s2
	s_nop 1
	v_cndmask_b32_e64 v128, v128, v129, s[0:1]
	v_cndmask_b32_e32 v129, 0, v213, vcc
	v_sub_f32_e32 v151, v128, v129
	v_mul_f32_e32 v128, 0xbfb8aa3b, v10
	v_exp_f32_e32 v128, v128
	s_nop 0
	v_add_f32_e32 v128, 1.0, v128
	v_rcp_f32_e32 v128, v128
	s_nop 0
	v_fma_f32 v128, v128, v159, v130
	v_cmp_gt_f32_e32 vcc, s33, v128
	v_cvt_pk_bf16_f32 v130, v150, v151
	s_nop 0
	v_cndmask_b32_e64 v129, 0, 32, vcc
	v_ldexp_f32 v128, v128, v129
	v_log_f32_e32 v128, v128
	s_nop 0
	v_mul_f32_e32 v129, 0x3f317217, v128
	v_fma_f32 v129, v128, s97, -v129
	v_fmac_f32_e32 v129, 0x3377d1cf, v128
	v_fmac_f32_e32 v129, 0x3f317217, v128
	v_cmp_lt_f32_e64 s[0:1], |v128|, s2
	s_nop 1
	v_cndmask_b32_e64 v128, v128, v129, s[0:1]
	v_cndmask_b32_e32 v129, 0, v213, vcc
	v_sub_f32_e32 v154, v128, v129
	v_mul_f32_e32 v128, 0xbfb8aa3b, v11
	v_exp_f32_e32 v128, v128
	s_nop 0
	v_add_f32_e32 v128, 1.0, v128
	v_rcp_f32_e32 v128, v128
	s_nop 0
	v_fmac_f32_e32 v131, v128, v158
	v_cmp_gt_f32_e32 vcc, s33, v131
	s_nop 1
	v_cndmask_b32_e64 v128, 0, 32, vcc
	v_ldexp_f32 v128, v131, v128
	v_log_f32_e32 v128, v128
	s_nop 0
	v_mul_f32_e32 v129, 0x3f317217, v128
	v_fma_f32 v129, v128, s97, -v129
	v_fmac_f32_e32 v129, 0x3377d1cf, v128
	v_fmac_f32_e32 v129, 0x3f317217, v128
	v_cmp_lt_f32_e64 s[0:1], |v128|, s2
	s_nop 1
	v_cndmask_b32_e64 v128, v128, v129, s[0:1]
	v_cndmask_b32_e32 v129, 0, v213, vcc
	s_mov_b64 s[0:1], 0x58000
	v_sub_f32_e32 v131, v128, v129
	v_lshl_add_u64 v[150:151], v[138:139], 0, s[0:1]
	v_cvt_pk_bf16_f32 v128, v132, v133
	v_cvt_pk_bf16_f32 v129, v134, v135
	v_cvt_pk_bf16_f32 v131, v154, v131
	v_lshl_add_u64 v[132:133], v[136:137], 0, v[150:151]
	global_store_dwordx4 v[132:133], v[128:131], off
	v_lshlrev_b32_e32 v132, 2, v160
	global_load_dwordx4 v[128:131], v132, s[42:43] offset:16
	s_nop 0
	global_load_dwordx4 v[132:135], v132, s[42:43]
	v_mul_f32_e32 v136, 0xbfb8aa3b, v116
	v_exp_f32_e32 v136, v136
	v_lshl_add_u64 v[138:139], s[8:9], 0, v[138:139]
	v_add_f32_e32 v136, 1.0, v136
	v_rcp_f32_e32 v136, v136
	s_waitcnt vmcnt(1)
	v_sub_f32_e32 v158, 1.0, v128
	s_waitcnt vmcnt(0)
	v_sub_f32_e32 v159, 1.0, v132
	v_fma_f32 v136, v136, v159, v132
	v_cmp_gt_f32_e32 vcc, s33, v136
	v_sub_f32_e32 v157, 1.0, v133
	v_sub_f32_e32 v156, 1.0, v134
	v_cndmask_b32_e64 v137, 0, 32, vcc
	v_ldexp_f32 v136, v136, v137
	v_log_f32_e32 v136, v136
	v_sub_f32_e32 v154, 1.0, v135
	v_mul_f32_e32 v137, 0x3f317217, v136
	v_fma_f32 v137, v136, s97, -v137
	v_fmac_f32_e32 v137, 0x3377d1cf, v136
	v_fmac_f32_e32 v137, 0x3f317217, v136
	v_cmp_lt_f32_e64 s[0:1], |v136|, s2
	s_nop 1
	v_cndmask_b32_e64 v136, v136, v137, s[0:1]
	v_cndmask_b32_e32 v137, 0, v213, vcc
	v_sub_f32_e32 v161, v136, v137
	v_mul_f32_e32 v136, 0xbfb8aa3b, v117
	v_exp_f32_e32 v136, v136
	s_nop 0
	v_add_f32_e32 v136, 1.0, v136
	v_rcp_f32_e32 v136, v136
	s_nop 0
	v_fma_f32 v136, v136, v157, v133
	v_cmp_gt_f32_e32 vcc, s33, v136
	s_nop 1
	v_cndmask_b32_e64 v137, 0, 32, vcc
	v_ldexp_f32 v136, v136, v137
	v_log_f32_e32 v136, v136
	s_nop 0
	v_mul_f32_e32 v137, 0x3f317217, v136
	v_fma_f32 v137, v136, s97, -v137
	v_fmac_f32_e32 v137, 0x3377d1cf, v136
	v_fmac_f32_e32 v137, 0x3f317217, v136
	v_cmp_lt_f32_e64 s[0:1], |v136|, s2
	s_nop 1
	v_cndmask_b32_e64 v136, v136, v137, s[0:1]
	v_cndmask_b32_e32 v137, 0, v213, vcc
	v_sub_f32_e32 v162, v136, v137
	v_mul_f32_e32 v136, 0xbfb8aa3b, v118
	v_exp_f32_e32 v136, v136
	v_cvt_pk_bf16_f32 v162, v161, v162
	v_add_f32_e32 v136, 1.0, v136
	v_rcp_f32_e32 v136, v136
	s_nop 0
	v_fma_f32 v136, v136, v156, v134
	v_cmp_gt_f32_e32 vcc, s33, v136
	s_nop 1
	v_cndmask_b32_e64 v137, 0, 32, vcc
	v_ldexp_f32 v136, v136, v137
	v_log_f32_e32 v136, v136
	s_nop 0
	v_mul_f32_e32 v137, 0x3f317217, v136
	v_fma_f32 v137, v136, s97, -v137
	v_fmac_f32_e32 v137, 0x3377d1cf, v136
	v_fmac_f32_e32 v137, 0x3f317217, v136
	v_cmp_lt_f32_e64 s[0:1], |v136|, s2
	s_nop 1
	v_cndmask_b32_e64 v136, v136, v137, s[0:1]
	v_cndmask_b32_e32 v137, 0, v213, vcc
	v_sub_f32_e32 v163, v136, v137
	v_mul_f32_e32 v136, 0xbfb8aa3b, v119
	v_exp_f32_e32 v136, v136
	s_nop 0
	v_add_f32_e32 v136, 1.0, v136
	v_rcp_f32_e32 v136, v136
	s_nop 0
	v_fma_f32 v136, v136, v154, v135
	v_cmp_gt_f32_e32 vcc, s33, v136
	s_nop 1
	v_cndmask_b32_e64 v137, 0, 32, vcc
	v_ldexp_f32 v136, v136, v137
	v_log_f32_e32 v136, v136
	s_nop 0
	v_mul_f32_e32 v137, 0x3f317217, v136
	v_fma_f32 v137, v136, s97, -v137
	v_fmac_f32_e32 v137, 0x3377d1cf, v136
	v_fmac_f32_e32 v137, 0x3f317217, v136
	v_cmp_lt_f32_e64 s[0:1], |v136|, s2
	s_nop 1
	v_cndmask_b32_e64 v136, v136, v137, s[0:1]
	v_cndmask_b32_e32 v137, 0, v213, vcc
	v_sub_f32_e32 v164, v136, v137
	v_mul_f32_e32 v136, 0xbfb8aa3b, v108
	v_exp_f32_e32 v136, v136
	v_cvt_pk_bf16_f32 v163, v163, v164
	v_add_f32_e32 v136, 1.0, v136
	v_rcp_f32_e32 v136, v136
	s_nop 0
	v_fma_f32 v136, v136, v158, v128
	v_cmp_gt_f32_e32 vcc, s33, v136
	s_nop 1
	v_cndmask_b32_e64 v137, 0, 32, vcc
	v_ldexp_f32 v136, v136, v137
	v_log_f32_e32 v136, v136
	s_nop 0
	v_mul_f32_e32 v137, 0x3f317217, v136
	v_fma_f32 v137, v136, s97, -v137
	v_fmac_f32_e32 v137, 0x3377d1cf, v136
	v_fmac_f32_e32 v137, 0x3f317217, v136
	v_cmp_lt_f32_e64 s[0:1], |v136|, s2
	s_nop 1
	v_cndmask_b32_e64 v136, v136, v137, s[0:1]
	v_cndmask_b32_e32 v137, 0, v213, vcc
	v_sub_f32_e32 v165, v136, v137
	v_mul_f32_e32 v136, 0xbfb8aa3b, v109
	v_exp_f32_e32 v136, v136
	s_nop 0
	v_add_f32_e32 v136, 1.0, v136
	v_rcp_f32_e32 v137, v136
	v_sub_f32_e32 v136, 1.0, v129
	v_fma_f32 v137, v137, v136, v129
	v_cmp_gt_f32_e32 vcc, s33, v137
	s_nop 1
	v_cndmask_b32_e64 v155, 0, 32, vcc
	v_ldexp_f32 v137, v137, v155
	v_log_f32_e32 v137, v137
	s_nop 0
	v_mul_f32_e32 v155, 0x3f317217, v137
	v_fma_f32 v155, v137, s97, -v155
	v_fmac_f32_e32 v155, 0x3377d1cf, v137
	v_fmac_f32_e32 v155, 0x3f317217, v137
	v_cmp_lt_f32_e64 s[0:1], |v137|, s2
	s_nop 1
	v_cndmask_b32_e64 v137, v137, v155, s[0:1]
	v_cndmask_b32_e32 v155, 0, v213, vcc
	v_sub_f32_e32 v166, v137, v155
	v_mul_f32_e32 v137, 0xbfb8aa3b, v110
	v_exp_f32_e32 v137, v137
	v_sub_f32_e32 v155, 1.0, v130
	v_cvt_pk_bf16_f32 v164, v165, v166
	v_add_f32_e32 v137, 1.0, v137
	v_rcp_f32_e32 v137, v137
	s_nop 0
	v_fma_f32 v137, v137, v155, v130
	v_cmp_gt_f32_e32 vcc, s33, v137
	s_nop 1
	v_cndmask_b32_e64 v167, 0, 32, vcc
	v_ldexp_f32 v137, v137, v167
	v_log_f32_e32 v137, v137
	s_nop 0
	v_mul_f32_e32 v167, 0x3f317217, v137
	v_fma_f32 v167, v137, s97, -v167
	v_fmac_f32_e32 v167, 0x3377d1cf, v137
	v_fmac_f32_e32 v167, 0x3f317217, v137
	v_cmp_lt_f32_e64 s[0:1], |v137|, s2
	s_nop 1
	v_cndmask_b32_e64 v137, v137, v167, s[0:1]
	v_cndmask_b32_e32 v167, 0, v213, vcc
	v_sub_f32_e32 v167, v137, v167
	v_mul_f32_e32 v137, 0xbfb8aa3b, v111
	v_exp_f32_e32 v137, v137
	s_nop 0
	v_add_f32_e32 v137, 1.0, v137
	v_rcp_f32_e32 v172, v137
	v_sub_f32_e32 v137, 1.0, v131
	v_fma_f32 v172, v172, v137, v131
	v_cmp_gt_f32_e32 vcc, s33, v172
	s_nop 1
	v_cndmask_b32_e64 v187, 0, 32, vcc
	v_ldexp_f32 v172, v172, v187
	v_log_f32_e32 v172, v172
	s_nop 0
	v_mul_f32_e32 v187, 0x3f317217, v172
	v_fma_f32 v187, v172, s97, -v187
	v_fmac_f32_e32 v187, 0x3377d1cf, v172
	v_fmac_f32_e32 v187, 0x3f317217, v172
	v_cmp_lt_f32_e64 s[0:1], |v172|, s2
	s_nop 1
	v_cndmask_b32_e64 v172, v172, v187, s[0:1]
	v_cndmask_b32_e32 v187, 0, v213, vcc
	v_sub_f32_e32 v172, v172, v187
	v_cvt_pk_bf16_f32 v165, v167, v172
	v_lshlrev_b32_e32 v172, 1, v160
	v_lshl_add_u64 v[138:139], v[138:139], 0, v[172:173]
	global_store_dwordx4 v[138:139], v[162:165], off
	v_mul_f32_e32 v138, 0xbfb8aa3b, v100
	v_exp_f32_e32 v138, v138
	v_lshl_add_u64 v[142:143], v[142:143], 0, v[172:173]
	v_add_f32_e32 v138, 1.0, v138
	v_rcp_f32_e32 v138, v138
	s_nop 0
	v_fma_f32 v138, v138, v159, v132
	v_cmp_gt_f32_e32 vcc, s33, v138
	s_nop 1
	v_cndmask_b32_e64 v139, 0, 32, vcc
	v_ldexp_f32 v138, v138, v139
	v_log_f32_e32 v138, v138
	s_nop 0
	v_mul_f32_e32 v139, 0x3f317217, v138
	v_fma_f32 v139, v138, s97, -v139
	v_fmac_f32_e32 v139, 0x3377d1cf, v138
	v_fmac_f32_e32 v139, 0x3f317217, v138
	v_cmp_lt_f32_e64 s[0:1], |v138|, s2
	s_nop 1
	v_cndmask_b32_e64 v138, v138, v139, s[0:1]
	v_cndmask_b32_e32 v139, 0, v213, vcc
	v_sub_f32_e32 v138, v138, v139
	v_mul_f32_e32 v139, 0xbfb8aa3b, v101
	v_exp_f32_e32 v139, v139
	s_nop 0
	v_add_f32_e32 v139, 1.0, v139
	v_rcp_f32_e32 v139, v139
	s_nop 0
	v_fma_f32 v139, v139, v157, v133
	v_cmp_gt_f32_e32 vcc, s33, v139
	s_nop 1
	v_cndmask_b32_e64 v160, 0, 32, vcc
	v_ldexp_f32 v139, v139, v160
	v_log_f32_e32 v139, v139
	s_nop 0
	v_mul_f32_e32 v160, 0x3f317217, v139
	v_fma_f32 v160, v139, s97, -v160
	v_fmac_f32_e32 v160, 0x3377d1cf, v139
	v_fmac_f32_e32 v160, 0x3f317217, v139
	v_cmp_lt_f32_e64 s[0:1], |v139|, s2
	s_nop 1
	v_cndmask_b32_e64 v139, v139, v160, s[0:1]
	v_cndmask_b32_e32 v160, 0, v213, vcc
	v_sub_f32_e32 v139, v139, v160
	v_mul_f32_e32 v160, 0xbfb8aa3b, v102
	v_exp_f32_e32 v160, v160
	s_nop 0
	v_add_f32_e32 v160, 1.0, v160
	v_rcp_f32_e32 v160, v160
	s_nop 0
	v_fma_f32 v160, v160, v156, v134
	v_cmp_gt_f32_e32 vcc, s33, v160
	s_nop 1
	v_cndmask_b32_e64 v161, 0, 32, vcc
	v_ldexp_f32 v160, v160, v161
	v_log_f32_e32 v160, v160
	s_nop 0
	v_mul_f32_e32 v161, 0x3f317217, v160
	v_fma_f32 v161, v160, s97, -v161
	v_fmac_f32_e32 v161, 0x3377d1cf, v160
	v_fmac_f32_e32 v161, 0x3f317217, v160
	v_cmp_lt_f32_e64 s[0:1], |v160|, s2
	s_nop 1
	v_cndmask_b32_e64 v160, v160, v161, s[0:1]
	v_cndmask_b32_e32 v161, 0, v213, vcc
	v_sub_f32_e32 v161, v160, v161
	v_mul_f32_e32 v160, 0xbfb8aa3b, v103
	v_exp_f32_e32 v160, v160
	s_nop 0
	v_add_f32_e32 v160, 1.0, v160
	v_rcp_f32_e32 v160, v160
	s_nop 0
	v_fma_f32 v160, v160, v154, v135
	v_cmp_gt_f32_e32 vcc, s33, v160
	s_nop 1
	v_cndmask_b32_e64 v162, 0, 32, vcc
	v_ldexp_f32 v160, v160, v162
	v_log_f32_e32 v160, v160
	s_nop 0
	v_mul_f32_e32 v162, 0x3f317217, v160
	v_fma_f32 v162, v160, s97, -v162
	v_fmac_f32_e32 v162, 0x3377d1cf, v160
	v_fmac_f32_e32 v162, 0x3f317217, v160
	v_cmp_lt_f32_e64 s[0:1], |v160|, s2
	s_nop 1
	v_cndmask_b32_e64 v160, v160, v162, s[0:1]
	v_cndmask_b32_e32 v162, 0, v213, vcc
	v_sub_f32_e32 v162, v160, v162
	v_mul_f32_e32 v160, 0xbfb8aa3b, v92
	v_exp_f32_e32 v160, v160
	v_cvt_pk_bf16_f32 v161, v161, v162
	v_add_f32_e32 v160, 1.0, v160
	v_rcp_f32_e32 v160, v160
	s_nop 0
	v_fma_f32 v160, v160, v158, v128
	v_cmp_gt_f32_e32 vcc, s33, v160
	s_nop 1
	v_cndmask_b32_e64 v163, 0, 32, vcc
	v_ldexp_f32 v160, v160, v163
	v_log_f32_e32 v160, v160
	s_nop 0
	v_mul_f32_e32 v163, 0x3f317217, v160
	v_fma_f32 v163, v160, s97, -v163
	v_fmac_f32_e32 v163, 0x3377d1cf, v160
	v_fmac_f32_e32 v163, 0x3f317217, v160
	v_cmp_lt_f32_e64 s[0:1], |v160|, s2
	s_nop 1
	v_cndmask_b32_e64 v160, v160, v163, s[0:1]
	v_cndmask_b32_e32 v163, 0, v213, vcc
	v_sub_f32_e32 v163, v160, v163
	v_mul_f32_e32 v160, 0xbfb8aa3b, v93
	v_exp_f32_e32 v160, v160
	s_nop 0
	v_add_f32_e32 v160, 1.0, v160
	v_rcp_f32_e32 v160, v160
	s_nop 0
	v_fma_f32 v160, v160, v136, v129
	v_cmp_gt_f32_e32 vcc, s33, v160
	s_nop 1
	v_cndmask_b32_e64 v164, 0, 32, vcc
	v_ldexp_f32 v160, v160, v164
	v_log_f32_e32 v160, v160
	s_nop 0
	v_mul_f32_e32 v164, 0x3f317217, v160
	v_fma_f32 v164, v160, s97, -v164
	v_fmac_f32_e32 v164, 0x3377d1cf, v160
	v_fmac_f32_e32 v164, 0x3f317217, v160
	v_cmp_lt_f32_e64 s[0:1], |v160|, s2
	s_nop 1
	v_cndmask_b32_e64 v160, v160, v164, s[0:1]
	v_cndmask_b32_e32 v164, 0, v213, vcc
	v_sub_f32_e32 v164, v160, v164
	v_mul_f32_e32 v160, 0xbfb8aa3b, v94
	v_exp_f32_e32 v160, v160
	v_cvt_pk_bf16_f32 v162, v163, v164
	v_add_f32_e32 v160, 1.0, v160
	v_rcp_f32_e32 v160, v160
	s_nop 0
	v_fma_f32 v160, v160, v155, v130
	v_cmp_gt_f32_e32 vcc, s33, v160
	s_nop 1
	v_cndmask_b32_e64 v165, 0, 32, vcc
	v_ldexp_f32 v160, v160, v165
	v_log_f32_e32 v160, v160
	s_nop 0
	v_mul_f32_e32 v165, 0x3f317217, v160
	v_fma_f32 v165, v160, s97, -v165
	v_fmac_f32_e32 v165, 0x3377d1cf, v160
	v_fmac_f32_e32 v165, 0x3f317217, v160
	v_cmp_lt_f32_e64 s[0:1], |v160|, s2
	s_nop 1
	v_cndmask_b32_e64 v160, v160, v165, s[0:1]
	v_cndmask_b32_e32 v165, 0, v213, vcc
	v_sub_f32_e32 v165, v160, v165
	v_mul_f32_e32 v160, 0xbfb8aa3b, v95
	v_exp_f32_e32 v160, v160
	s_nop 0
	v_add_f32_e32 v160, 1.0, v160
	v_rcp_f32_e32 v160, v160
	s_nop 0
	v_fma_f32 v160, v160, v137, v131
	v_cmp_gt_f32_e32 vcc, s33, v160
	s_nop 1
	v_cndmask_b32_e64 v166, 0, 32, vcc
	v_ldexp_f32 v160, v160, v166
	v_log_f32_e32 v160, v160
	s_nop 0
	v_mul_f32_e32 v166, 0x3f317217, v160
	v_fma_f32 v166, v160, s97, -v166
	v_fmac_f32_e32 v166, 0x3377d1cf, v160
	v_fmac_f32_e32 v166, 0x3f317217, v160
	v_cmp_lt_f32_e64 s[0:1], |v160|, s2
	s_nop 1
	v_cndmask_b32_e64 v160, v160, v166, s[0:1]
	v_cndmask_b32_e32 v166, 0, v213, vcc
	v_sub_f32_e32 v166, v160, v166
	v_cvt_pk_bf16_f32 v160, v138, v139
	v_lshl_add_u64 v[138:139], s[8:9], 0, v[140:141]
	v_cvt_pk_bf16_f32 v163, v165, v166
	v_lshl_add_u64 v[138:139], v[138:139], 0, v[172:173]
	global_store_dwordx4 v[138:139], v[160:163], off
	v_mul_f32_e32 v138, 0xbfb8aa3b, v84
	v_exp_f32_e32 v138, v138
	s_nop 0
	v_add_f32_e32 v138, 1.0, v138
	v_rcp_f32_e32 v138, v138
	s_nop 0
	v_fma_f32 v138, v138, v159, v132
	v_cmp_gt_f32_e32 vcc, s33, v138
	s_nop 1
	v_cndmask_b32_e64 v139, 0, 32, vcc
	v_ldexp_f32 v138, v138, v139
	v_log_f32_e32 v138, v138
	s_nop 0
	v_mul_f32_e32 v139, 0x3f317217, v138
	v_fma_f32 v139, v138, s97, -v139
	v_fmac_f32_e32 v139, 0x3377d1cf, v138
	v_fmac_f32_e32 v139, 0x3f317217, v138
	v_cmp_lt_f32_e64 s[0:1], |v138|, s2
	s_nop 1
	v_cndmask_b32_e64 v138, v138, v139, s[0:1]
	v_cndmask_b32_e32 v139, 0, v213, vcc
	v_sub_f32_e32 v138, v138, v139
	v_mul_f32_e32 v139, 0xbfb8aa3b, v85
	v_exp_f32_e32 v139, v139
	s_nop 0
	v_add_f32_e32 v139, 1.0, v139
	v_rcp_f32_e32 v139, v139
	s_nop 0
	v_fma_f32 v139, v139, v157, v133
	v_cmp_gt_f32_e32 vcc, s33, v139
	s_nop 1
	v_cndmask_b32_e64 v140, 0, 32, vcc
	v_ldexp_f32 v139, v139, v140
	v_log_f32_e32 v139, v139
	s_nop 0
	v_mul_f32_e32 v140, 0x3f317217, v139
	v_fma_f32 v140, v139, s97, -v140
	v_fmac_f32_e32 v140, 0x3377d1cf, v139
	v_fmac_f32_e32 v140, 0x3f317217, v139
	v_cmp_lt_f32_e64 s[0:1], |v139|, s2
	s_nop 1
	v_cndmask_b32_e64 v139, v139, v140, s[0:1]
	v_cndmask_b32_e32 v140, 0, v213, vcc
	v_sub_f32_e32 v139, v139, v140
	v_mul_f32_e32 v140, 0xbfb8aa3b, v86
	v_exp_f32_e32 v140, v140
	v_cvt_pk_bf16_f32 v138, v138, v139
	v_add_f32_e32 v140, 1.0, v140
	v_rcp_f32_e32 v140, v140
	s_nop 0
	v_fma_f32 v140, v140, v156, v134
	v_cmp_gt_f32_e32 vcc, s33, v140
	s_nop 1
	v_cndmask_b32_e64 v141, 0, 32, vcc
	v_ldexp_f32 v140, v140, v141
	v_log_f32_e32 v140, v140
	s_nop 0
	v_mul_f32_e32 v141, 0x3f317217, v140
	v_fma_f32 v141, v140, s97, -v141
	v_fmac_f32_e32 v141, 0x3377d1cf, v140
	v_fmac_f32_e32 v141, 0x3f317217, v140
	v_cmp_lt_f32_e64 s[0:1], |v140|, s2
	s_nop 1
	v_cndmask_b32_e64 v140, v140, v141, s[0:1]
	v_cndmask_b32_e32 v141, 0, v213, vcc
	v_sub_f32_e32 v140, v140, v141
	v_mul_f32_e32 v141, 0xbfb8aa3b, v87
	v_exp_f32_e32 v141, v141
	s_nop 0
	v_add_f32_e32 v141, 1.0, v141
	v_rcp_f32_e32 v141, v141
	s_nop 0
	v_fma_f32 v141, v141, v154, v135
	v_cmp_gt_f32_e32 vcc, s33, v141
	s_nop 1
	v_cndmask_b32_e64 v160, 0, 32, vcc
	v_ldexp_f32 v141, v141, v160
	v_log_f32_e32 v141, v141
	s_nop 0
	v_mul_f32_e32 v160, 0x3f317217, v141
	v_fma_f32 v160, v141, s97, -v160
	v_fmac_f32_e32 v160, 0x3377d1cf, v141
	v_fmac_f32_e32 v160, 0x3f317217, v141
	v_cmp_lt_f32_e64 s[0:1], |v141|, s2
	s_nop 1
	v_cndmask_b32_e64 v141, v141, v160, s[0:1]
	v_cndmask_b32_e32 v160, 0, v213, vcc
	v_sub_f32_e32 v141, v141, v160
	v_mul_f32_e32 v160, 0xbfb8aa3b, v76
	v_exp_f32_e32 v160, v160
	v_cvt_pk_bf16_f32 v139, v140, v141
	v_add_f32_e32 v160, 1.0, v160
	v_rcp_f32_e32 v160, v160
	s_nop 0
	v_fma_f32 v160, v160, v158, v128
	v_cmp_gt_f32_e32 vcc, s33, v160
	s_nop 1
	v_cndmask_b32_e64 v161, 0, 32, vcc
	v_ldexp_f32 v160, v160, v161
	v_log_f32_e32 v160, v160
	s_nop 0
	v_mul_f32_e32 v161, 0x3f317217, v160
	v_fma_f32 v161, v160, s97, -v161
	v_fmac_f32_e32 v161, 0x3377d1cf, v160
	v_fmac_f32_e32 v161, 0x3f317217, v160
	v_cmp_lt_f32_e64 s[0:1], |v160|, s2
	s_nop 1
	v_cndmask_b32_e64 v160, v160, v161, s[0:1]
	v_cndmask_b32_e32 v161, 0, v213, vcc
	v_sub_f32_e32 v160, v160, v161
	v_mul_f32_e32 v161, 0xbfb8aa3b, v77
	v_exp_f32_e32 v161, v161
	s_nop 0
	v_add_f32_e32 v161, 1.0, v161
	v_rcp_f32_e32 v161, v161
	s_nop 0
	v_fma_f32 v161, v161, v136, v129
	v_cmp_gt_f32_e32 vcc, s33, v161
	s_nop 1
	v_cndmask_b32_e64 v162, 0, 32, vcc
	v_ldexp_f32 v161, v161, v162
	v_log_f32_e32 v161, v161
	s_nop 0
	v_mul_f32_e32 v162, 0x3f317217, v161
	v_fma_f32 v162, v161, s97, -v162
	v_fmac_f32_e32 v162, 0x3377d1cf, v161
	v_fmac_f32_e32 v162, 0x3f317217, v161
	v_cmp_lt_f32_e64 s[0:1], |v161|, s2
	s_nop 1
	v_cndmask_b32_e64 v161, v161, v162, s[0:1]
	v_cndmask_b32_e32 v162, 0, v213, vcc
	v_sub_f32_e32 v161, v161, v162
	v_mul_f32_e32 v162, 0xbfb8aa3b, v78
	v_exp_f32_e32 v162, v162
	v_cvt_pk_bf16_f32 v140, v160, v161
	v_add_f32_e32 v162, 1.0, v162
	v_rcp_f32_e32 v162, v162
	s_nop 0
	v_fma_f32 v162, v162, v155, v130
	v_cmp_gt_f32_e32 vcc, s33, v162
	s_nop 1
	v_cndmask_b32_e64 v163, 0, 32, vcc
	v_ldexp_f32 v162, v162, v163
	v_log_f32_e32 v162, v162
	s_nop 0
	v_mul_f32_e32 v163, 0x3f317217, v162
	v_fma_f32 v163, v162, s97, -v163
	v_fmac_f32_e32 v163, 0x3377d1cf, v162
	v_fmac_f32_e32 v163, 0x3f317217, v162
	v_cmp_lt_f32_e64 s[0:1], |v162|, s2
	s_nop 1
	v_cndmask_b32_e64 v162, v162, v163, s[0:1]
	v_cndmask_b32_e32 v163, 0, v213, vcc
	v_sub_f32_e32 v162, v162, v163
	v_mul_f32_e32 v163, 0xbfb8aa3b, v79
	v_exp_f32_e32 v163, v163
	s_nop 0
	v_add_f32_e32 v163, 1.0, v163
	v_rcp_f32_e32 v163, v163
	s_nop 0
	v_fma_f32 v163, v163, v137, v131
	v_cmp_gt_f32_e32 vcc, s33, v163
	s_nop 1
	v_cndmask_b32_e64 v164, 0, 32, vcc
	v_ldexp_f32 v163, v163, v164
	v_log_f32_e32 v163, v163
	s_nop 0
	v_mul_f32_e32 v164, 0x3f317217, v163
	v_fma_f32 v164, v163, s97, -v164
	v_fmac_f32_e32 v164, 0x3377d1cf, v163
	v_fmac_f32_e32 v164, 0x3f317217, v163
	v_cmp_lt_f32_e64 s[0:1], |v163|, s2
	s_nop 1
	v_cndmask_b32_e64 v163, v163, v164, s[0:1]
	v_cndmask_b32_e32 v164, 0, v213, vcc
	v_sub_f32_e32 v163, v163, v164
	v_cvt_pk_bf16_f32 v141, v162, v163
	global_store_dwordx4 v[142:143], v[138:141], off
	s_nop 1
	v_mul_f32_e32 v138, 0xbfb8aa3b, v68
	v_exp_f32_e32 v138, v138
	s_nop 0
	v_add_f32_e32 v138, 1.0, v138
	v_rcp_f32_e32 v138, v138
	s_nop 0
	v_fma_f32 v138, v138, v159, v132
	v_cmp_gt_f32_e32 vcc, s33, v138
	s_nop 1
	v_cndmask_b32_e64 v139, 0, 32, vcc
	v_ldexp_f32 v138, v138, v139
	v_log_f32_e32 v138, v138
	s_nop 0
	v_mul_f32_e32 v139, 0x3f317217, v138
	v_fma_f32 v139, v138, s97, -v139
	v_fmac_f32_e32 v139, 0x3377d1cf, v138
	v_fmac_f32_e32 v139, 0x3f317217, v138
	v_cmp_lt_f32_e64 s[0:1], |v138|, s2
	s_nop 1
	v_cndmask_b32_e64 v138, v138, v139, s[0:1]
	v_cndmask_b32_e32 v139, 0, v213, vcc
	v_sub_f32_e32 v138, v138, v139
	v_mul_f32_e32 v139, 0xbfb8aa3b, v69
	v_exp_f32_e32 v139, v139
	s_nop 0
	v_add_f32_e32 v139, 1.0, v139
	v_rcp_f32_e32 v139, v139
	s_nop 0
	v_fma_f32 v139, v139, v157, v133
	v_cmp_gt_f32_e32 vcc, s33, v139
	s_nop 1
	v_cndmask_b32_e64 v140, 0, 32, vcc
	v_ldexp_f32 v139, v139, v140
	v_log_f32_e32 v139, v139
	s_nop 0
	v_mul_f32_e32 v140, 0x3f317217, v139
	v_fma_f32 v140, v139, s97, -v140
	v_fmac_f32_e32 v140, 0x3377d1cf, v139
	v_fmac_f32_e32 v140, 0x3f317217, v139
	v_cmp_lt_f32_e64 s[0:1], |v139|, s2
	s_nop 1
	v_cndmask_b32_e64 v139, v139, v140, s[0:1]
	v_cndmask_b32_e32 v140, 0, v213, vcc
	v_sub_f32_e32 v139, v139, v140
	v_mul_f32_e32 v140, 0xbfb8aa3b, v70
	v_exp_f32_e32 v140, v140
	v_cvt_pk_bf16_f32 v138, v138, v139
	v_add_f32_e32 v140, 1.0, v140
	v_rcp_f32_e32 v140, v140
	s_nop 0
	v_fma_f32 v140, v140, v156, v134
	v_cmp_gt_f32_e32 vcc, s33, v140
	s_nop 1
	v_cndmask_b32_e64 v141, 0, 32, vcc
	v_ldexp_f32 v140, v140, v141
	v_log_f32_e32 v140, v140
	s_nop 0
	v_mul_f32_e32 v141, 0x3f317217, v140
	v_fma_f32 v141, v140, s97, -v141
	v_fmac_f32_e32 v141, 0x3377d1cf, v140
	v_fmac_f32_e32 v141, 0x3f317217, v140
	v_cmp_lt_f32_e64 s[0:1], |v140|, s2
	s_nop 1
	v_cndmask_b32_e64 v140, v140, v141, s[0:1]
	v_cndmask_b32_e32 v141, 0, v213, vcc
	v_sub_f32_e32 v140, v140, v141
	v_mul_f32_e32 v141, 0xbfb8aa3b, v71
	v_exp_f32_e32 v141, v141
	s_nop 0
	v_add_f32_e32 v141, 1.0, v141
	v_rcp_f32_e32 v141, v141
	s_nop 0
	v_fma_f32 v141, v141, v154, v135
	v_cmp_gt_f32_e32 vcc, s33, v141
	s_nop 1
	v_cndmask_b32_e64 v142, 0, 32, vcc
	v_ldexp_f32 v141, v141, v142
	v_log_f32_e32 v141, v141
	s_nop 0
	v_mul_f32_e32 v142, 0x3f317217, v141
	v_fma_f32 v142, v141, s97, -v142
	v_fmac_f32_e32 v142, 0x3377d1cf, v141
	v_fmac_f32_e32 v142, 0x3f317217, v141
	v_cmp_lt_f32_e64 s[0:1], |v141|, s2
	s_nop 1
	v_cndmask_b32_e64 v141, v141, v142, s[0:1]
	v_cndmask_b32_e32 v142, 0, v213, vcc
	v_sub_f32_e32 v141, v141, v142
	v_mul_f32_e32 v142, 0xbfb8aa3b, v64
	v_exp_f32_e32 v142, v142
	v_cvt_pk_bf16_f32 v139, v140, v141
	v_add_f32_e32 v142, 1.0, v142
	v_rcp_f32_e32 v142, v142
	s_nop 0
	v_fma_f32 v142, v142, v158, v128
	v_cmp_gt_f32_e32 vcc, s33, v142
	s_nop 1
	v_cndmask_b32_e64 v143, 0, 32, vcc
	v_ldexp_f32 v142, v142, v143
	v_log_f32_e32 v142, v142
	s_nop 0
	v_mul_f32_e32 v143, 0x3f317217, v142
	v_fma_f32 v143, v142, s97, -v143
	v_fmac_f32_e32 v143, 0x3377d1cf, v142
	v_fmac_f32_e32 v143, 0x3f317217, v142
	v_cmp_lt_f32_e64 s[0:1], |v142|, s2
	s_nop 1
	v_cndmask_b32_e64 v142, v142, v143, s[0:1]
	v_cndmask_b32_e32 v143, 0, v213, vcc
	v_sub_f32_e32 v142, v142, v143
	v_mul_f32_e32 v143, 0xbfb8aa3b, v65
	v_exp_f32_e32 v143, v143
	s_nop 0
	v_add_f32_e32 v143, 1.0, v143
	v_rcp_f32_e32 v143, v143
	s_nop 0
	v_fma_f32 v143, v143, v136, v129
	v_cmp_gt_f32_e32 vcc, s33, v143
	s_nop 1
	v_cndmask_b32_e64 v160, 0, 32, vcc
	v_ldexp_f32 v143, v143, v160
	v_log_f32_e32 v143, v143
	s_nop 0
	v_mul_f32_e32 v160, 0x3f317217, v143
	v_fma_f32 v160, v143, s97, -v160
	v_fmac_f32_e32 v160, 0x3377d1cf, v143
	v_fmac_f32_e32 v160, 0x3f317217, v143
	v_cmp_lt_f32_e64 s[0:1], |v143|, s2
	s_nop 1
	v_cndmask_b32_e64 v143, v143, v160, s[0:1]
	v_cndmask_b32_e32 v160, 0, v213, vcc
	v_sub_f32_e32 v143, v143, v160
	v_mul_f32_e32 v160, 0xbfb8aa3b, v66
	v_exp_f32_e32 v160, v160
	v_cvt_pk_bf16_f32 v140, v142, v143
	v_lshl_add_u64 v[142:143], s[8:9], 0, v[144:145]
	v_lshl_add_u64 v[142:143], v[142:143], 0, v[172:173]
	v_add_f32_e32 v160, 1.0, v160
	v_rcp_f32_e32 v160, v160
	s_nop 0
	v_fma_f32 v160, v160, v155, v130
	v_cmp_gt_f32_e32 vcc, s33, v160
	s_nop 1
	v_cndmask_b32_e64 v161, 0, 32, vcc
	v_ldexp_f32 v160, v160, v161
	v_log_f32_e32 v160, v160
	s_nop 0
	v_mul_f32_e32 v161, 0x3f317217, v160
	v_fma_f32 v161, v160, s97, -v161
	v_fmac_f32_e32 v161, 0x3377d1cf, v160
	v_fmac_f32_e32 v161, 0x3f317217, v160
	v_cmp_lt_f32_e64 s[0:1], |v160|, s2
	s_nop 1
	v_cndmask_b32_e64 v160, v160, v161, s[0:1]
	v_cndmask_b32_e32 v161, 0, v213, vcc
	v_sub_f32_e32 v160, v160, v161
	v_mul_f32_e32 v161, 0xbfb8aa3b, v67
	v_exp_f32_e32 v161, v161
	s_nop 0
	v_add_f32_e32 v161, 1.0, v161
	v_rcp_f32_e32 v161, v161
	s_nop 0
	v_fma_f32 v161, v161, v137, v131
	v_cmp_gt_f32_e32 vcc, s33, v161
	s_nop 1
	v_cndmask_b32_e64 v162, 0, 32, vcc
	v_ldexp_f32 v161, v161, v162
	v_log_f32_e32 v161, v161
	s_nop 0
	v_mul_f32_e32 v162, 0x3f317217, v161
	v_fma_f32 v162, v161, s97, -v162
	v_fmac_f32_e32 v162, 0x3377d1cf, v161
	v_fmac_f32_e32 v162, 0x3f317217, v161
	v_cmp_lt_f32_e64 s[0:1], |v161|, s2
	s_nop 1
	v_cndmask_b32_e64 v161, v161, v162, s[0:1]
	v_cndmask_b32_e32 v162, 0, v213, vcc
	v_sub_f32_e32 v161, v161, v162
	v_cvt_pk_bf16_f32 v141, v160, v161
	global_store_dwordx4 v[142:143], v[138:141], off
	s_nop 1
	v_mul_f32_e32 v138, 0xbfb8aa3b, v52
	v_exp_f32_e32 v138, v138
	s_nop 0
	v_add_f32_e32 v138, 1.0, v138
	v_rcp_f32_e32 v138, v138
	s_nop 0
	v_fma_f32 v138, v138, v159, v132
	v_cmp_gt_f32_e32 vcc, s33, v138
	s_nop 1
	v_cndmask_b32_e64 v139, 0, 32, vcc
	v_ldexp_f32 v138, v138, v139
	v_log_f32_e32 v138, v138
	s_nop 0
	v_mul_f32_e32 v139, 0x3f317217, v138
	v_fma_f32 v139, v138, s97, -v139
	v_fmac_f32_e32 v139, 0x3377d1cf, v138
	v_fmac_f32_e32 v139, 0x3f317217, v138
	v_cmp_lt_f32_e64 s[0:1], |v138|, s2
	s_nop 1
	v_cndmask_b32_e64 v138, v138, v139, s[0:1]
	v_cndmask_b32_e32 v139, 0, v213, vcc
	v_sub_f32_e32 v138, v138, v139
	v_mul_f32_e32 v139, 0xbfb8aa3b, v53
	v_exp_f32_e32 v139, v139
	s_nop 0
	v_add_f32_e32 v139, 1.0, v139
	v_rcp_f32_e32 v139, v139
	s_nop 0
	v_fma_f32 v139, v139, v157, v133
	v_cmp_gt_f32_e32 vcc, s33, v139
	s_nop 1
	v_cndmask_b32_e64 v140, 0, 32, vcc
	v_ldexp_f32 v139, v139, v140
	v_log_f32_e32 v139, v139
	s_nop 0
	v_mul_f32_e32 v140, 0x3f317217, v139
	v_fma_f32 v140, v139, s97, -v140
	v_fmac_f32_e32 v140, 0x3377d1cf, v139
	v_fmac_f32_e32 v140, 0x3f317217, v139
	v_cmp_lt_f32_e64 s[0:1], |v139|, s2
	s_nop 1
	v_cndmask_b32_e64 v139, v139, v140, s[0:1]
	v_cndmask_b32_e32 v140, 0, v213, vcc
	v_sub_f32_e32 v139, v139, v140
	v_mul_f32_e32 v140, 0xbfb8aa3b, v54
	v_exp_f32_e32 v140, v140
	v_cvt_pk_bf16_f32 v138, v138, v139
	v_add_f32_e32 v140, 1.0, v140
	v_rcp_f32_e32 v140, v140
	s_nop 0
	v_fma_f32 v140, v140, v156, v134
	v_cmp_gt_f32_e32 vcc, s33, v140
	s_nop 1
	v_cndmask_b32_e64 v141, 0, 32, vcc
	v_ldexp_f32 v140, v140, v141
	v_log_f32_e32 v140, v140
	s_nop 0
	v_mul_f32_e32 v141, 0x3f317217, v140
	v_fma_f32 v141, v140, s97, -v141
	v_fmac_f32_e32 v141, 0x3377d1cf, v140
	v_fmac_f32_e32 v141, 0x3f317217, v140
	v_cmp_lt_f32_e64 s[0:1], |v140|, s2
	s_nop 1
	v_cndmask_b32_e64 v140, v140, v141, s[0:1]
	v_cndmask_b32_e32 v141, 0, v213, vcc
	v_sub_f32_e32 v140, v140, v141
	v_mul_f32_e32 v141, 0xbfb8aa3b, v55
	v_exp_f32_e32 v141, v141
	s_nop 0
	v_add_f32_e32 v141, 1.0, v141
	v_rcp_f32_e32 v141, v141
	s_nop 0
	v_fma_f32 v141, v141, v154, v135
	v_cmp_gt_f32_e32 vcc, s33, v141
	s_nop 1
	v_cndmask_b32_e64 v142, 0, 32, vcc
	v_ldexp_f32 v141, v141, v142
	v_log_f32_e32 v141, v141
	s_nop 0
	v_mul_f32_e32 v142, 0x3f317217, v141
	v_fma_f32 v142, v141, s97, -v142
	v_fmac_f32_e32 v142, 0x3377d1cf, v141
	v_fmac_f32_e32 v142, 0x3f317217, v141
	v_cmp_lt_f32_e64 s[0:1], |v141|, s2
	s_nop 1
	v_cndmask_b32_e64 v141, v141, v142, s[0:1]
	v_cndmask_b32_e32 v142, 0, v213, vcc
	v_sub_f32_e32 v141, v141, v142
	v_mul_f32_e32 v142, 0xbfb8aa3b, v44
	v_exp_f32_e32 v142, v142
	v_cvt_pk_bf16_f32 v139, v140, v141
	v_add_f32_e32 v142, 1.0, v142
	v_rcp_f32_e32 v142, v142
	s_nop 0
	v_fma_f32 v142, v142, v158, v128
	v_cmp_gt_f32_e32 vcc, s33, v142
	s_nop 1
	v_cndmask_b32_e64 v143, 0, 32, vcc
	v_ldexp_f32 v142, v142, v143
	v_log_f32_e32 v142, v142
	s_nop 0
	v_mul_f32_e32 v143, 0x3f317217, v142
	v_fma_f32 v143, v142, s97, -v143
	v_fmac_f32_e32 v143, 0x3377d1cf, v142
	v_fmac_f32_e32 v143, 0x3f317217, v142
	v_cmp_lt_f32_e64 s[0:1], |v142|, s2
	s_nop 1
	v_cndmask_b32_e64 v142, v142, v143, s[0:1]
	v_cndmask_b32_e32 v143, 0, v213, vcc
	v_sub_f32_e32 v142, v142, v143
	v_mul_f32_e32 v143, 0xbfb8aa3b, v45
	v_exp_f32_e32 v143, v143
	s_nop 0
	v_add_f32_e32 v143, 1.0, v143
	v_rcp_f32_e32 v143, v143
	s_nop 0
	v_fma_f32 v143, v143, v136, v129
	v_cmp_gt_f32_e32 vcc, s33, v143
	s_nop 1
	v_cndmask_b32_e64 v144, 0, 32, vcc
	v_ldexp_f32 v143, v143, v144
	v_log_f32_e32 v143, v143
	s_nop 0
	v_mul_f32_e32 v144, 0x3f317217, v143
	v_fma_f32 v144, v143, s97, -v144
	v_fmac_f32_e32 v144, 0x3377d1cf, v143
	v_fmac_f32_e32 v144, 0x3f317217, v143
	v_cmp_lt_f32_e64 s[0:1], |v143|, s2
	s_nop 1
	v_cndmask_b32_e64 v143, v143, v144, s[0:1]
	v_cndmask_b32_e32 v144, 0, v213, vcc
	v_sub_f32_e32 v143, v143, v144
	v_mul_f32_e32 v144, 0xbfb8aa3b, v46
	v_exp_f32_e32 v144, v144
	v_cvt_pk_bf16_f32 v140, v142, v143
	v_lshl_add_u64 v[142:143], s[8:9], 0, v[146:147]
	v_lshl_add_u64 v[142:143], v[142:143], 0, v[172:173]
	v_add_f32_e32 v144, 1.0, v144
	v_rcp_f32_e32 v144, v144
	s_nop 0
	v_fma_f32 v144, v144, v155, v130
	v_cmp_gt_f32_e32 vcc, s33, v144
	s_nop 1
	v_cndmask_b32_e64 v145, 0, 32, vcc
	v_ldexp_f32 v144, v144, v145
	v_log_f32_e32 v144, v144
	s_nop 0
	v_mul_f32_e32 v145, 0x3f317217, v144
	v_fma_f32 v145, v144, s97, -v145
	v_fmac_f32_e32 v145, 0x3377d1cf, v144
	v_fmac_f32_e32 v145, 0x3f317217, v144
	v_cmp_lt_f32_e64 s[0:1], |v144|, s2
	s_nop 1
	v_cndmask_b32_e64 v144, v144, v145, s[0:1]
	v_cndmask_b32_e32 v145, 0, v213, vcc
	v_sub_f32_e32 v144, v144, v145
	v_mul_f32_e32 v145, 0xbfb8aa3b, v47
	v_exp_f32_e32 v145, v145
	s_nop 0
	v_add_f32_e32 v145, 1.0, v145
	v_rcp_f32_e32 v145, v145
	s_nop 0
	v_fma_f32 v145, v145, v137, v131
	v_cmp_gt_f32_e32 vcc, s33, v145
	s_nop 1
	v_cndmask_b32_e64 v160, 0, 32, vcc
	v_ldexp_f32 v145, v145, v160
	v_log_f32_e32 v145, v145
	s_nop 0
	v_mul_f32_e32 v160, 0x3f317217, v145
	v_fma_f32 v160, v145, s97, -v160
	v_fmac_f32_e32 v160, 0x3377d1cf, v145
	v_fmac_f32_e32 v160, 0x3f317217, v145
	v_cmp_lt_f32_e64 s[0:1], |v145|, s2
	s_nop 1
	v_cndmask_b32_e64 v145, v145, v160, s[0:1]
	v_cndmask_b32_e32 v160, 0, v213, vcc
	v_sub_f32_e32 v145, v145, v160
	v_cvt_pk_bf16_f32 v141, v144, v145
	global_store_dwordx4 v[142:143], v[138:141], off
	s_nop 1
	v_mul_f32_e32 v138, 0xbfb8aa3b, v36
	v_exp_f32_e32 v138, v138
	s_nop 0
	v_add_f32_e32 v138, 1.0, v138
	v_rcp_f32_e32 v138, v138
	s_nop 0
	v_fma_f32 v138, v138, v159, v132
	v_cmp_gt_f32_e32 vcc, s33, v138
	s_nop 1
	v_cndmask_b32_e64 v139, 0, 32, vcc
	v_ldexp_f32 v138, v138, v139
	v_log_f32_e32 v138, v138
	s_nop 0
	v_mul_f32_e32 v139, 0x3f317217, v138
	v_fma_f32 v139, v138, s97, -v139
	v_fmac_f32_e32 v139, 0x3377d1cf, v138
	v_fmac_f32_e32 v139, 0x3f317217, v138
	v_cmp_lt_f32_e64 s[0:1], |v138|, s2
	s_nop 1
	v_cndmask_b32_e64 v138, v138, v139, s[0:1]
	v_cndmask_b32_e32 v139, 0, v213, vcc
	v_sub_f32_e32 v138, v138, v139
	v_mul_f32_e32 v139, 0xbfb8aa3b, v37
	v_exp_f32_e32 v139, v139
	s_nop 0
	v_add_f32_e32 v139, 1.0, v139
	v_rcp_f32_e32 v139, v139
	s_nop 0
	v_fma_f32 v139, v139, v157, v133
	v_cmp_gt_f32_e32 vcc, s33, v139
	s_nop 1
	v_cndmask_b32_e64 v140, 0, 32, vcc
	v_ldexp_f32 v139, v139, v140
	v_log_f32_e32 v139, v139
	s_nop 0
	v_mul_f32_e32 v140, 0x3f317217, v139
	v_fma_f32 v140, v139, s97, -v140
	v_fmac_f32_e32 v140, 0x3377d1cf, v139
	v_fmac_f32_e32 v140, 0x3f317217, v139
	v_cmp_lt_f32_e64 s[0:1], |v139|, s2
	s_nop 1
	v_cndmask_b32_e64 v139, v139, v140, s[0:1]
	v_cndmask_b32_e32 v140, 0, v213, vcc
	v_sub_f32_e32 v139, v139, v140
	v_mul_f32_e32 v140, 0xbfb8aa3b, v38
	v_exp_f32_e32 v140, v140
	v_cvt_pk_bf16_f32 v138, v138, v139
	v_add_f32_e32 v140, 1.0, v140
	v_rcp_f32_e32 v140, v140
	s_nop 0
	v_fma_f32 v140, v140, v156, v134
	v_cmp_gt_f32_e32 vcc, s33, v140
	s_nop 1
	v_cndmask_b32_e64 v141, 0, 32, vcc
	v_ldexp_f32 v140, v140, v141
	v_log_f32_e32 v140, v140
	s_nop 0
	v_mul_f32_e32 v141, 0x3f317217, v140
	v_fma_f32 v141, v140, s97, -v141
	v_fmac_f32_e32 v141, 0x3377d1cf, v140
	v_fmac_f32_e32 v141, 0x3f317217, v140
	v_cmp_lt_f32_e64 s[0:1], |v140|, s2
	s_nop 1
	v_cndmask_b32_e64 v140, v140, v141, s[0:1]
	v_cndmask_b32_e32 v141, 0, v213, vcc
	v_sub_f32_e32 v140, v140, v141
	v_mul_f32_e32 v141, 0xbfb8aa3b, v39
	v_exp_f32_e32 v141, v141
	s_nop 0
	v_add_f32_e32 v141, 1.0, v141
	v_rcp_f32_e32 v141, v141
	s_nop 0
	v_fma_f32 v141, v141, v154, v135
	v_cmp_gt_f32_e32 vcc, s33, v141
	s_nop 1
	v_cndmask_b32_e64 v142, 0, 32, vcc
	v_ldexp_f32 v141, v141, v142
	v_log_f32_e32 v141, v141
	s_nop 0
	v_mul_f32_e32 v142, 0x3f317217, v141
	v_fma_f32 v142, v141, s97, -v142
	v_fmac_f32_e32 v142, 0x3377d1cf, v141
	v_fmac_f32_e32 v142, 0x3f317217, v141
	v_cmp_lt_f32_e64 s[0:1], |v141|, s2
	s_nop 1
	v_cndmask_b32_e64 v141, v141, v142, s[0:1]
	v_cndmask_b32_e32 v142, 0, v213, vcc
	v_sub_f32_e32 v141, v141, v142
	v_mul_f32_e32 v142, 0xbfb8aa3b, v28
	v_exp_f32_e32 v142, v142
	v_cvt_pk_bf16_f32 v139, v140, v141
	v_add_f32_e32 v142, 1.0, v142
	v_rcp_f32_e32 v142, v142
	s_nop 0
	v_fma_f32 v142, v142, v158, v128
	v_cmp_gt_f32_e32 vcc, s33, v142
	s_nop 1
	v_cndmask_b32_e64 v143, 0, 32, vcc
	v_ldexp_f32 v142, v142, v143
	v_log_f32_e32 v142, v142
	s_nop 0
	v_mul_f32_e32 v143, 0x3f317217, v142
	v_fma_f32 v143, v142, s97, -v143
	v_fmac_f32_e32 v143, 0x3377d1cf, v142
	v_fmac_f32_e32 v143, 0x3f317217, v142
	v_cmp_lt_f32_e64 s[0:1], |v142|, s2
	s_nop 1
	v_cndmask_b32_e64 v142, v142, v143, s[0:1]
	v_cndmask_b32_e32 v143, 0, v213, vcc
	v_sub_f32_e32 v142, v142, v143
	v_mul_f32_e32 v143, 0xbfb8aa3b, v29
	v_exp_f32_e32 v143, v143
	s_nop 0
	v_add_f32_e32 v143, 1.0, v143
	v_rcp_f32_e32 v143, v143
	s_nop 0
	v_fma_f32 v143, v143, v136, v129
	v_cmp_gt_f32_e32 vcc, s33, v143
	s_nop 1
	v_cndmask_b32_e64 v144, 0, 32, vcc
	v_ldexp_f32 v143, v143, v144
	v_log_f32_e32 v143, v143
	s_nop 0
	v_mul_f32_e32 v144, 0x3f317217, v143
	v_fma_f32 v144, v143, s97, -v144
	v_fmac_f32_e32 v144, 0x3377d1cf, v143
	v_fmac_f32_e32 v144, 0x3f317217, v143
	v_cmp_lt_f32_e64 s[0:1], |v143|, s2
	s_nop 1
	v_cndmask_b32_e64 v143, v143, v144, s[0:1]
	v_cndmask_b32_e32 v144, 0, v213, vcc
	v_sub_f32_e32 v143, v143, v144
	v_mul_f32_e32 v144, 0xbfb8aa3b, v30
	v_exp_f32_e32 v144, v144
	v_cvt_pk_bf16_f32 v140, v142, v143
	v_lshl_add_u64 v[142:143], s[8:9], 0, v[148:149]
	v_lshl_add_u64 v[142:143], v[142:143], 0, v[172:173]
	v_add_f32_e32 v144, 1.0, v144
	v_rcp_f32_e32 v144, v144
	s_nop 0
	v_fma_f32 v144, v144, v155, v130
	v_cmp_gt_f32_e32 vcc, s33, v144
	s_nop 1
	v_cndmask_b32_e64 v145, 0, 32, vcc
	v_ldexp_f32 v144, v144, v145
	v_log_f32_e32 v144, v144
	s_nop 0
	v_mul_f32_e32 v145, 0x3f317217, v144
	v_fma_f32 v145, v144, s97, -v145
	v_fmac_f32_e32 v145, 0x3377d1cf, v144
	v_fmac_f32_e32 v145, 0x3f317217, v144
	v_cmp_lt_f32_e64 s[0:1], |v144|, s2
	s_nop 1
	v_cndmask_b32_e64 v144, v144, v145, s[0:1]
	v_cndmask_b32_e32 v145, 0, v213, vcc
	v_sub_f32_e32 v144, v144, v145
	v_mul_f32_e32 v145, 0xbfb8aa3b, v31
	v_exp_f32_e32 v145, v145
	s_nop 0
	v_add_f32_e32 v145, 1.0, v145
	v_rcp_f32_e32 v145, v145
	s_nop 0
	v_fma_f32 v145, v145, v137, v131
	v_cmp_gt_f32_e32 vcc, s33, v145
	s_nop 1
	v_cndmask_b32_e64 v146, 0, 32, vcc
	v_ldexp_f32 v145, v145, v146
	v_log_f32_e32 v145, v145
	s_nop 0
	v_mul_f32_e32 v146, 0x3f317217, v145
	v_fma_f32 v146, v145, s97, -v146
	v_fmac_f32_e32 v146, 0x3377d1cf, v145
	v_fmac_f32_e32 v146, 0x3f317217, v145
	v_cmp_lt_f32_e64 s[0:1], |v145|, s2
	s_nop 1
	v_cndmask_b32_e64 v145, v145, v146, s[0:1]
	v_cndmask_b32_e32 v146, 0, v213, vcc
	v_sub_f32_e32 v145, v145, v146
	v_cvt_pk_bf16_f32 v141, v144, v145
	global_store_dwordx4 v[142:143], v[138:141], off
	s_nop 1
	v_mul_f32_e32 v138, 0xbfb8aa3b, v20
	v_exp_f32_e32 v138, v138
	s_nop 0
	v_add_f32_e32 v138, 1.0, v138
	v_rcp_f32_e32 v138, v138
	s_nop 0
	v_fma_f32 v138, v138, v159, v132
	v_cmp_gt_f32_e32 vcc, s33, v138
	s_nop 1
	v_cndmask_b32_e64 v139, 0, 32, vcc
	v_ldexp_f32 v138, v138, v139
	v_log_f32_e32 v138, v138
	s_nop 0
	v_mul_f32_e32 v139, 0x3f317217, v138
	v_fma_f32 v139, v138, s97, -v139
	v_fmac_f32_e32 v139, 0x3377d1cf, v138
	v_fmac_f32_e32 v139, 0x3f317217, v138
	v_cmp_lt_f32_e64 s[0:1], |v138|, s2
	s_nop 1
	v_cndmask_b32_e64 v138, v138, v139, s[0:1]
	v_cndmask_b32_e32 v139, 0, v213, vcc
	v_sub_f32_e32 v138, v138, v139
	v_mul_f32_e32 v139, 0xbfb8aa3b, v21
	v_exp_f32_e32 v139, v139
	s_nop 0
	v_add_f32_e32 v139, 1.0, v139
	v_rcp_f32_e32 v139, v139
	s_nop 0
	v_fma_f32 v139, v139, v157, v133
	v_cmp_gt_f32_e32 vcc, s33, v139
	s_nop 1
	v_cndmask_b32_e64 v140, 0, 32, vcc
	v_ldexp_f32 v139, v139, v140
	v_log_f32_e32 v139, v139
	s_nop 0
	v_mul_f32_e32 v140, 0x3f317217, v139
	v_fma_f32 v140, v139, s97, -v140
	v_fmac_f32_e32 v140, 0x3377d1cf, v139
	v_fmac_f32_e32 v140, 0x3f317217, v139
	v_cmp_lt_f32_e64 s[0:1], |v139|, s2
	s_nop 1
	v_cndmask_b32_e64 v139, v139, v140, s[0:1]
	v_cndmask_b32_e32 v140, 0, v213, vcc
	v_sub_f32_e32 v139, v139, v140
	v_mul_f32_e32 v140, 0xbfb8aa3b, v22
	v_exp_f32_e32 v140, v140
	v_cvt_pk_bf16_f32 v138, v138, v139
	v_add_f32_e32 v140, 1.0, v140
	v_rcp_f32_e32 v140, v140
	s_nop 0
	v_fma_f32 v140, v140, v156, v134
	v_cmp_gt_f32_e32 vcc, s33, v140
	s_nop 1
	v_cndmask_b32_e64 v141, 0, 32, vcc
	v_ldexp_f32 v140, v140, v141
	v_log_f32_e32 v140, v140
	s_nop 0
	v_mul_f32_e32 v141, 0x3f317217, v140
	v_fma_f32 v141, v140, s97, -v141
	v_fmac_f32_e32 v141, 0x3377d1cf, v140
	v_fmac_f32_e32 v141, 0x3f317217, v140
	v_cmp_lt_f32_e64 s[0:1], |v140|, s2
	s_nop 1
	v_cndmask_b32_e64 v140, v140, v141, s[0:1]
	v_cndmask_b32_e32 v141, 0, v213, vcc
	v_sub_f32_e32 v140, v140, v141
	v_mul_f32_e32 v141, 0xbfb8aa3b, v23
	v_exp_f32_e32 v141, v141
	s_nop 0
	v_add_f32_e32 v141, 1.0, v141
	v_rcp_f32_e32 v141, v141
	s_nop 0
	v_fma_f32 v141, v141, v154, v135
	v_cmp_gt_f32_e32 vcc, s33, v141
	s_nop 1
	v_cndmask_b32_e64 v142, 0, 32, vcc
	v_ldexp_f32 v141, v141, v142
	v_log_f32_e32 v141, v141
	s_nop 0
	v_mul_f32_e32 v142, 0x3f317217, v141
	v_fma_f32 v142, v141, s97, -v142
	v_fmac_f32_e32 v142, 0x3377d1cf, v141
	v_fmac_f32_e32 v142, 0x3f317217, v141
	v_cmp_lt_f32_e64 s[0:1], |v141|, s2
	s_nop 1
	v_cndmask_b32_e64 v141, v141, v142, s[0:1]
	v_cndmask_b32_e32 v142, 0, v213, vcc
	v_sub_f32_e32 v141, v141, v142
	v_mul_f32_e32 v142, 0xbfb8aa3b, v12
	v_exp_f32_e32 v142, v142
	v_cvt_pk_bf16_f32 v139, v140, v141
	v_add_f32_e32 v142, 1.0, v142
	v_rcp_f32_e32 v142, v142
	s_nop 0
	v_fma_f32 v142, v142, v158, v128
	v_cmp_gt_f32_e32 vcc, s33, v142
	s_nop 1
	v_cndmask_b32_e64 v143, 0, 32, vcc
	v_ldexp_f32 v142, v142, v143
	v_log_f32_e32 v142, v142
	s_nop 0
	v_mul_f32_e32 v143, 0x3f317217, v142
	v_fma_f32 v143, v142, s97, -v143
	v_fmac_f32_e32 v143, 0x3377d1cf, v142
	v_fmac_f32_e32 v143, 0x3f317217, v142
	v_cmp_lt_f32_e64 s[0:1], |v142|, s2
	s_nop 1
	v_cndmask_b32_e64 v142, v142, v143, s[0:1]
	v_cndmask_b32_e32 v143, 0, v213, vcc
	v_sub_f32_e32 v142, v142, v143
	v_mul_f32_e32 v143, 0xbfb8aa3b, v13
	v_exp_f32_e32 v143, v143
	s_nop 0
	v_add_f32_e32 v143, 1.0, v143
	v_rcp_f32_e32 v143, v143
	s_nop 0
	v_fma_f32 v143, v143, v136, v129
	v_cmp_gt_f32_e32 vcc, s33, v143
	s_nop 1
	v_cndmask_b32_e64 v144, 0, 32, vcc
	v_ldexp_f32 v143, v143, v144
	v_log_f32_e32 v143, v143
	s_nop 0
	v_mul_f32_e32 v144, 0x3f317217, v143
	v_fma_f32 v144, v143, s97, -v144
	v_fmac_f32_e32 v144, 0x3377d1cf, v143
	v_fmac_f32_e32 v144, 0x3f317217, v143
	v_cmp_lt_f32_e64 s[0:1], |v143|, s2
	s_nop 1
	v_cndmask_b32_e64 v143, v143, v144, s[0:1]
	v_cndmask_b32_e32 v144, 0, v213, vcc
	v_sub_f32_e32 v143, v143, v144
	v_mul_f32_e32 v144, 0xbfb8aa3b, v14
	v_exp_f32_e32 v144, v144
	v_cvt_pk_bf16_f32 v140, v142, v143
	v_lshl_add_u64 v[142:143], s[8:9], 0, v[152:153]
	v_lshl_add_u64 v[142:143], v[142:143], 0, v[172:173]
	v_add_f32_e32 v144, 1.0, v144
	v_rcp_f32_e32 v144, v144
	s_nop 0
	v_fma_f32 v144, v144, v155, v130
	v_cmp_gt_f32_e32 vcc, s33, v144
	s_nop 1
	v_cndmask_b32_e64 v145, 0, 32, vcc
	v_ldexp_f32 v144, v144, v145
	v_log_f32_e32 v144, v144
	s_nop 0
	v_mul_f32_e32 v145, 0x3f317217, v144
	v_fma_f32 v145, v144, s97, -v145
	v_fmac_f32_e32 v145, 0x3377d1cf, v144
	v_fmac_f32_e32 v145, 0x3f317217, v144
	v_cmp_lt_f32_e64 s[0:1], |v144|, s2
	s_nop 1
	v_cndmask_b32_e64 v144, v144, v145, s[0:1]
	v_cndmask_b32_e32 v145, 0, v213, vcc
	v_sub_f32_e32 v144, v144, v145
	v_mul_f32_e32 v145, 0xbfb8aa3b, v15
	v_exp_f32_e32 v145, v145
	s_nop 0
	v_add_f32_e32 v145, 1.0, v145
	v_rcp_f32_e32 v145, v145
	s_nop 0
	v_fma_f32 v145, v145, v137, v131
	v_cmp_gt_f32_e32 vcc, s33, v145
	s_nop 1
	v_cndmask_b32_e64 v146, 0, 32, vcc
	v_ldexp_f32 v145, v145, v146
	v_log_f32_e32 v145, v145
	s_nop 0
	v_mul_f32_e32 v146, 0x3f317217, v145
	v_fma_f32 v146, v145, s97, -v146
	v_fmac_f32_e32 v146, 0x3377d1cf, v145
	v_fmac_f32_e32 v146, 0x3f317217, v145
	v_cmp_lt_f32_e64 s[0:1], |v145|, s2
	s_nop 1
	v_cndmask_b32_e64 v145, v145, v146, s[0:1]
	v_cndmask_b32_e32 v146, 0, v213, vcc
	v_sub_f32_e32 v145, v145, v146
	v_cvt_pk_bf16_f32 v141, v144, v145
	global_store_dwordx4 v[142:143], v[138:141], off
	s_nop 1
	v_mul_f32_e32 v138, 0xbfb8aa3b, v4
	v_exp_f32_e32 v138, v138
	s_nop 0
	v_add_f32_e32 v138, 1.0, v138
	v_rcp_f32_e32 v138, v138
	s_nop 0
	v_fma_f32 v132, v138, v159, v132
	v_cmp_gt_f32_e32 vcc, s33, v132
	s_nop 1
	v_cndmask_b32_e64 v138, 0, 32, vcc
	v_ldexp_f32 v132, v132, v138
	v_log_f32_e32 v132, v132
	s_nop 0
	v_mul_f32_e32 v138, 0x3f317217, v132
	v_fma_f32 v138, v132, s97, -v138
	v_fmac_f32_e32 v138, 0x3377d1cf, v132
	v_fmac_f32_e32 v138, 0x3f317217, v132
	v_cmp_lt_f32_e64 s[0:1], |v132|, s2
	s_nop 1
	v_cndmask_b32_e64 v132, v132, v138, s[0:1]
	v_cndmask_b32_e32 v138, 0, v213, vcc
	v_sub_f32_e32 v132, v132, v138
	v_mul_f32_e32 v138, 0xbfb8aa3b, v5
	v_exp_f32_e32 v138, v138
	s_nop 0
	v_add_f32_e32 v138, 1.0, v138
	v_rcp_f32_e32 v138, v138
	s_nop 0
	v_fma_f32 v133, v138, v157, v133
	v_cmp_gt_f32_e32 vcc, s33, v133
	s_nop 1
	v_cndmask_b32_e64 v138, 0, 32, vcc
	v_ldexp_f32 v133, v133, v138
	v_log_f32_e32 v133, v133
	s_nop 0
	v_mul_f32_e32 v138, 0x3f317217, v133
	v_fma_f32 v138, v133, s97, -v138
	v_fmac_f32_e32 v138, 0x3377d1cf, v133
	v_fmac_f32_e32 v138, 0x3f317217, v133
	v_cmp_lt_f32_e64 s[0:1], |v133|, s2
	s_nop 1
	v_cndmask_b32_e64 v133, v133, v138, s[0:1]
	v_cndmask_b32_e32 v138, 0, v213, vcc
	v_sub_f32_e32 v133, v133, v138
	v_mul_f32_e32 v138, 0xbfb8aa3b, v6
	v_exp_f32_e32 v138, v138
	s_nop 0
	v_add_f32_e32 v138, 1.0, v138
	v_rcp_f32_e32 v138, v138
	s_nop 0
	v_fma_f32 v134, v138, v156, v134
	v_cmp_gt_f32_e32 vcc, s33, v134
	s_nop 1
	v_cndmask_b32_e64 v138, 0, 32, vcc
	v_ldexp_f32 v134, v134, v138
	v_log_f32_e32 v134, v134
	s_nop 0
	v_mul_f32_e32 v138, 0x3f317217, v134
	v_fma_f32 v138, v134, s97, -v138
	v_fmac_f32_e32 v138, 0x3377d1cf, v134
	v_fmac_f32_e32 v138, 0x3f317217, v134
	v_cmp_lt_f32_e64 s[0:1], |v134|, s2
	s_nop 1
	v_cndmask_b32_e64 v134, v134, v138, s[0:1]
	v_cndmask_b32_e32 v138, 0, v213, vcc
	v_sub_f32_e32 v134, v134, v138
	v_mul_f32_e32 v138, 0xbfb8aa3b, v7
	v_exp_f32_e32 v138, v138
	s_nop 0
	v_add_f32_e32 v138, 1.0, v138
	v_rcp_f32_e32 v138, v138
	s_nop 0
	v_fmac_f32_e32 v135, v138, v154
	v_cmp_gt_f32_e32 vcc, s33, v135
	s_nop 1
	v_cndmask_b32_e64 v138, 0, 32, vcc
	v_ldexp_f32 v135, v135, v138
	v_log_f32_e32 v135, v135
	s_nop 0
	v_mul_f32_e32 v138, 0x3f317217, v135
	v_fma_f32 v138, v135, s97, -v138
	v_fmac_f32_e32 v138, 0x3377d1cf, v135
	v_fmac_f32_e32 v138, 0x3f317217, v135
	v_cmp_lt_f32_e64 s[0:1], |v135|, s2
	s_nop 1
	v_cndmask_b32_e64 v135, v135, v138, s[0:1]
	v_cndmask_b32_e32 v138, 0, v213, vcc
	v_sub_f32_e32 v135, v135, v138
	v_mul_f32_e32 v138, 0xbfb8aa3b, v0
	v_exp_f32_e32 v138, v138
	s_nop 0
	v_add_f32_e32 v138, 1.0, v138
	v_rcp_f32_e32 v138, v138
	s_nop 0
	v_fma_f32 v128, v138, v158, v128
	v_cmp_gt_f32_e32 vcc, s33, v128
	s_nop 1
	v_cndmask_b32_e64 v138, 0, 32, vcc
	v_ldexp_f32 v128, v128, v138
	v_log_f32_e32 v128, v128
	s_nop 0
	v_mul_f32_e32 v138, 0x3f317217, v128
	v_fma_f32 v138, v128, s97, -v138
	v_fmac_f32_e32 v138, 0x3377d1cf, v128
	v_fmac_f32_e32 v138, 0x3f317217, v128
	v_cmp_lt_f32_e64 s[0:1], |v128|, s2
	s_nop 1
	v_cndmask_b32_e64 v128, v128, v138, s[0:1]
	v_cndmask_b32_e32 v138, 0, v213, vcc
	v_sub_f32_e32 v138, v128, v138
	v_mul_f32_e32 v128, 0xbfb8aa3b, v1
	v_exp_f32_e32 v128, v128
	s_nop 0
	v_add_f32_e32 v128, 1.0, v128
	v_rcp_f32_e32 v128, v128
	s_nop 0
	v_fma_f32 v128, v128, v136, v129
	v_cmp_gt_f32_e32 vcc, s33, v128
	s_nop 1
	v_cndmask_b32_e64 v129, 0, 32, vcc
	v_ldexp_f32 v128, v128, v129
	v_log_f32_e32 v128, v128
	s_nop 0
	v_mul_f32_e32 v129, 0x3f317217, v128
	v_fma_f32 v129, v128, s97, -v129
	v_fmac_f32_e32 v129, 0x3377d1cf, v128
	v_fmac_f32_e32 v129, 0x3f317217, v128
	v_cmp_lt_f32_e64 s[0:1], |v128|, s2
	s_nop 1
	v_cndmask_b32_e64 v128, v128, v129, s[0:1]
	v_cndmask_b32_e32 v129, 0, v213, vcc
	v_sub_f32_e32 v136, v128, v129
	v_mul_f32_e32 v128, 0xbfb8aa3b, v2
	v_exp_f32_e32 v128, v128
	s_nop 0
	v_add_f32_e32 v128, 1.0, v128
	v_rcp_f32_e32 v128, v128
	s_nop 0
	v_fma_f32 v128, v128, v155, v130
	v_cmp_gt_f32_e32 vcc, s33, v128
	v_cvt_pk_bf16_f32 v130, v138, v136
	s_nop 0
	v_cndmask_b32_e64 v129, 0, 32, vcc
	v_ldexp_f32 v128, v128, v129
	v_log_f32_e32 v128, v128
	s_nop 0
	v_mul_f32_e32 v129, 0x3f317217, v128
	v_fma_f32 v129, v128, s97, -v129
	v_fmac_f32_e32 v129, 0x3377d1cf, v128
	v_fmac_f32_e32 v129, 0x3f317217, v128
	v_cmp_lt_f32_e64 s[0:1], |v128|, s2
	s_nop 1
	v_cndmask_b32_e64 v128, v128, v129, s[0:1]
	v_cndmask_b32_e32 v129, 0, v213, vcc
	v_sub_f32_e32 v139, v128, v129
	v_mul_f32_e32 v128, 0xbfb8aa3b, v3
	v_exp_f32_e32 v128, v128
	s_nop 0
	v_add_f32_e32 v128, 1.0, v128
	v_rcp_f32_e32 v128, v128
	s_nop 0
	v_fmac_f32_e32 v131, v128, v137
	v_cmp_gt_f32_e32 vcc, s33, v131
	s_nop 1
	v_cndmask_b32_e64 v128, 0, 32, vcc
	v_ldexp_f32 v128, v131, v128
	v_log_f32_e32 v128, v128
	s_nop 0
	v_mul_f32_e32 v129, 0x3f317217, v128
	v_fma_f32 v129, v128, s97, -v129
	v_fmac_f32_e32 v129, 0x3377d1cf, v128
	v_fmac_f32_e32 v129, 0x3f317217, v128
	v_cmp_lt_f32_e64 s[0:1], |v128|, s2
	s_nop 1
	v_cndmask_b32_e64 v128, v128, v129, s[0:1]
	v_cndmask_b32_e32 v129, 0, v213, vcc
	v_sub_f32_e32 v131, v128, v129
	v_cvt_pk_bf16_f32 v128, v132, v133
	v_lshl_add_u64 v[132:133], s[8:9], 0, v[150:151]
	v_cvt_pk_bf16_f32 v129, v134, v135
	v_cvt_pk_bf16_f32 v131, v139, v131
	v_lshl_add_u64 v[132:133], v[132:133], 0, v[172:173]
	global_store_dwordx4 v[132:133], v[128:131], off

.LBB0_411:
	s_andn2_b64 vcc, exec, s[0:1]
	s_cbranch_vccnz .LBB0_413
	v_mul_f32_e32 v132, 0xbfb8aa3b, v120
	v_mul_f32_e32 v133, 0xbfb8aa3b, v121
	v_mul_f32_e32 v136, 0xbfb8aa3b, v122
	v_mul_f32_e32 v137, 0xbfb8aa3b, v123
	v_exp_f32_e32 v132, v132
	v_exp_f32_e32 v133, v133
	v_exp_f32_e32 v136, v136
	v_exp_f32_e32 v137, v137
	v_mul_f32_e32 v128, 0xbfb8aa3b, v124
	v_mul_f32_e32 v129, 0xbfb8aa3b, v125
	v_exp_f32_e32 v128, v128
	v_exp_f32_e32 v129, v129
	v_mul_f32_e32 v130, 0xbfb8aa3b, v126
	v_mul_f32_e32 v131, 0xbfb8aa3b, v127
	v_exp_f32_e32 v130, v130
	v_exp_f32_e32 v131, v131
	v_add_f32_e32 v132, 1.0, v132
	v_add_f32_e32 v133, 1.0, v133
	v_add_f32_e32 v136, 1.0, v136
	v_add_f32_e32 v137, 1.0, v137
	v_rcp_f32_e32 v132, v132
	v_rcp_f32_e32 v133, v133
	v_rcp_f32_e32 v136, v136
	v_rcp_f32_e32 v137, v137
	v_add_f32_e32 v128, 1.0, v128
	v_add_f32_e32 v129, 1.0, v129
	v_rcp_f32_e32 v128, v128
	v_rcp_f32_e32 v129, v129
	v_add_f32_e32 v130, 1.0, v130
	v_add_f32_e32 v131, 1.0, v131
	v_rcp_f32_e32 v130, v130
	v_rcp_f32_e32 v131, v131
	v_pk_mul_f32 v[132:133], v[120:121], v[132:133]
	v_pk_mul_f32 v[136:137], v[122:123], v[136:137]
	v_cvt_pk_bf16_f32 v132, v132, v133
	v_cvt_pk_bf16_f32 v133, v136, v137
	v_mul_f32_e32 v136, 0xbfb8aa3b, v112
	v_mul_f32_e32 v137, 0xbfb8aa3b, v113
	v_readlane_b32 s0, v251, 56
	v_exp_f32_e32 v136, v136
	v_exp_f32_e32 v137, v137
	v_lshlrev_b32_e32 v172, 1, v223
	v_readlane_b32 s1, v251, 57
	v_pk_mul_f32 v[128:129], v[124:125], v[128:129]
	v_ashrrev_i32_e32 v187, 31, v186
	v_lshl_add_u64 v[134:135], s[0:1], 0, v[172:173]
	v_pk_mul_f32 v[138:139], v[126:127], v[130:131]
	v_cvt_pk_bf16_f32 v130, v128, v129
	v_lshlrev_b64 v[128:129], 11, v[186:187]
	v_cvt_pk_bf16_f32 v131, v138, v139
	v_lshl_add_u64 v[128:129], v[134:135], 0, v[128:129]
	global_store_dwordx4 v[128:129], v[130:133], off
	v_mul_f32_e32 v138, 0xbfb8aa3b, v106
	v_mul_f32_e32 v139, 0xbfb8aa3b, v107
	v_add_f32_e32 v130, 1.0, v136
	v_add_f32_e32 v131, 1.0, v137
	v_mul_f32_e32 v136, 0xbfb8aa3b, v104
	v_mul_f32_e32 v137, 0xbfb8aa3b, v105
	v_exp_f32_e32 v136, v136
	v_exp_f32_e32 v137, v137
	v_mul_f32_e32 v132, 0xbfb8aa3b, v114
	v_mul_f32_e32 v133, 0xbfb8aa3b, v115
	v_exp_f32_e32 v132, v132
	v_exp_f32_e32 v133, v133
	v_exp_f32_e32 v138, v138
	v_exp_f32_e32 v139, v139
	v_rcp_f32_e32 v130, v130
	v_rcp_f32_e32 v131, v131
	v_add_f32_e32 v136, 1.0, v136
	v_add_f32_e32 v137, 1.0, v137
	v_rcp_f32_e32 v136, v136
	v_rcp_f32_e32 v137, v137
	v_add_f32_e32 v132, 1.0, v132
	v_add_f32_e32 v133, 1.0, v133
	v_add_f32_e32 v138, 1.0, v138
	v_add_f32_e32 v139, 1.0, v139
	v_rcp_f32_e32 v132, v132
	v_rcp_f32_e32 v133, v133
	v_rcp_f32_e32 v138, v138
	v_rcp_f32_e32 v139, v139
	v_pk_mul_f32 v[130:131], v[112:113], v[130:131]
	v_pk_mul_f32 v[140:141], v[104:105], v[136:137]
	v_cvt_pk_bf16_f32 v136, v130, v131
	v_or_b32_e32 v130, 16, v186
	v_ashrrev_i32_e32 v131, 31, v130
	v_pk_mul_f32 v[132:133], v[114:115], v[132:133]
	v_pk_mul_f32 v[142:143], v[106:107], v[138:139]
	v_lshlrev_b64 v[130:131], 11, v[130:131]
	v_cvt_pk_bf16_f32 v137, v132, v133
	v_cvt_pk_bf16_f32 v138, v140, v141
	v_cvt_pk_bf16_f32 v139, v142, v143
	v_lshl_add_u64 v[130:131], v[134:135], 0, v[130:131]
	global_store_dwordx4 v[130:131], v[136:139], off
	v_mul_f32_e32 v140, 0xbfb8aa3b, v90
	v_mul_f32_e32 v141, 0xbfb8aa3b, v91
	v_mul_f32_e32 v138, 0xbfb8aa3b, v88
	v_mul_f32_e32 v139, 0xbfb8aa3b, v89
	v_mul_f32_e32 v132, 0xbfb8aa3b, v96
	v_mul_f32_e32 v133, 0xbfb8aa3b, v97
	v_exp_f32_e32 v138, v138
	v_exp_f32_e32 v139, v139
	v_exp_f32_e32 v140, v140
	v_exp_f32_e32 v141, v141
	v_exp_f32_e32 v132, v132
	v_exp_f32_e32 v133, v133
	v_mul_f32_e32 v136, 0xbfb8aa3b, v98
	v_mul_f32_e32 v137, 0xbfb8aa3b, v99
	v_exp_f32_e32 v136, v136
	v_exp_f32_e32 v137, v137
	v_add_f32_e32 v138, 1.0, v138
	v_add_f32_e32 v139, 1.0, v139
	v_add_f32_e32 v140, 1.0, v140
	v_add_f32_e32 v141, 1.0, v141
	v_add_f32_e32 v132, 1.0, v132
	v_add_f32_e32 v133, 1.0, v133
	v_rcp_f32_e32 v138, v138
	v_rcp_f32_e32 v139, v139
	v_rcp_f32_e32 v140, v140
	v_rcp_f32_e32 v141, v141
	v_rcp_f32_e32 v132, v132
	v_rcp_f32_e32 v133, v133
	v_add_f32_e32 v136, 1.0, v136
	v_add_f32_e32 v137, 1.0, v137
	v_rcp_f32_e32 v136, v136
	v_rcp_f32_e32 v137, v137
	v_pk_mul_f32 v[138:139], v[88:89], v[138:139]
	v_pk_mul_f32 v[140:141], v[90:91], v[140:141]
	v_pk_mul_f32 v[132:133], v[96:97], v[132:133]
	v_cvt_pk_bf16_f32 v138, v138, v139
	v_cvt_pk_bf16_f32 v139, v140, v141
	v_mul_f32_e32 v140, 0xbfb8aa3b, v80
	v_mul_f32_e32 v141, 0xbfb8aa3b, v81
	v_pk_mul_f32 v[142:143], v[98:99], v[136:137]
	v_cvt_pk_bf16_f32 v136, v132, v133
	v_or_b32_e32 v132, 32, v186
	v_exp_f32_e32 v140, v140
	v_exp_f32_e32 v141, v141
	v_ashrrev_i32_e32 v133, 31, v132
	v_lshlrev_b64 v[132:133], 11, v[132:133]
	v_cvt_pk_bf16_f32 v137, v142, v143
	v_lshl_add_u64 v[132:133], v[134:135], 0, v[132:133]
	global_store_dwordx4 v[132:133], v[136:139], off
	v_mul_f32_e32 v142, 0xbfb8aa3b, v74
	v_mul_f32_e32 v143, 0xbfb8aa3b, v75
	v_add_f32_e32 v136, 1.0, v140
	v_add_f32_e32 v137, 1.0, v141
	v_mul_f32_e32 v138, 0xbfb8aa3b, v82
	v_mul_f32_e32 v139, 0xbfb8aa3b, v83
	v_mul_f32_e32 v140, 0xbfb8aa3b, v72
	v_mul_f32_e32 v141, 0xbfb8aa3b, v73
	v_exp_f32_e32 v138, v138
	v_exp_f32_e32 v139, v139
	v_exp_f32_e32 v140, v140
	v_exp_f32_e32 v141, v141
	v_add_f32_e32 v138, 1.0, v138
	v_add_f32_e32 v139, 1.0, v139
	v_add_f32_e32 v140, 1.0, v140
	v_add_f32_e32 v141, 1.0, v141
	v_exp_f32_e32 v142, v142
	v_exp_f32_e32 v143, v143
	v_rcp_f32_e32 v136, v136
	v_rcp_f32_e32 v137, v137
	v_rcp_f32_e32 v138, v138
	v_rcp_f32_e32 v139, v139
	v_rcp_f32_e32 v140, v140
	v_rcp_f32_e32 v141, v141
	v_add_f32_e32 v142, 1.0, v142
	v_add_f32_e32 v143, 1.0, v143
	v_rcp_f32_e32 v142, v142
	v_rcp_f32_e32 v143, v143
	v_pk_mul_f32 v[136:137], v[80:81], v[136:137]
	v_pk_mul_f32 v[138:139], v[82:83], v[138:139]
	v_pk_mul_f32 v[140:141], v[72:73], v[140:141]
	v_cvt_pk_bf16_f32 v136, v136, v137
	v_cvt_pk_bf16_f32 v137, v138, v139
	v_cvt_pk_bf16_f32 v138, v140, v141
	v_or_b32_e32 v140, 48, v186
	v_ashrrev_i32_e32 v141, 31, v140
	v_lshlrev_b64 v[140:141], 11, v[140:141]
	v_pk_mul_f32 v[142:143], v[74:75], v[142:143]
	v_lshl_add_u64 v[134:135], v[134:135], 0, v[140:141]
	v_mul_f32_e32 v140, 0xbfb8aa3b, v60
	v_mul_f32_e32 v141, 0xbfb8aa3b, v61
	v_cvt_pk_bf16_f32 v139, v142, v143
	v_exp_f32_e32 v140, v140
	v_exp_f32_e32 v141, v141
	global_store_dwordx4 v[134:135], v[136:139], off
	v_mul_f32_e32 v142, 0xbfb8aa3b, v58
	v_mul_f32_e32 v143, 0xbfb8aa3b, v59
	v_mul_f32_e32 v138, 0xbfb8aa3b, v62
	v_mul_f32_e32 v139, 0xbfb8aa3b, v63
	v_exp_f32_e32 v138, v138
	v_exp_f32_e32 v139, v139
	v_add_f32_e32 v136, 1.0, v140
	v_add_f32_e32 v137, 1.0, v141
	v_mul_f32_e32 v140, 0xbfb8aa3b, v56
	v_mul_f32_e32 v141, 0xbfb8aa3b, v57
	v_exp_f32_e32 v140, v140
	v_exp_f32_e32 v141, v141
	v_exp_f32_e32 v142, v142
	v_exp_f32_e32 v143, v143
	v_add_f32_e32 v138, 1.0, v138
	v_add_f32_e32 v139, 1.0, v139
	v_rcp_f32_e32 v138, v138
	v_rcp_f32_e32 v139, v139
	v_add_f32_e32 v140, 1.0, v140
	v_add_f32_e32 v141, 1.0, v141
	v_add_f32_e32 v142, 1.0, v142
	v_add_f32_e32 v143, 1.0, v143
	v_rcp_f32_e32 v140, v140
	v_rcp_f32_e32 v141, v141
	v_rcp_f32_e32 v142, v142
	v_rcp_f32_e32 v143, v143
	v_rcp_f32_e32 v136, v136
	v_rcp_f32_e32 v137, v137
	v_pk_mul_f32 v[144:145], v[62:63], v[138:139]
	v_pk_mul_f32 v[140:141], v[56:57], v[140:141]
	v_cvt_pk_bf16_f32 v139, v144, v145
	v_mul_f32_e32 v144, 0xbfb8aa3b, v48
	v_mul_f32_e32 v145, 0xbfb8aa3b, v49
	v_exp_f32_e32 v144, v144
	v_exp_f32_e32 v145, v145
	v_pk_mul_f32 v[142:143], v[58:59], v[142:143]
	v_pk_mul_f32 v[136:137], v[60:61], v[136:137]
	v_cvt_pk_bf16_f32 v140, v140, v141
	v_cvt_pk_bf16_f32 v141, v142, v143
	v_add_co_u32_e32 v142, vcc, s93, v128
	v_cvt_pk_bf16_f32 v138, v136, v137
	s_nop 0
	v_addc_co_u32_e32 v143, vcc, 0, v129, vcc
	global_store_dwordx4 v[142:143], v[138:141], off
	v_mul_f32_e32 v142, 0xbfb8aa3b, v40
	v_mul_f32_e32 v143, 0xbfb8aa3b, v41
	v_add_f32_e32 v138, 1.0, v144
	v_add_f32_e32 v139, 1.0, v145
	v_mul_f32_e32 v140, 0xbfb8aa3b, v50
	v_mul_f32_e32 v141, 0xbfb8aa3b, v51
	v_mul_f32_e32 v144, 0xbfb8aa3b, v42
	v_mul_f32_e32 v145, 0xbfb8aa3b, v43
	v_exp_f32_e32 v140, v140
	v_exp_f32_e32 v141, v141
	v_exp_f32_e32 v142, v142
	v_exp_f32_e32 v143, v143
	v_exp_f32_e32 v144, v144
	v_exp_f32_e32 v145, v145
	v_add_f32_e32 v140, 1.0, v140
	v_add_f32_e32 v141, 1.0, v141
	v_add_f32_e32 v142, 1.0, v142
	v_add_f32_e32 v143, 1.0, v143
	v_add_f32_e32 v144, 1.0, v144
	v_add_f32_e32 v145, 1.0, v145
	v_rcp_f32_e32 v140, v140
	v_rcp_f32_e32 v141, v141
	v_rcp_f32_e32 v142, v142
	v_rcp_f32_e32 v143, v143
	v_rcp_f32_e32 v144, v144
	v_rcp_f32_e32 v145, v145
	v_rcp_f32_e32 v138, v138
	v_rcp_f32_e32 v139, v139
	v_pk_mul_f32 v[146:147], v[50:51], v[140:141]
	v_pk_mul_f32 v[142:143], v[40:41], v[142:143]
	v_pk_mul_f32 v[144:145], v[42:43], v[144:145]
	v_pk_mul_f32 v[138:139], v[48:49], v[138:139]
	v_cvt_pk_bf16_f32 v141, v146, v147
	v_cvt_pk_bf16_f32 v142, v142, v143
	v_cvt_pk_bf16_f32 v143, v144, v145
	v_add_co_u32_e32 v144, vcc, s96, v128
	v_mul_f32_e32 v146, 0xbfb8aa3b, v32
	v_mul_f32_e32 v147, 0xbfb8aa3b, v33
	v_cvt_pk_bf16_f32 v140, v138, v139
	v_addc_co_u32_e32 v145, vcc, 0, v129, vcc
	v_exp_f32_e32 v146, v146
	v_exp_f32_e32 v147, v147
	global_store_dwordx4 v[144:145], v[140:143], off
	v_mul_f32_e32 v144, 0xbfb8aa3b, v24
	v_mul_f32_e32 v145, 0xbfb8aa3b, v25
	v_mul_f32_e32 v142, 0xbfb8aa3b, v34
	v_mul_f32_e32 v143, 0xbfb8aa3b, v35
	v_exp_f32_e32 v142, v142
	v_exp_f32_e32 v143, v143
	v_add_f32_e32 v140, 1.0, v146
	v_add_f32_e32 v141, 1.0, v147
	v_mul_f32_e32 v146, 0xbfb8aa3b, v26
	v_mul_f32_e32 v147, 0xbfb8aa3b, v27
	v_exp_f32_e32 v144, v144
	v_exp_f32_e32 v145, v145
	v_exp_f32_e32 v146, v146
	v_exp_f32_e32 v147, v147
	v_add_f32_e32 v142, 1.0, v142
	v_add_f32_e32 v143, 1.0, v143
	v_rcp_f32_e32 v142, v142
	v_rcp_f32_e32 v143, v143
	v_rcp_f32_e32 v140, v140
	v_rcp_f32_e32 v141, v141
	v_add_f32_e32 v144, 1.0, v144
	v_add_f32_e32 v145, 1.0, v145
	v_add_f32_e32 v146, 1.0, v146
	v_add_f32_e32 v147, 1.0, v147
	v_rcp_f32_e32 v144, v144
	v_rcp_f32_e32 v145, v145
	v_rcp_f32_e32 v146, v146
	v_rcp_f32_e32 v147, v147
	v_pk_mul_f32 v[148:149], v[34:35], v[142:143]
	s_mov_b64 s[0:1], 0x48000
	v_cvt_pk_bf16_f32 v143, v148, v149
	v_mul_f32_e32 v148, 0xbfb8aa3b, v16
	v_mul_f32_e32 v149, 0xbfb8aa3b, v17
	v_lshl_add_u64 v[138:139], v[128:129], 0, s[0:1]
	v_pk_mul_f32 v[140:141], v[32:33], v[140:141]
	s_mov_b64 s[0:1], 0x50000
	v_exp_f32_e32 v148, v148
	v_exp_f32_e32 v149, v149
	v_pk_mul_f32 v[144:145], v[24:25], v[144:145]
	v_pk_mul_f32 v[146:147], v[26:27], v[146:147]
	v_cvt_pk_bf16_f32 v142, v140, v141
	v_lshl_add_u64 v[140:141], v[128:129], 0, s[0:1]
	s_mov_b32 s0, 0x50000
	v_cvt_pk_bf16_f32 v144, v144, v145
	v_cvt_pk_bf16_f32 v145, v146, v147
	v_add_co_u32_e32 v146, vcc, s0, v128
	s_mov_b64 s[0:1], 0x58000
	s_nop 0
	v_addc_co_u32_e32 v147, vcc, 0, v129, vcc
	global_store_dwordx4 v[146:147], v[142:145], off
	v_mul_f32_e32 v146, 0xbfb8aa3b, v8
	v_mul_f32_e32 v147, 0xbfb8aa3b, v9
	v_add_f32_e32 v142, 1.0, v148
	v_add_f32_e32 v143, 1.0, v149
	v_mul_f32_e32 v144, 0xbfb8aa3b, v18
	v_mul_f32_e32 v145, 0xbfb8aa3b, v19
	v_mul_f32_e32 v148, 0xbfb8aa3b, v10
	v_mul_f32_e32 v149, 0xbfb8aa3b, v11
	v_exp_f32_e32 v144, v144
	v_exp_f32_e32 v145, v145
	v_exp_f32_e32 v146, v146
	v_exp_f32_e32 v147, v147
	v_exp_f32_e32 v148, v148
	v_exp_f32_e32 v149, v149
	v_rcp_f32_e32 v142, v142
	v_rcp_f32_e32 v143, v143
	v_add_f32_e32 v144, 1.0, v144
	v_add_f32_e32 v145, 1.0, v145
	v_add_f32_e32 v146, 1.0, v146
	v_add_f32_e32 v147, 1.0, v147
	v_add_f32_e32 v148, 1.0, v148
	v_add_f32_e32 v149, 1.0, v149
	v_rcp_f32_e32 v144, v144
	v_rcp_f32_e32 v145, v145
	v_rcp_f32_e32 v146, v146
	v_rcp_f32_e32 v147, v147
	v_rcp_f32_e32 v148, v148
	v_rcp_f32_e32 v149, v149
	v_pk_mul_f32 v[142:143], v[16:17], v[142:143]
	v_pk_mul_f32 v[150:151], v[18:19], v[144:145]
	v_pk_mul_f32 v[146:147], v[8:9], v[146:147]
	v_pk_mul_f32 v[148:149], v[10:11], v[148:149]
	v_cvt_pk_bf16_f32 v144, v142, v143
	v_lshl_add_u64 v[142:143], v[128:129], 0, s[0:1]
	s_mov_b32 s0, 0x58000
	v_cvt_pk_bf16_f32 v146, v146, v147
	v_cvt_pk_bf16_f32 v147, v148, v149
	v_add_co_u32_e32 v148, vcc, s0, v128
	v_cvt_pk_bf16_f32 v145, v150, v151
	s_nop 0
	v_addc_co_u32_e32 v149, vcc, 0, v129, vcc
	v_mul_f32_e32 v150, 0xbfb8aa3b, v116
	v_mul_f32_e32 v151, 0xbfb8aa3b, v117
	v_exp_f32_e32 v150, v150
	v_exp_f32_e32 v151, v151
	global_store_dwordx4 v[148:149], v[144:147], off
	v_mul_f32_e32 v148, 0xbfb8aa3b, v108
	v_mul_f32_e32 v149, 0xbfb8aa3b, v109
	v_mul_f32_e32 v146, 0xbfb8aa3b, v118
	v_mul_f32_e32 v147, 0xbfb8aa3b, v119
	v_exp_f32_e32 v146, v146
	v_exp_f32_e32 v147, v147
	v_exp_f32_e32 v148, v148
	v_exp_f32_e32 v149, v149
	v_add_f32_e32 v144, 1.0, v150
	v_add_f32_e32 v145, 1.0, v151
	v_mul_f32_e32 v150, 0xbfb8aa3b, v110
	v_mul_f32_e32 v151, 0xbfb8aa3b, v111
	v_add_f32_e32 v146, 1.0, v146
	v_add_f32_e32 v147, 1.0, v147
	v_add_f32_e32 v148, 1.0, v148
	v_add_f32_e32 v149, 1.0, v149
	v_exp_f32_e32 v150, v150
	v_exp_f32_e32 v151, v151
	v_rcp_f32_e32 v144, v144
	v_rcp_f32_e32 v145, v145
	v_rcp_f32_e32 v146, v146
	v_rcp_f32_e32 v147, v147
	v_rcp_f32_e32 v148, v148
	v_rcp_f32_e32 v149, v149
	v_add_f32_e32 v150, 1.0, v150
	v_add_f32_e32 v151, 1.0, v151
	v_rcp_f32_e32 v150, v150
	v_rcp_f32_e32 v151, v151
	v_pk_mul_f32 v[144:145], v[116:117], v[144:145]
	v_pk_mul_f32 v[146:147], v[118:119], v[146:147]
	v_pk_mul_f32 v[148:149], v[108:109], v[148:149]
	v_cvt_pk_bf16_f32 v144, v144, v145
	v_cvt_pk_bf16_f32 v145, v146, v147
	v_cvt_pk_bf16_f32 v146, v148, v149
	v_mul_f32_e32 v148, 0xbfb8aa3b, v100
	v_mul_f32_e32 v149, 0xbfb8aa3b, v101
	v_exp_f32_e32 v148, v148
	v_exp_f32_e32 v149, v149
	v_pk_mul_f32 v[150:151], v[110:111], v[150:151]
	v_lshl_add_u64 v[136:137], v[128:129], 0, s[4:5]
	v_cvt_pk_bf16_f32 v147, v150, v151
	global_store_dwordx4 v[128:129], v[144:147], off offset:256
	v_add_f32_e32 v128, 1.0, v148
	v_add_f32_e32 v129, 1.0, v149
	v_mul_f32_e32 v144, 0xbfb8aa3b, v102
	v_mul_f32_e32 v145, 0xbfb8aa3b, v103
	v_mul_f32_e32 v146, 0xbfb8aa3b, v92
	v_mul_f32_e32 v147, 0xbfb8aa3b, v93
	v_mul_f32_e32 v148, 0xbfb8aa3b, v94
	v_mul_f32_e32 v149, 0xbfb8aa3b, v95
	v_exp_f32_e32 v144, v144
	v_exp_f32_e32 v145, v145
	v_exp_f32_e32 v146, v146
	v_exp_f32_e32 v147, v147
	v_exp_f32_e32 v148, v148
	v_exp_f32_e32 v149, v149
	v_add_f32_e32 v144, 1.0, v144
	v_add_f32_e32 v145, 1.0, v145
	v_add_f32_e32 v146, 1.0, v146
	v_add_f32_e32 v147, 1.0, v147
	v_add_f32_e32 v148, 1.0, v148
	v_add_f32_e32 v149, 1.0, v149
	v_rcp_f32_e32 v128, v128
	v_rcp_f32_e32 v129, v129
	v_rcp_f32_e32 v144, v144
	v_rcp_f32_e32 v145, v145
	v_rcp_f32_e32 v146, v146
	v_rcp_f32_e32 v147, v147
	v_rcp_f32_e32 v148, v148
	v_rcp_f32_e32 v149, v149
	v_pk_mul_f32 v[128:129], v[100:101], v[128:129]
	v_pk_mul_f32 v[150:151], v[102:103], v[144:145]
	v_pk_mul_f32 v[146:147], v[92:93], v[146:147]
	v_pk_mul_f32 v[148:149], v[94:95], v[148:149]
	v_cvt_pk_bf16_f32 v144, v128, v129
	v_cvt_pk_bf16_f32 v145, v150, v151
	v_cvt_pk_bf16_f32 v146, v146, v147
	v_cvt_pk_bf16_f32 v147, v148, v149
	v_mul_f32_e32 v128, 0xbfb8aa3b, v84
	v_mul_f32_e32 v129, 0xbfb8aa3b, v85
	global_store_dwordx4 v[130:131], v[144:147], off offset:256
	v_mul_f32_e32 v130, 0xbfb8aa3b, v86
	v_mul_f32_e32 v131, 0xbfb8aa3b, v87
	v_mul_f32_e32 v144, 0xbfb8aa3b, v76
	v_mul_f32_e32 v145, 0xbfb8aa3b, v77
	v_mul_f32_e32 v146, 0xbfb8aa3b, v78
	v_mul_f32_e32 v147, 0xbfb8aa3b, v79
	v_exp_f32_e32 v128, v128
	v_exp_f32_e32 v129, v129
	v_exp_f32_e32 v130, v130
	v_exp_f32_e32 v131, v131
	v_exp_f32_e32 v144, v144
	v_exp_f32_e32 v145, v145
	v_exp_f32_e32 v146, v146
	v_exp_f32_e32 v147, v147
	v_add_f32_e32 v128, 1.0, v128
	v_add_f32_e32 v129, 1.0, v129
	v_add_f32_e32 v130, 1.0, v130
	v_add_f32_e32 v131, 1.0, v131
	v_add_f32_e32 v144, 1.0, v144
	v_add_f32_e32 v145, 1.0, v145
	v_add_f32_e32 v146, 1.0, v146
	v_add_f32_e32 v147, 1.0, v147
	v_rcp_f32_e32 v128, v128
	v_rcp_f32_e32 v129, v129
	v_rcp_f32_e32 v130, v130
	v_rcp_f32_e32 v131, v131
	v_rcp_f32_e32 v144, v144
	v_rcp_f32_e32 v145, v145
	v_rcp_f32_e32 v146, v146
	v_rcp_f32_e32 v147, v147
	v_pk_mul_f32 v[128:129], v[84:85], v[128:129]
	v_pk_mul_f32 v[130:131], v[86:87], v[130:131]
	v_pk_mul_f32 v[144:145], v[76:77], v[144:145]
	v_pk_mul_f32 v[146:147], v[78:79], v[146:147]
	v_cvt_pk_bf16_f32 v128, v128, v129
	v_cvt_pk_bf16_f32 v129, v130, v131
	v_cvt_pk_bf16_f32 v130, v144, v145
	v_cvt_pk_bf16_f32 v131, v146, v147
	v_mul_f32_e32 v144, 0xbfb8aa3b, v68
	v_mul_f32_e32 v145, 0xbfb8aa3b, v69
	v_exp_f32_e32 v144, v144
	v_exp_f32_e32 v145, v145
	global_store_dwordx4 v[132:133], v[128:131], off offset:256
	v_mul_f32_e32 v132, 0xbfb8aa3b, v64
	v_mul_f32_e32 v133, 0xbfb8aa3b, v65
	v_mul_f32_e32 v130, 0xbfb8aa3b, v70
	v_mul_f32_e32 v131, 0xbfb8aa3b, v71
	v_exp_f32_e32 v130, v130
	v_exp_f32_e32 v131, v131
	v_exp_f32_e32 v132, v132
	v_exp_f32_e32 v133, v133
	v_add_f32_e32 v128, 1.0, v144
	v_add_f32_e32 v129, 1.0, v145
	v_mul_f32_e32 v144, 0xbfb8aa3b, v66
	v_mul_f32_e32 v145, 0xbfb8aa3b, v67
	v_add_f32_e32 v130, 1.0, v130
	v_add_f32_e32 v131, 1.0, v131
	v_add_f32_e32 v132, 1.0, v132
	v_add_f32_e32 v133, 1.0, v133
	v_exp_f32_e32 v144, v144
	v_exp_f32_e32 v145, v145
	v_rcp_f32_e32 v128, v128
	v_rcp_f32_e32 v129, v129
	v_rcp_f32_e32 v130, v130
	v_rcp_f32_e32 v131, v131
	v_rcp_f32_e32 v132, v132
	v_rcp_f32_e32 v133, v133
	v_add_f32_e32 v144, 1.0, v144
	v_add_f32_e32 v145, 1.0, v145
	v_rcp_f32_e32 v144, v144
	v_rcp_f32_e32 v145, v145
	v_pk_mul_f32 v[128:129], v[68:69], v[128:129]
	v_pk_mul_f32 v[130:131], v[70:71], v[130:131]
	v_pk_mul_f32 v[132:133], v[64:65], v[132:133]
	v_cvt_pk_bf16_f32 v128, v128, v129
	v_cvt_pk_bf16_f32 v129, v130, v131
	v_cvt_pk_bf16_f32 v130, v132, v133
	v_mul_f32_e32 v132, 0xbfb8aa3b, v52
	v_mul_f32_e32 v133, 0xbfb8aa3b, v53
	v_exp_f32_e32 v132, v132
	v_exp_f32_e32 v133, v133
	v_pk_mul_f32 v[144:145], v[66:67], v[144:145]
	s_nop 0
	v_cvt_pk_bf16_f32 v131, v144, v145
	global_store_dwordx4 v[134:135], v[128:131], off offset:256
	v_mul_f32_e32 v134, 0xbfb8aa3b, v46
	v_mul_f32_e32 v135, 0xbfb8aa3b, v47
	v_add_f32_e32 v128, 1.0, v132
	v_add_f32_e32 v129, 1.0, v133
	v_mul_f32_e32 v130, 0xbfb8aa3b, v54
	v_mul_f32_e32 v131, 0xbfb8aa3b, v55
	v_mul_f32_e32 v132, 0xbfb8aa3b, v44
	v_mul_f32_e32 v133, 0xbfb8aa3b, v45
	v_exp_f32_e32 v130, v130
	v_exp_f32_e32 v131, v131
	v_exp_f32_e32 v132, v132
	v_exp_f32_e32 v133, v133
	v_add_f32_e32 v130, 1.0, v130
	v_add_f32_e32 v131, 1.0, v131
	v_add_f32_e32 v132, 1.0, v132
	v_add_f32_e32 v133, 1.0, v133
	v_exp_f32_e32 v134, v134
	v_exp_f32_e32 v135, v135
	v_rcp_f32_e32 v128, v128
	v_rcp_f32_e32 v129, v129
	v_rcp_f32_e32 v130, v130
	v_rcp_f32_e32 v131, v131
	v_rcp_f32_e32 v132, v132
	v_rcp_f32_e32 v133, v133
	v_add_f32_e32 v134, 1.0, v134
	v_add_f32_e32 v135, 1.0, v135
	v_rcp_f32_e32 v134, v134
	v_rcp_f32_e32 v135, v135
	v_pk_mul_f32 v[128:129], v[52:53], v[128:129]
	v_pk_mul_f32 v[130:131], v[54:55], v[130:131]
	v_pk_mul_f32 v[132:133], v[44:45], v[132:133]
	v_cvt_pk_bf16_f32 v128, v128, v129
	v_cvt_pk_bf16_f32 v129, v130, v131
	v_cvt_pk_bf16_f32 v130, v132, v133
	v_mul_f32_e32 v132, 0xbfb8aa3b, v36
	v_mul_f32_e32 v133, 0xbfb8aa3b, v37
	v_exp_f32_e32 v132, v132
	v_exp_f32_e32 v133, v133
	v_pk_mul_f32 v[134:135], v[46:47], v[134:135]
	s_nop 0
	v_cvt_pk_bf16_f32 v131, v134, v135
	global_store_dwordx4 v[136:137], v[128:131], off offset:256
	v_mul_f32_e32 v134, 0xbfb8aa3b, v30
	v_mul_f32_e32 v135, 0xbfb8aa3b, v31
	v_add_f32_e32 v128, 1.0, v132
	v_add_f32_e32 v129, 1.0, v133
	v_mul_f32_e32 v130, 0xbfb8aa3b, v38
	v_mul_f32_e32 v131, 0xbfb8aa3b, v39
	v_mul_f32_e32 v132, 0xbfb8aa3b, v28
	v_mul_f32_e32 v133, 0xbfb8aa3b, v29
	v_exp_f32_e32 v130, v130
	v_exp_f32_e32 v131, v131
	v_exp_f32_e32 v132, v132
	v_exp_f32_e32 v133, v133
	v_add_f32_e32 v130, 1.0, v130
	v_add_f32_e32 v131, 1.0, v131
	v_add_f32_e32 v132, 1.0, v132
	v_add_f32_e32 v133, 1.0, v133
	v_exp_f32_e32 v134, v134
	v_exp_f32_e32 v135, v135
	v_rcp_f32_e32 v128, v128
	v_rcp_f32_e32 v129, v129
	v_rcp_f32_e32 v130, v130
	v_rcp_f32_e32 v131, v131
	v_rcp_f32_e32 v132, v132
	v_rcp_f32_e32 v133, v133
	v_add_f32_e32 v134, 1.0, v134
	v_add_f32_e32 v135, 1.0, v135
	v_rcp_f32_e32 v134, v134
	v_rcp_f32_e32 v135, v135
	v_pk_mul_f32 v[128:129], v[36:37], v[128:129]
	v_pk_mul_f32 v[130:131], v[38:39], v[130:131]
	v_pk_mul_f32 v[132:133], v[28:29], v[132:133]
	v_cvt_pk_bf16_f32 v128, v128, v129
	v_cvt_pk_bf16_f32 v129, v130, v131
	v_cvt_pk_bf16_f32 v130, v132, v133
	v_mul_f32_e32 v132, 0xbfb8aa3b, v20
	v_mul_f32_e32 v133, 0xbfb8aa3b, v21
	v_exp_f32_e32 v132, v132
	v_exp_f32_e32 v133, v133
	v_pk_mul_f32 v[134:135], v[30:31], v[134:135]
	s_nop 0
	v_cvt_pk_bf16_f32 v131, v134, v135
	global_store_dwordx4 v[138:139], v[128:131], off offset:256
	v_mul_f32_e32 v134, 0xbfb8aa3b, v14
	v_mul_f32_e32 v135, 0xbfb8aa3b, v15
	v_add_f32_e32 v128, 1.0, v132
	v_add_f32_e32 v129, 1.0, v133
	v_mul_f32_e32 v130, 0xbfb8aa3b, v22
	v_mul_f32_e32 v131, 0xbfb8aa3b, v23
	v_mul_f32_e32 v132, 0xbfb8aa3b, v12
	v_mul_f32_e32 v133, 0xbfb8aa3b, v13
	v_exp_f32_e32 v130, v130
	v_exp_f32_e32 v131, v131
	v_exp_f32_e32 v132, v132
	v_exp_f32_e32 v133, v133
	v_add_f32_e32 v130, 1.0, v130
	v_add_f32_e32 v131, 1.0, v131
	v_add_f32_e32 v132, 1.0, v132
	v_add_f32_e32 v133, 1.0, v133
	v_exp_f32_e32 v134, v134
	v_exp_f32_e32 v135, v135
	v_rcp_f32_e32 v128, v128
	v_rcp_f32_e32 v129, v129
	v_rcp_f32_e32 v130, v130
	v_rcp_f32_e32 v131, v131
	v_rcp_f32_e32 v132, v132
	v_rcp_f32_e32 v133, v133
	v_add_f32_e32 v134, 1.0, v134
	v_add_f32_e32 v135, 1.0, v135
	v_rcp_f32_e32 v134, v134
	v_rcp_f32_e32 v135, v135
	v_pk_mul_f32 v[128:129], v[20:21], v[128:129]
	v_pk_mul_f32 v[130:131], v[22:23], v[130:131]
	v_pk_mul_f32 v[132:133], v[12:13], v[132:133]
	v_cvt_pk_bf16_f32 v128, v128, v129
	v_cvt_pk_bf16_f32 v129, v130, v131
	v_cvt_pk_bf16_f32 v130, v132, v133
	v_mul_f32_e32 v132, 0xbfb8aa3b, v4
	v_mul_f32_e32 v133, 0xbfb8aa3b, v5
	v_exp_f32_e32 v132, v132
	v_exp_f32_e32 v133, v133
	v_pk_mul_f32 v[134:135], v[14:15], v[134:135]
	s_nop 0
	v_cvt_pk_bf16_f32 v131, v134, v135
	global_store_dwordx4 v[140:141], v[128:131], off offset:256
	v_mul_f32_e32 v134, 0xbfb8aa3b, v2
	v_mul_f32_e32 v135, 0xbfb8aa3b, v3
	v_add_f32_e32 v128, 1.0, v132
	v_add_f32_e32 v129, 1.0, v133
	v_mul_f32_e32 v130, 0xbfb8aa3b, v6
	v_mul_f32_e32 v131, 0xbfb8aa3b, v7
	v_mul_f32_e32 v132, 0xbfb8aa3b, v0
	v_mul_f32_e32 v133, 0xbfb8aa3b, v1
	v_exp_f32_e32 v130, v130
	v_exp_f32_e32 v131, v131
	v_exp_f32_e32 v132, v132
	v_exp_f32_e32 v133, v133
	v_exp_f32_e32 v134, v134
	v_exp_f32_e32 v135, v135
	v_add_f32_e32 v130, 1.0, v130
	v_add_f32_e32 v131, 1.0, v131
	v_add_f32_e32 v132, 1.0, v132
	v_add_f32_e32 v133, 1.0, v133
	v_add_f32_e32 v134, 1.0, v134
	v_add_f32_e32 v135, 1.0, v135
	v_rcp_f32_e32 v128, v128
	v_rcp_f32_e32 v129, v129
	v_rcp_f32_e32 v130, v130
	v_rcp_f32_e32 v131, v131
	v_rcp_f32_e32 v132, v132
	v_rcp_f32_e32 v133, v133
	v_rcp_f32_e32 v134, v134
	v_rcp_f32_e32 v135, v135
	v_pk_mul_f32 v[128:129], v[4:5], v[128:129]
	v_pk_mul_f32 v[130:131], v[6:7], v[130:131]
	v_pk_mul_f32 v[132:133], v[0:1], v[132:133]
	v_pk_mul_f32 v[134:135], v[2:3], v[134:135]
	v_cvt_pk_bf16_f32 v128, v128, v129
	v_cvt_pk_bf16_f32 v129, v130, v131
	v_cvt_pk_bf16_f32 v130, v132, v133
	v_cvt_pk_bf16_f32 v131, v134, v135
	global_store_dwordx4 v[142:143], v[128:131], off offset:256

.LBB0_414:
	s_andn2_b64 vcc, exec, s[0:1]
	s_cbranch_vccnz .LBB0_416
	v_lshlrev_b32_e32 v172, 1, v223
	v_ashrrev_i32_e32 v187, 31, v186
	v_or_b32_e32 v136, 16, v186
	v_lshl_add_u64 v[132:133], s[86:87], 0, v[172:173]
	v_lshlrev_b64 v[134:135], 11, v[186:187]
	v_ashrrev_i32_e32 v137, 31, v136
	v_or_b32_e32 v138, 32, v186
	v_cvt_pk_bf16_f32 v128, v124, v125
	v_cvt_pk_bf16_f32 v129, v126, v127
	v_cvt_pk_bf16_f32 v130, v120, v121
	v_cvt_pk_bf16_f32 v131, v122, v123
	v_lshl_add_u64 v[134:135], v[132:133], 0, v[134:135]
	v_lshlrev_b64 v[136:137], 11, v[136:137]
	v_ashrrev_i32_e32 v139, 31, v138
	v_or_b32_e32 v140, 48, v186
	global_store_dwordx4 v[134:135], v[128:131], off
	v_lshl_add_u64 v[136:137], v[132:133], 0, v[136:137]
	v_lshlrev_b64 v[138:139], 11, v[138:139]
	v_cvt_pk_bf16_f32 v128, v112, v113
	v_cvt_pk_bf16_f32 v129, v114, v115
	v_cvt_pk_bf16_f32 v130, v104, v105
	v_cvt_pk_bf16_f32 v131, v106, v107
	v_ashrrev_i32_e32 v141, 31, v140
	global_store_dwordx4 v[136:137], v[128:131], off
	v_lshl_add_u64 v[138:139], v[132:133], 0, v[138:139]
	v_lshlrev_b64 v[140:141], 11, v[140:141]
	v_cvt_pk_bf16_f32 v128, v96, v97
	v_cvt_pk_bf16_f32 v129, v98, v99
	v_cvt_pk_bf16_f32 v130, v88, v89
	v_cvt_pk_bf16_f32 v131, v90, v91
	v_add_co_u32_e32 v142, vcc, s93, v134
	global_store_dwordx4 v[138:139], v[128:131], off
	v_lshl_add_u64 v[132:133], v[132:133], 0, v[140:141]
	v_addc_co_u32_e32 v143, vcc, 0, v135, vcc
	v_cvt_pk_bf16_f32 v128, v80, v81
	v_cvt_pk_bf16_f32 v129, v82, v83
	v_cvt_pk_bf16_f32 v130, v72, v73
	v_cvt_pk_bf16_f32 v131, v74, v75
	global_store_dwordx4 v[132:133], v[128:131], off
	s_mov_b64 s[0:1], 0x48000
	v_add_co_u32_e32 v144, vcc, s96, v134
	v_cvt_pk_bf16_f32 v128, v60, v61
	v_cvt_pk_bf16_f32 v129, v62, v63
	v_cvt_pk_bf16_f32 v130, v56, v57
	v_cvt_pk_bf16_f32 v131, v58, v59
	global_store_dwordx4 v[142:143], v[128:131], off
	v_lshl_add_u64 v[142:143], v[134:135], 0, s[0:1]
	v_addc_co_u32_e32 v145, vcc, 0, v135, vcc
	v_cvt_pk_bf16_f32 v128, v48, v49
	v_cvt_pk_bf16_f32 v129, v50, v51
	v_cvt_pk_bf16_f32 v130, v40, v41
	v_cvt_pk_bf16_f32 v131, v42, v43
	s_mov_b64 s[0:1], 0x50000
	global_store_dwordx4 v[144:145], v[128:131], off
	v_lshl_add_u64 v[144:145], v[134:135], 0, s[0:1]
	s_mov_b32 s0, 0x50000
	v_add_co_u32_e32 v146, vcc, s0, v134
	v_cvt_pk_bf16_f32 v128, v32, v33
	v_cvt_pk_bf16_f32 v129, v34, v35
	v_cvt_pk_bf16_f32 v130, v24, v25
	v_cvt_pk_bf16_f32 v131, v26, v27
	v_addc_co_u32_e32 v147, vcc, 0, v135, vcc
	s_mov_b64 s[0:1], 0x58000
	global_store_dwordx4 v[146:147], v[128:131], off
	v_lshl_add_u64 v[146:147], v[134:135], 0, s[0:1]
	s_mov_b32 s0, 0x58000
	v_add_co_u32_e32 v148, vcc, s0, v134
	v_cvt_pk_bf16_f32 v128, v16, v17
	v_cvt_pk_bf16_f32 v129, v18, v19
	v_cvt_pk_bf16_f32 v130, v8, v9
	v_cvt_pk_bf16_f32 v131, v10, v11
	v_addc_co_u32_e32 v149, vcc, 0, v135, vcc
	global_store_dwordx4 v[148:149], v[128:131], off
	v_lshl_add_u64 v[140:141], v[134:135], 0, s[4:5]
	s_nop 0
	v_cvt_pk_bf16_f32 v128, v116, v117
	v_cvt_pk_bf16_f32 v129, v118, v119
	v_cvt_pk_bf16_f32 v130, v108, v109
	v_cvt_pk_bf16_f32 v131, v110, v111
	global_store_dwordx4 v[134:135], v[128:131], off offset:256
	s_nop 1
	v_cvt_pk_bf16_f32 v128, v100, v101
	v_cvt_pk_bf16_f32 v129, v102, v103
	v_cvt_pk_bf16_f32 v130, v92, v93
	v_cvt_pk_bf16_f32 v131, v94, v95
	global_store_dwordx4 v[136:137], v[128:131], off offset:256
	s_nop 1
	v_cvt_pk_bf16_f32 v128, v84, v85
	v_cvt_pk_bf16_f32 v129, v86, v87
	v_cvt_pk_bf16_f32 v130, v76, v77
	v_cvt_pk_bf16_f32 v131, v78, v79
	global_store_dwordx4 v[138:139], v[128:131], off offset:256
	s_nop 1
	v_cvt_pk_bf16_f32 v128, v68, v69
	v_cvt_pk_bf16_f32 v129, v70, v71
	v_cvt_pk_bf16_f32 v130, v64, v65
	v_cvt_pk_bf16_f32 v131, v66, v67
	global_store_dwordx4 v[132:133], v[128:131], off offset:256
	s_nop 1
	v_cvt_pk_bf16_f32 v128, v52, v53
	v_cvt_pk_bf16_f32 v129, v54, v55
	v_cvt_pk_bf16_f32 v130, v44, v45
	v_cvt_pk_bf16_f32 v131, v46, v47
	global_store_dwordx4 v[140:141], v[128:131], off offset:256
	s_nop 1
	v_cvt_pk_bf16_f32 v128, v36, v37
	v_cvt_pk_bf16_f32 v129, v38, v39
	v_cvt_pk_bf16_f32 v130, v28, v29
	v_cvt_pk_bf16_f32 v131, v30, v31
	global_store_dwordx4 v[142:143], v[128:131], off offset:256
	s_nop 1
	v_cvt_pk_bf16_f32 v128, v20, v21
	v_cvt_pk_bf16_f32 v129, v22, v23
	v_cvt_pk_bf16_f32 v130, v12, v13
	v_cvt_pk_bf16_f32 v131, v14, v15
	global_store_dwordx4 v[144:145], v[128:131], off offset:256
	s_nop 1
	v_cvt_pk_bf16_f32 v128, v4, v5
	v_cvt_pk_bf16_f32 v129, v6, v7
	v_cvt_pk_bf16_f32 v130, v0, v1
	v_cvt_pk_bf16_f32 v131, v2, v3
	global_store_dwordx4 v[146:147], v[128:131], off offset:256

.LBB0_417:
	s_lshl_b32 s0, s38, 7
	s_add_i32 s0, s89, s0
	v_pk_mul_f32 v[116:117], v[124:125], v[116:117]
	v_ashrrev_i32_e32 v187, 31, v186
	v_or_b32_e32 v172, s0, v222
	v_pk_mul_f32 v[118:119], v[126:127], v[118:119]
	v_pk_mul_f32 v[122:123], v[122:123], v[110:111]
	v_pk_mul_f32 v[110:111], v[120:121], v[108:109]
	v_cvt_pk_bf16_f32 v108, v116, v117
	v_lshlrev_b64 v[116:117], 11, v[186:187]
	v_cvt_pk_bf16_f32 v109, v118, v119
	v_lshl_add_u64 v[116:117], s[34:35], 0, v[116:117]
	v_lshlrev_b64 v[118:119], 1, v[172:173]
	v_lshl_add_u64 v[116:117], v[116:117], 0, v[118:119]
	v_pk_mul_f32 v[52:53], v[60:61], v[52:53]
	v_pk_mul_f32 v[58:59], v[58:59], v[46:47]
	v_pk_mul_f32 v[46:47], v[56:57], v[44:45]
	v_cvt_pk_bf16_f32 v44, v52, v53
	v_add_co_u32_e32 v52, vcc, s93, v116
	v_pk_mul_f32 v[36:37], v[48:49], v[36:37]
	s_nop 0
	v_addc_co_u32_e32 v53, vcc, 0, v117, vcc
	v_pk_mul_f32 v[100:101], v[112:113], v[100:101]
	v_pk_mul_f32 v[84:85], v[96:97], v[84:85]
	v_pk_mul_f32 v[68:69], v[80:81], v[68:69]
	v_pk_mul_f32 v[42:43], v[42:43], v[30:31]
	v_pk_mul_f32 v[30:31], v[40:41], v[28:29]
	v_cvt_pk_bf16_f32 v28, v36, v37
	v_add_co_u32_e32 v36, vcc, s96, v116
	v_pk_mul_f32 v[106:107], v[106:107], v[94:95]
	v_pk_mul_f32 v[94:95], v[104:105], v[92:93]
	v_cvt_pk_bf16_f32 v92, v100, v101
	v_or_b32_e32 v100, 16, v186
	v_pk_mul_f32 v[90:91], v[90:91], v[78:79]
	v_pk_mul_f32 v[78:79], v[88:89], v[76:77]
	v_cvt_pk_bf16_f32 v76, v84, v85
	v_or_b32_e32 v84, 32, v186
	v_pk_mul_f32 v[74:75], v[74:75], v[66:67]
	v_pk_mul_f32 v[66:67], v[72:73], v[64:65]
	v_cvt_pk_bf16_f32 v64, v68, v69
	v_or_b32_e32 v68, 48, v186
	v_addc_co_u32_e32 v37, vcc, 0, v117, vcc
	v_pk_mul_f32 v[20:21], v[32:33], v[20:21]
	s_mov_b32 s0, 0x50000
	v_ashrrev_i32_e32 v101, 31, v100
	v_ashrrev_i32_e32 v85, 31, v84
	v_ashrrev_i32_e32 v69, 31, v68
	v_pk_mul_f32 v[26:27], v[26:27], v[14:15]
	v_pk_mul_f32 v[14:15], v[24:25], v[12:13]
	v_cvt_pk_bf16_f32 v12, v20, v21
	v_add_co_u32_e32 v20, vcc, s0, v116
	v_lshlrev_b64 v[100:101], 11, v[100:101]
	v_lshlrev_b64 v[84:85], 11, v[84:85]
	v_lshlrev_b64 v[68:69], 11, v[68:69]
	v_addc_co_u32_e32 v21, vcc, 0, v117, vcc
	v_pk_mul_f32 v[4:5], v[16:17], v[4:5]
	v_pk_mul_f32 v[102:103], v[114:115], v[102:103]
	v_lshl_add_u64 v[100:101], s[34:35], 0, v[100:101]
	v_pk_mul_f32 v[86:87], v[98:99], v[86:87]
	v_lshl_add_u64 v[84:85], s[34:35], 0, v[84:85]
	v_pk_mul_f32 v[70:71], v[82:83], v[70:71]
	v_lshl_add_u64 v[68:69], s[34:35], 0, v[68:69]
	v_pk_mul_f32 v[54:55], v[62:63], v[54:55]
	v_pk_mul_f32 v[38:39], v[50:51], v[38:39]
	v_pk_mul_f32 v[22:23], v[34:35], v[22:23]
	v_pk_mul_f32 v[6:7], v[18:19], v[6:7]
	v_pk_mul_f32 v[10:11], v[10:11], v[2:3]
	v_pk_mul_f32 v[2:3], v[8:9], v[0:1]
	v_cvt_pk_bf16_f32 v0, v4, v5
	v_add_co_u32_e32 v4, vcc, 0x58000, v116
	v_cvt_pk_bf16_f32 v110, v110, v111
	v_cvt_pk_bf16_f32 v111, v122, v123
	v_cvt_pk_bf16_f32 v93, v102, v103
	v_cvt_pk_bf16_f32 v94, v94, v95
	v_cvt_pk_bf16_f32 v95, v106, v107
	v_lshl_add_u64 v[100:101], v[100:101], 0, v[118:119]
	v_cvt_pk_bf16_f32 v77, v86, v87
	v_cvt_pk_bf16_f32 v78, v78, v79
	v_cvt_pk_bf16_f32 v79, v90, v91
	v_lshl_add_u64 v[84:85], v[84:85], 0, v[118:119]
	v_cvt_pk_bf16_f32 v65, v70, v71
	v_cvt_pk_bf16_f32 v66, v66, v67
	v_cvt_pk_bf16_f32 v67, v74, v75
	v_lshl_add_u64 v[68:69], v[68:69], 0, v[118:119]
	v_cvt_pk_bf16_f32 v45, v54, v55
	v_cvt_pk_bf16_f32 v46, v46, v47
	v_cvt_pk_bf16_f32 v47, v58, v59
	v_cvt_pk_bf16_f32 v29, v38, v39
	v_cvt_pk_bf16_f32 v30, v30, v31
	v_cvt_pk_bf16_f32 v31, v42, v43
	v_cvt_pk_bf16_f32 v13, v22, v23
	v_cvt_pk_bf16_f32 v14, v14, v15
	v_cvt_pk_bf16_f32 v15, v26, v27
	v_cvt_pk_bf16_f32 v1, v6, v7
	v_cvt_pk_bf16_f32 v2, v2, v3
	v_cvt_pk_bf16_f32 v3, v10, v11
	v_addc_co_u32_e32 v5, vcc, 0, v117, vcc
	global_store_dwordx4 v[116:117], v[108:111], off
	global_store_dwordx4 v[100:101], v[92:95], off
	global_store_dwordx4 v[84:85], v[76:79], off
	global_store_dwordx4 v[68:69], v[64:67], off
	global_store_dwordx4 v[52:53], v[44:47], off
	global_store_dwordx4 v[36:37], v[28:31], off
	global_store_dwordx4 v[20:21], v[12:15], off
	global_store_dwordx4 v[4:5], v[0:3], off
	s_andn2_b64 vcc, exec, s[36:37]
	s_mov_b64 s[0:1], -1
	s_cbranch_vccnz .LBB0_382

.LBB0_859:
	v_mov_b32_e32 v131, v132
	s_lshl_b32 s24, s24, 8
	s_add_i32 s24, s24, s70
	v_and_or_b32 v130, v131, 15, s24
	s_lshl_b32 s24, s25, 8
	v_lshrrev_b32_e32 v131, 1, v131
	v_and_or_b32 v131, v131, 24, s24
	v_or_b32_e32 v136, s71, v131
	v_ashrrev_i32_e32 v131, 31, v130
	v_ashrrev_i32_e32 v137, 31, v136
	v_lshlrev_b64 v[138:139], 11, v[130:131]
	v_lshl_add_u64 v[138:139], s[2:3], 0, v[138:139]
	v_lshlrev_b64 v[136:137], 1, v[136:137]
	v_lshl_add_u64 v[138:139], v[138:139], 0, v[136:137]
	v_cvt_pk_bf16_f32 v60, v60, v61
	v_cvt_pk_bf16_f32 v61, v62, v63
	v_cvt_pk_bf16_f32 v62, v56, v57
	v_add_co_u32_e32 v56, vcc, s93, v138
	v_cvt_pk_bf16_f32 v68, v68, v69
	v_cvt_pk_bf16_f32 v69, v70, v71
	v_cvt_pk_bf16_f32 v70, v64, v65
	v_lshl_add_u64 v[64:65], v[138:139], 0, s[4:5]
	v_addc_co_u32_e32 v57, vcc, 0, v139, vcc
	v_cvt_pk_bf16_f32 v44, v44, v45
	v_cvt_pk_bf16_f32 v45, v46, v47
	v_cvt_pk_bf16_f32 v46, v40, v41
	v_cvt_pk_bf16_f32 v47, v42, v43
	s_mov_b64 s[24:25], 0x48000
	v_cvt_pk_bf16_f32 v108, v108, v109
	v_cvt_pk_bf16_f32 v109, v110, v111
	v_cvt_pk_bf16_f32 v110, v104, v105
	v_or_b32_e32 v104, 16, v130
	global_store_dwordx4 v[64:65], v[44:47], off offset:256
	v_cvt_pk_bf16_f32 v28, v28, v29
	v_cvt_pk_bf16_f32 v29, v30, v31
	v_lshl_add_u64 v[44:45], v[138:139], 0, s[24:25]
	v_add_co_u32_e32 v46, vcc, s96, v138
	v_cvt_pk_bf16_f32 v30, v24, v25
	v_cvt_pk_bf16_f32 v31, v26, v27
	s_mov_b64 s[24:25], 0x50000
	v_ashrrev_i32_e32 v105, 31, v104
	v_cvt_pk_bf16_f32 v92, v92, v93
	v_cvt_pk_bf16_f32 v93, v94, v95
	v_cvt_pk_bf16_f32 v94, v88, v89
	v_or_b32_e32 v88, 32, v130
	v_addc_co_u32_e32 v47, vcc, 0, v139, vcc
	global_store_dwordx4 v[44:45], v[28:31], off offset:256
	v_lshlrev_b64 v[104:105], 11, v[104:105]
	v_ashrrev_i32_e32 v89, 31, v88
	v_lshl_add_u64 v[28:29], v[138:139], 0, s[24:25]
	s_mov_b32 s24, 0x50000
	v_cvt_pk_bf16_f32 v76, v76, v77
	v_cvt_pk_bf16_f32 v77, v78, v79
	v_cvt_pk_bf16_f32 v78, v72, v73
	v_or_b32_e32 v72, 48, v130
	v_add_co_u32_e32 v30, vcc, s24, v138
	v_cvt_pk_bf16_f32 v12, v12, v13
	v_cvt_pk_bf16_f32 v13, v14, v15
	v_cvt_pk_bf16_f32 v14, v8, v9
	v_cvt_pk_bf16_f32 v15, v10, v11
	s_mov_b64 s[24:25], 0x58000
	v_cvt_pk_bf16_f32 v111, v106, v107
	v_lshl_add_u64 v[104:105], s[2:3], 0, v[104:105]
	v_lshlrev_b64 v[88:89], 11, v[88:89]
	v_ashrrev_i32_e32 v73, 31, v72
	v_addc_co_u32_e32 v31, vcc, 0, v139, vcc
	global_store_dwordx4 v[28:29], v[12:15], off offset:256
	global_store_dwordx4 v[138:139], v[108:111], off offset:256
	v_cvt_pk_bf16_f32 v95, v90, v91
	v_lshl_add_u64 v[12:13], v[138:139], 0, s[24:25]
	s_mov_b32 s24, 0x58000
	v_lshl_add_u64 v[108:109], v[104:105], 0, v[136:137]
	v_lshl_add_u64 v[88:89], s[2:3], 0, v[88:89]
	v_lshlrev_b64 v[72:73], 11, v[72:73]
	v_add_co_u32_e32 v14, vcc, s24, v138
	global_store_dwordx4 v[108:109], v[92:95], off offset:256
	v_cvt_pk_bf16_f32 v79, v74, v75
	v_lshl_add_u64 v[72:73], s[2:3], 0, v[72:73]
	v_lshl_add_u64 v[92:93], v[88:89], 0, v[136:137]
	v_addc_co_u32_e32 v15, vcc, 0, v139, vcc
	v_cvt_pk_bf16_f32 v124, v124, v125
	v_cvt_pk_bf16_f32 v125, v126, v127
	v_cvt_pk_bf16_f32 v126, v120, v121
	v_cvt_pk_bf16_f32 v127, v122, v123
	v_cvt_pk_bf16_f32 v104, v116, v117
	v_cvt_pk_bf16_f32 v105, v118, v119
	v_cvt_pk_bf16_f32 v106, v112, v113
	v_cvt_pk_bf16_f32 v107, v114, v115
	v_cvt_pk_bf16_f32 v88, v100, v101
	v_cvt_pk_bf16_f32 v89, v102, v103
	v_cvt_pk_bf16_f32 v90, v96, v97
	v_cvt_pk_bf16_f32 v91, v98, v99
	global_store_dwordx4 v[92:93], v[76:79], off offset:256
	v_cvt_pk_bf16_f32 v74, v80, v81
	v_cvt_pk_bf16_f32 v75, v82, v83
	v_lshl_add_u64 v[76:77], v[72:73], 0, v[136:137]
	v_cvt_pk_bf16_f32 v72, v84, v85
	v_cvt_pk_bf16_f32 v73, v86, v87
	v_cvt_pk_bf16_f32 v71, v66, v67
	v_cvt_pk_bf16_f32 v63, v58, v59
	v_cvt_pk_bf16_f32 v40, v52, v53
	v_cvt_pk_bf16_f32 v41, v54, v55
	v_cvt_pk_bf16_f32 v42, v48, v49
	v_cvt_pk_bf16_f32 v43, v50, v51
	v_cvt_pk_bf16_f32 v24, v36, v37
	v_cvt_pk_bf16_f32 v25, v38, v39
	v_cvt_pk_bf16_f32 v26, v32, v33
	v_cvt_pk_bf16_f32 v27, v34, v35
	v_cvt_pk_bf16_f32 v8, v20, v21
	v_cvt_pk_bf16_f32 v9, v22, v23
	v_cvt_pk_bf16_f32 v10, v16, v17
	v_cvt_pk_bf16_f32 v11, v18, v19
	v_cvt_pk_bf16_f32 v4, v4, v5
	v_cvt_pk_bf16_f32 v5, v6, v7
	v_cvt_pk_bf16_f32 v6, v0, v1
	v_cvt_pk_bf16_f32 v7, v2, v3
	s_andn2_b64 vcc, exec, s[36:37]
	s_mov_b64 s[24:25], -1
	global_store_dwordx4 v[138:139], v[124:127], off
	global_store_dwordx4 v[108:109], v[104:107], off
	global_store_dwordx4 v[92:93], v[88:91], off
	global_store_dwordx4 v[76:77], v[72:75], off
	global_store_dwordx4 v[76:77], v[68:71], off offset:256
	global_store_dwordx4 v[56:57], v[60:63], off
	global_store_dwordx4 v[46:47], v[40:43], off
	global_store_dwordx4 v[30:31], v[24:27], off
	global_store_dwordx4 v[14:15], v[8:11], off
	global_store_dwordx4 v[12:13], v[4:7], off offset:256
	s_cbranch_vccnz .LBB0_848
	s_andn2_b64 vcc, exec, s[0:1]
	s_cbranch_vccnz .LBB0_847
	s_barrier
	s_branch .LBB0_847

.LBB0_973:
	v_mov_b32_e32 v136, v138
	s_lshl_b32 s21, s28, 8
	s_add_i32 s21, s21, s55
	v_and_or_b32 v144, v136, 15, s21
	s_lshl_b32 s21, s29, 7
	v_lshrrev_b32_e32 v136, 1, v136
	v_and_or_b32 v136, v136, 24, s21
	v_or_b32_e32 v146, s56, v136
	v_mul_f32_e32 v136, 0xbfb8aa3b, v124
	v_exp_f32_e32 v136, v136
	v_mul_f32_e32 v137, 0xbfb8aa3b, v125
	v_exp_f32_e32 v137, v137
	v_mul_f32_e32 v145, 0xbfb8aa3b, v126
	v_add_f32_e32 v136, 1.0, v136
	v_rcp_f32_e32 v148, v136
	v_add_f32_e32 v136, 1.0, v137
	v_rcp_f32_e32 v149, v136
	v_exp_f32_e32 v145, v145
	v_ashrrev_i32_e32 v147, 31, v146
	v_mov_b64_e32 v[136:137], s[8:9]
	v_pk_mul_f32 v[124:125], v[124:125], v[148:149]
	v_mul_f32_e32 v148, 0xbfb8aa3b, v127
	v_exp_f32_e32 v148, v148
	v_pk_mul_f32 v[120:121], v[124:125], v[120:121]
	v_add_f32_e32 v124, 1.0, v145
	v_mul_f32_e32 v145, 0xbfb8aa3b, v112
	v_add_f32_e32 v125, 1.0, v148
	v_rcp_f32_e32 v124, v124
	v_rcp_f32_e32 v125, v125
	v_exp_f32_e32 v145, v145
	v_mul_f32_e32 v148, 0xbfb8aa3b, v113
	v_exp_f32_e32 v148, v148
	v_pk_mul_f32 v[124:125], v[126:127], v[124:125]
	v_add_f32_e32 v126, 1.0, v145
	v_mul_f32_e32 v145, 0xbfb8aa3b, v114
	v_add_f32_e32 v127, 1.0, v148
	v_exp_f32_e32 v145, v145
	v_mul_f32_e32 v148, 0xbfb8aa3b, v115
	v_exp_f32_e32 v149, v148
	v_rcp_f32_e32 v126, v126
	v_add_f32_e32 v145, 1.0, v145
	v_rcp_f32_e32 v127, v127
	v_rcp_f32_e32 v148, v145
	v_add_f32_e32 v145, 1.0, v149
	v_rcp_f32_e32 v149, v145
	v_pk_mul_f32 v[112:113], v[112:113], v[126:127]
	v_mad_i64_i32 v[150:151], s[28:29], v144, s58, v[136:137]
	v_pk_mul_f32 v[116:117], v[112:113], v[116:117]
	v_pk_mul_f32 v[112:113], v[114:115], v[148:149]
	v_cvt_pk_bf16_f32 v116, v116, v117
	v_pk_mul_f32 v[118:119], v[112:113], v[118:119]
	v_pk_mul_f32 v[122:123], v[124:125], v[122:123]
	v_cvt_pk_bf16_f32 v117, v118, v119
	v_mul_f32_e32 v118, 0xbfb8aa3b, v108
	v_mul_f32_e32 v119, 0xbfb8aa3b, v109
	v_exp_f32_e32 v118, v118
	v_exp_f32_e32 v119, v119
	v_lshlrev_b64 v[112:113], 1, v[146:147]
	v_lshl_add_u64 v[124:125], v[150:151], 0, v[112:113]
	v_cvt_pk_bf16_f32 v114, v120, v121
	v_cvt_pk_bf16_f32 v115, v122, v123
	global_store_dwordx4 v[124:125], v[114:117], off
	s_andn2_b64 vcc, exec, s[36:37]
	s_nop 0
	v_add_f32_e32 v114, 1.0, v118
	v_add_f32_e32 v115, 1.0, v119
	v_rcp_f32_e32 v114, v114
	v_rcp_f32_e32 v115, v115
	v_or_b32_e32 v116, 16, v144
	v_mad_i64_i32 v[116:117], s[28:29], v116, s58, v[136:137]
	v_pk_mul_f32 v[108:109], v[108:109], v[114:115]
	v_mul_f32_e32 v114, 0xbfb8aa3b, v110
	v_mul_f32_e32 v115, 0xbfb8aa3b, v111
	v_exp_f32_e32 v114, v114
	v_exp_f32_e32 v115, v115
	v_pk_mul_f32 v[104:105], v[108:109], v[104:105]
	v_add_f32_e32 v108, 1.0, v114
	v_add_f32_e32 v109, 1.0, v115
	v_mul_f32_e32 v114, 0xbfb8aa3b, v96
	v_mul_f32_e32 v115, 0xbfb8aa3b, v97
	v_rcp_f32_e32 v108, v108
	v_rcp_f32_e32 v109, v109
	v_exp_f32_e32 v114, v114
	v_exp_f32_e32 v115, v115
	v_pk_mul_f32 v[108:109], v[110:111], v[108:109]
	v_add_f32_e32 v110, 1.0, v114
	v_add_f32_e32 v111, 1.0, v115
	v_mul_f32_e32 v114, 0xbfb8aa3b, v98
	v_mul_f32_e32 v115, 0xbfb8aa3b, v99
	v_exp_f32_e32 v114, v114
	v_exp_f32_e32 v115, v115
	v_rcp_f32_e32 v110, v110
	v_rcp_f32_e32 v111, v111
	v_add_f32_e32 v114, 1.0, v114
	v_add_f32_e32 v115, 1.0, v115
	v_rcp_f32_e32 v114, v114
	v_rcp_f32_e32 v115, v115
	v_pk_mul_f32 v[96:97], v[96:97], v[110:111]
	v_pk_mul_f32 v[106:107], v[108:109], v[106:107]
	v_pk_mul_f32 v[100:101], v[96:97], v[100:101]
	v_pk_mul_f32 v[96:97], v[98:99], v[114:115]
	v_cvt_pk_bf16_f32 v98, v100, v101
	v_mul_f32_e32 v100, 0xbfb8aa3b, v92
	v_mul_f32_e32 v101, 0xbfb8aa3b, v93
	v_exp_f32_e32 v100, v100
	v_exp_f32_e32 v101, v101
	v_pk_mul_f32 v[102:103], v[96:97], v[102:103]
	v_lshl_add_u64 v[108:109], v[116:117], 0, v[112:113]
	v_cvt_pk_bf16_f32 v96, v104, v105
	v_cvt_pk_bf16_f32 v97, v106, v107
	v_cvt_pk_bf16_f32 v99, v102, v103
	global_store_dwordx4 v[108:109], v[96:99], off
	s_nop 1
	v_add_f32_e32 v96, 1.0, v100
	v_add_f32_e32 v97, 1.0, v101
	v_rcp_f32_e32 v96, v96
	v_rcp_f32_e32 v97, v97
	v_or_b32_e32 v98, 32, v144
	v_mad_i64_i32 v[98:99], s[28:29], v98, s58, v[136:137]
	v_pk_mul_f32 v[92:93], v[92:93], v[96:97]
	v_mul_f32_e32 v96, 0xbfb8aa3b, v94
	v_mul_f32_e32 v97, 0xbfb8aa3b, v95
	v_exp_f32_e32 v96, v96
	v_exp_f32_e32 v97, v97
	v_pk_mul_f32 v[88:89], v[92:93], v[88:89]
	v_add_f32_e32 v92, 1.0, v96
	v_add_f32_e32 v93, 1.0, v97
	v_mul_f32_e32 v96, 0xbfb8aa3b, v80
	v_mul_f32_e32 v97, 0xbfb8aa3b, v81
	v_rcp_f32_e32 v92, v92
	v_rcp_f32_e32 v93, v93
	v_exp_f32_e32 v96, v96
	v_exp_f32_e32 v97, v97
	v_pk_mul_f32 v[92:93], v[94:95], v[92:93]
	v_add_f32_e32 v94, 1.0, v96
	v_add_f32_e32 v95, 1.0, v97
	v_mul_f32_e32 v96, 0xbfb8aa3b, v82
	v_mul_f32_e32 v97, 0xbfb8aa3b, v83
	v_exp_f32_e32 v96, v96
	v_exp_f32_e32 v97, v97
	v_rcp_f32_e32 v94, v94
	v_rcp_f32_e32 v95, v95
	v_add_f32_e32 v96, 1.0, v96
	v_add_f32_e32 v97, 1.0, v97
	v_rcp_f32_e32 v96, v96
	v_rcp_f32_e32 v97, v97
	v_pk_mul_f32 v[80:81], v[80:81], v[94:95]
	v_pk_mul_f32 v[90:91], v[92:93], v[90:91]
	v_pk_mul_f32 v[84:85], v[80:81], v[84:85]
	v_pk_mul_f32 v[80:81], v[82:83], v[96:97]
	v_cvt_pk_bf16_f32 v82, v84, v85
	v_mul_f32_e32 v84, 0xbfb8aa3b, v76
	v_mul_f32_e32 v85, 0xbfb8aa3b, v77
	v_exp_f32_e32 v84, v84
	v_exp_f32_e32 v85, v85
	v_pk_mul_f32 v[86:87], v[80:81], v[86:87]
	v_lshl_add_u64 v[92:93], v[98:99], 0, v[112:113]
	v_cvt_pk_bf16_f32 v80, v88, v89
	v_cvt_pk_bf16_f32 v81, v90, v91
	v_cvt_pk_bf16_f32 v83, v86, v87
	global_store_dwordx4 v[92:93], v[80:83], off
	s_nop 1
	v_add_f32_e32 v80, 1.0, v84
	v_add_f32_e32 v81, 1.0, v85
	v_rcp_f32_e32 v80, v80
	v_rcp_f32_e32 v81, v81
	v_or_b32_e32 v82, 48, v144
	v_mad_i64_i32 v[82:83], s[28:29], v82, s58, v[136:137]
	v_pk_mul_f32 v[76:77], v[76:77], v[80:81]
	v_mul_f32_e32 v80, 0xbfb8aa3b, v78
	v_mul_f32_e32 v81, 0xbfb8aa3b, v79
	v_exp_f32_e32 v80, v80
	v_exp_f32_e32 v81, v81
	v_pk_mul_f32 v[72:73], v[76:77], v[72:73]
	v_add_f32_e32 v76, 1.0, v80
	v_add_f32_e32 v77, 1.0, v81
	v_mul_f32_e32 v80, 0xbfb8aa3b, v64
	v_mul_f32_e32 v81, 0xbfb8aa3b, v65
	v_rcp_f32_e32 v76, v76
	v_rcp_f32_e32 v77, v77
	v_exp_f32_e32 v80, v80
	v_exp_f32_e32 v81, v81
	v_pk_mul_f32 v[76:77], v[78:79], v[76:77]
	v_add_f32_e32 v78, 1.0, v80
	v_add_f32_e32 v79, 1.0, v81
	v_mul_f32_e32 v80, 0xbfb8aa3b, v66
	v_mul_f32_e32 v81, 0xbfb8aa3b, v67
	v_exp_f32_e32 v80, v80
	v_exp_f32_e32 v81, v81
	v_rcp_f32_e32 v78, v78
	v_rcp_f32_e32 v79, v79
	v_add_f32_e32 v80, 1.0, v80
	v_add_f32_e32 v81, 1.0, v81
	v_rcp_f32_e32 v80, v80
	v_rcp_f32_e32 v81, v81
	v_pk_mul_f32 v[64:65], v[64:65], v[78:79]
	v_pk_mul_f32 v[74:75], v[76:77], v[74:75]
	v_pk_mul_f32 v[68:69], v[64:65], v[68:69]
	v_pk_mul_f32 v[64:65], v[66:67], v[80:81]
	v_cvt_pk_bf16_f32 v66, v68, v69
	v_mul_f32_e32 v68, 0xbfb8aa3b, v60
	v_mul_f32_e32 v69, 0xbfb8aa3b, v61
	v_exp_f32_e32 v68, v68
	v_exp_f32_e32 v69, v69
	v_pk_mul_f32 v[70:71], v[64:65], v[70:71]
	v_lshl_add_u64 v[76:77], v[82:83], 0, v[112:113]
	v_cvt_pk_bf16_f32 v64, v72, v73
	v_cvt_pk_bf16_f32 v65, v74, v75
	v_cvt_pk_bf16_f32 v67, v70, v71
	global_store_dwordx4 v[76:77], v[64:67], off
	s_nop 1
	v_add_f32_e32 v64, 1.0, v68
	v_add_f32_e32 v65, 1.0, v69
	v_rcp_f32_e32 v64, v64
	v_rcp_f32_e32 v65, v65
	v_add_u32_e32 v66, 0x80, v144
	v_mad_i64_i32 v[66:67], s[28:29], v66, s58, v[136:137]
	v_pk_mul_f32 v[60:61], v[60:61], v[64:65]
	v_mul_f32_e32 v64, 0xbfb8aa3b, v62
	v_mul_f32_e32 v65, 0xbfb8aa3b, v63
	v_exp_f32_e32 v64, v64
	v_exp_f32_e32 v65, v65
	v_pk_mul_f32 v[56:57], v[60:61], v[56:57]
	v_add_f32_e32 v60, 1.0, v64
	v_add_f32_e32 v61, 1.0, v65
	v_mul_f32_e32 v64, 0xbfb8aa3b, v48
	v_mul_f32_e32 v65, 0xbfb8aa3b, v49
	v_rcp_f32_e32 v60, v60
	v_rcp_f32_e32 v61, v61
	v_exp_f32_e32 v64, v64
	v_exp_f32_e32 v65, v65
	v_pk_mul_f32 v[60:61], v[62:63], v[60:61]
	v_add_f32_e32 v62, 1.0, v64
	v_add_f32_e32 v63, 1.0, v65
	v_mul_f32_e32 v64, 0xbfb8aa3b, v50
	v_mul_f32_e32 v65, 0xbfb8aa3b, v51
	v_exp_f32_e32 v64, v64
	v_exp_f32_e32 v65, v65
	v_rcp_f32_e32 v62, v62
	v_rcp_f32_e32 v63, v63
	v_add_f32_e32 v64, 1.0, v64
	v_add_f32_e32 v65, 1.0, v65
	v_rcp_f32_e32 v64, v64
	v_rcp_f32_e32 v65, v65
	v_pk_mul_f32 v[48:49], v[48:49], v[62:63]
	v_pk_mul_f32 v[58:59], v[60:61], v[58:59]
	v_pk_mul_f32 v[52:53], v[48:49], v[52:53]
	v_pk_mul_f32 v[48:49], v[50:51], v[64:65]
	v_cvt_pk_bf16_f32 v50, v52, v53
	v_mul_f32_e32 v52, 0xbfb8aa3b, v44
	v_mul_f32_e32 v53, 0xbfb8aa3b, v45
	v_exp_f32_e32 v52, v52
	v_exp_f32_e32 v53, v53
	v_pk_mul_f32 v[54:55], v[48:49], v[54:55]
	v_lshl_add_u64 v[60:61], v[66:67], 0, v[112:113]
	v_cvt_pk_bf16_f32 v48, v56, v57
	v_cvt_pk_bf16_f32 v49, v58, v59
	v_cvt_pk_bf16_f32 v51, v54, v55
	global_store_dwordx4 v[60:61], v[48:51], off
	s_nop 1
	v_add_f32_e32 v48, 1.0, v52
	v_add_f32_e32 v49, 1.0, v53
	v_rcp_f32_e32 v48, v48
	v_rcp_f32_e32 v49, v49
	v_add_u32_e32 v50, 0x90, v144
	v_mad_i64_i32 v[50:51], s[28:29], v50, s58, v[136:137]
	v_pk_mul_f32 v[44:45], v[44:45], v[48:49]
	v_mul_f32_e32 v48, 0xbfb8aa3b, v46
	v_mul_f32_e32 v49, 0xbfb8aa3b, v47
	v_exp_f32_e32 v48, v48
	v_exp_f32_e32 v49, v49
	v_pk_mul_f32 v[40:41], v[44:45], v[40:41]
	v_add_f32_e32 v44, 1.0, v48
	v_add_f32_e32 v45, 1.0, v49
	v_mul_f32_e32 v48, 0xbfb8aa3b, v32
	v_mul_f32_e32 v49, 0xbfb8aa3b, v33
	v_rcp_f32_e32 v44, v44
	v_rcp_f32_e32 v45, v45
	v_exp_f32_e32 v48, v48
	v_exp_f32_e32 v49, v49
	v_pk_mul_f32 v[44:45], v[46:47], v[44:45]
	v_add_f32_e32 v46, 1.0, v48
	v_add_f32_e32 v47, 1.0, v49
	v_mul_f32_e32 v48, 0xbfb8aa3b, v34
	v_mul_f32_e32 v49, 0xbfb8aa3b, v35
	v_exp_f32_e32 v48, v48
	v_exp_f32_e32 v49, v49
	v_rcp_f32_e32 v46, v46
	v_rcp_f32_e32 v47, v47
	v_add_f32_e32 v48, 1.0, v48
	v_add_f32_e32 v49, 1.0, v49
	v_rcp_f32_e32 v48, v48
	v_rcp_f32_e32 v49, v49
	v_pk_mul_f32 v[32:33], v[32:33], v[46:47]
	v_pk_mul_f32 v[42:43], v[44:45], v[42:43]
	v_pk_mul_f32 v[36:37], v[32:33], v[36:37]
	v_pk_mul_f32 v[32:33], v[34:35], v[48:49]
	v_cvt_pk_bf16_f32 v34, v36, v37
	v_mul_f32_e32 v36, 0xbfb8aa3b, v28
	v_mul_f32_e32 v37, 0xbfb8aa3b, v29
	v_exp_f32_e32 v36, v36
	v_exp_f32_e32 v37, v37
	v_pk_mul_f32 v[38:39], v[32:33], v[38:39]
	v_lshl_add_u64 v[44:45], v[50:51], 0, v[112:113]
	v_cvt_pk_bf16_f32 v32, v40, v41
	v_cvt_pk_bf16_f32 v33, v42, v43
	v_cvt_pk_bf16_f32 v35, v38, v39
	global_store_dwordx4 v[44:45], v[32:35], off
	s_nop 1
	v_add_f32_e32 v32, 1.0, v36
	v_add_f32_e32 v33, 1.0, v37
	v_rcp_f32_e32 v32, v32
	v_rcp_f32_e32 v33, v33
	v_add_u32_e32 v34, 0xa0, v144
	v_mad_i64_i32 v[34:35], s[28:29], v34, s58, v[136:137]
	v_pk_mul_f32 v[28:29], v[28:29], v[32:33]
	v_mul_f32_e32 v32, 0xbfb8aa3b, v30
	v_mul_f32_e32 v33, 0xbfb8aa3b, v31
	v_exp_f32_e32 v32, v32
	v_exp_f32_e32 v33, v33
	v_pk_mul_f32 v[24:25], v[28:29], v[24:25]
	v_add_f32_e32 v28, 1.0, v32
	v_add_f32_e32 v29, 1.0, v33
	v_mul_f32_e32 v32, 0xbfb8aa3b, v16
	v_mul_f32_e32 v33, 0xbfb8aa3b, v17
	v_rcp_f32_e32 v28, v28
	v_rcp_f32_e32 v29, v29
	v_exp_f32_e32 v32, v32
	v_exp_f32_e32 v33, v33
	v_pk_mul_f32 v[28:29], v[30:31], v[28:29]
	v_add_f32_e32 v30, 1.0, v32
	v_add_f32_e32 v31, 1.0, v33
	v_mul_f32_e32 v32, 0xbfb8aa3b, v18
	v_mul_f32_e32 v33, 0xbfb8aa3b, v19
	v_exp_f32_e32 v32, v32
	v_exp_f32_e32 v33, v33
	v_rcp_f32_e32 v30, v30
	v_rcp_f32_e32 v31, v31
	v_add_f32_e32 v32, 1.0, v32
	v_add_f32_e32 v33, 1.0, v33
	v_rcp_f32_e32 v32, v32
	v_rcp_f32_e32 v33, v33
	v_pk_mul_f32 v[16:17], v[16:17], v[30:31]
	v_pk_mul_f32 v[26:27], v[28:29], v[26:27]
	v_pk_mul_f32 v[20:21], v[16:17], v[20:21]
	v_pk_mul_f32 v[16:17], v[18:19], v[32:33]
	v_cvt_pk_bf16_f32 v18, v20, v21
	v_mul_f32_e32 v20, 0xbfb8aa3b, v12
	v_mul_f32_e32 v21, 0xbfb8aa3b, v13
	v_exp_f32_e32 v20, v20
	v_exp_f32_e32 v21, v21
	v_pk_mul_f32 v[22:23], v[16:17], v[22:23]
	v_lshl_add_u64 v[28:29], v[34:35], 0, v[112:113]
	v_cvt_pk_bf16_f32 v16, v24, v25
	v_cvt_pk_bf16_f32 v17, v26, v27
	v_cvt_pk_bf16_f32 v19, v22, v23
	global_store_dwordx4 v[28:29], v[16:19], off
	s_nop 1
	v_add_f32_e32 v16, 1.0, v20
	v_add_f32_e32 v17, 1.0, v21
	v_rcp_f32_e32 v16, v16
	v_rcp_f32_e32 v17, v17
	v_add_u32_e32 v18, 0xb0, v144
	v_mad_i64_i32 v[18:19], s[28:29], v18, s58, v[136:137]
	v_pk_mul_f32 v[12:13], v[12:13], v[16:17]
	v_mul_f32_e32 v16, 0xbfb8aa3b, v14
	v_mul_f32_e32 v17, 0xbfb8aa3b, v15
	v_exp_f32_e32 v16, v16
	v_exp_f32_e32 v17, v17
	v_pk_mul_f32 v[8:9], v[12:13], v[8:9]
	s_mov_b64 s[28:29], -1
	v_add_f32_e32 v12, 1.0, v16
	v_add_f32_e32 v13, 1.0, v17
	v_mul_f32_e32 v16, 0xbfb8aa3b, v0
	v_mul_f32_e32 v17, 0xbfb8aa3b, v1
	v_rcp_f32_e32 v12, v12
	v_rcp_f32_e32 v13, v13
	v_exp_f32_e32 v16, v16
	v_exp_f32_e32 v17, v17
	v_pk_mul_f32 v[12:13], v[14:15], v[12:13]
	v_add_f32_e32 v14, 1.0, v16
	v_add_f32_e32 v15, 1.0, v17
	v_mul_f32_e32 v16, 0xbfb8aa3b, v2
	v_mul_f32_e32 v17, 0xbfb8aa3b, v3
	v_exp_f32_e32 v16, v16
	v_exp_f32_e32 v17, v17
	v_rcp_f32_e32 v14, v14
	v_rcp_f32_e32 v15, v15
	v_add_f32_e32 v16, 1.0, v16
	v_add_f32_e32 v17, 1.0, v17
	v_rcp_f32_e32 v16, v16
	v_rcp_f32_e32 v17, v17
	v_pk_mul_f32 v[0:1], v[0:1], v[14:15]
	v_pk_mul_f32 v[10:11], v[12:13], v[10:11]
	v_pk_mul_f32 v[4:5], v[0:1], v[4:5]
	v_pk_mul_f32 v[0:1], v[2:3], v[16:17]
	v_lshl_add_u64 v[12:13], v[18:19], 0, v[112:113]
	v_pk_mul_f32 v[6:7], v[0:1], v[6:7]
	v_cvt_pk_bf16_f32 v0, v8, v9
	v_cvt_pk_bf16_f32 v1, v10, v11
	v_cvt_pk_bf16_f32 v2, v4, v5
	v_cvt_pk_bf16_f32 v3, v6, v7
	global_store_dwordx4 v[12:13], v[0:3], off
	s_cbranch_vccnz .LBB0_966
	s_andn2_b64 vcc, exec, s[6:7]
	s_cbranch_vccnz .LBB0_965
	s_barrier
	s_branch .LBB0_965

.LBB0_1049:
	v_mov_b32_e32 v137, v138
	s_lshl_b32 s22, s53, 8
	s_add_i32 s22, s22, s46
	v_and_or_b32 v136, v137, 15, s22
	s_lshl_b32 s22, s54, 8
	v_lshrrev_b32_e32 v137, 1, v137
	v_and_or_b32 v137, v137, 24, s22
	v_or_b32_e32 v144, s47, v137
	v_ashrrev_i32_e32 v137, 31, v136
	v_ashrrev_i32_e32 v145, 31, v144
	v_lshlrev_b64 v[146:147], 11, v[136:137]
	v_lshl_add_u64 v[146:147], s[10:11], 0, v[146:147]
	v_lshlrev_b64 v[144:145], 1, v[144:145]
	v_lshl_add_u64 v[146:147], v[146:147], 0, v[144:145]
	s_mov_b64 s[22:23], 0x40000
	v_cvt_pk_bf16_f32 v68, v68, v69
	v_cvt_pk_bf16_f32 v69, v70, v71
	v_cvt_pk_bf16_f32 v70, v64, v65
	v_lshl_add_u64 v[64:65], v[146:147], 0, s[22:23]
	s_mov_b32 s22, 0x40000
	v_cvt_pk_bf16_f32 v60, v60, v61
	v_cvt_pk_bf16_f32 v61, v62, v63
	v_cvt_pk_bf16_f32 v62, v56, v57
	v_add_co_u32_e32 v56, vcc, s22, v146
	v_cvt_pk_bf16_f32 v44, v44, v45
	v_cvt_pk_bf16_f32 v45, v46, v47
	v_cvt_pk_bf16_f32 v46, v40, v41
	v_cvt_pk_bf16_f32 v47, v42, v43
	s_mov_b64 s[22:23], 0x48000
	v_addc_co_u32_e32 v57, vcc, 0, v147, vcc
	global_store_dwordx4 v[64:65], v[44:47], off offset:256
	v_cvt_pk_bf16_f32 v108, v108, v109
	v_cvt_pk_bf16_f32 v109, v110, v111
	v_lshl_add_u64 v[44:45], v[146:147], 0, s[22:23]
	s_mov_b32 s22, 0x48000
	v_cvt_pk_bf16_f32 v110, v104, v105
	v_or_b32_e32 v104, 16, v136
	v_add_co_u32_e32 v46, vcc, s22, v146
	v_cvt_pk_bf16_f32 v28, v28, v29
	v_cvt_pk_bf16_f32 v29, v30, v31
	v_cvt_pk_bf16_f32 v30, v24, v25
	v_cvt_pk_bf16_f32 v31, v26, v27
	s_mov_b64 s[22:23], 0x50000
	v_ashrrev_i32_e32 v105, 31, v104
	v_cvt_pk_bf16_f32 v92, v92, v93
	v_cvt_pk_bf16_f32 v93, v94, v95
	v_cvt_pk_bf16_f32 v94, v88, v89
	v_or_b32_e32 v88, 32, v136
	v_addc_co_u32_e32 v47, vcc, 0, v147, vcc
	global_store_dwordx4 v[44:45], v[28:31], off offset:256
	v_lshlrev_b64 v[104:105], 11, v[104:105]
	v_ashrrev_i32_e32 v89, 31, v88
	v_lshl_add_u64 v[28:29], v[146:147], 0, s[22:23]
	s_mov_b32 s22, 0x50000
	v_cvt_pk_bf16_f32 v76, v76, v77
	v_cvt_pk_bf16_f32 v77, v78, v79
	v_cvt_pk_bf16_f32 v78, v72, v73
	v_or_b32_e32 v72, 48, v136
	v_add_co_u32_e32 v30, vcc, s22, v146
	v_cvt_pk_bf16_f32 v111, v106, v107
	v_lshl_add_u64 v[104:105], s[10:11], 0, v[104:105]
	v_lshlrev_b64 v[88:89], 11, v[88:89]
	v_ashrrev_i32_e32 v73, 31, v72
	v_addc_co_u32_e32 v31, vcc, 0, v147, vcc
	v_cvt_pk_bf16_f32 v12, v12, v13
	v_cvt_pk_bf16_f32 v13, v14, v15
	v_cvt_pk_bf16_f32 v14, v8, v9
	v_cvt_pk_bf16_f32 v15, v10, v11
	s_mov_b32 s22, 0x58000
	global_store_dwordx4 v[146:147], v[108:111], off offset:256
	v_cvt_pk_bf16_f32 v95, v90, v91
	v_lshl_add_u64 v[88:89], s[10:11], 0, v[88:89]
	v_lshl_add_u64 v[108:109], v[104:105], 0, v[144:145]
	v_lshlrev_b64 v[72:73], 11, v[72:73]
	global_store_dwordx4 v[28:29], v[12:15], off offset:256
	global_store_dwordx4 v[108:109], v[92:95], off offset:256
	v_cvt_pk_bf16_f32 v79, v74, v75
	v_add_co_u32_e32 v14, vcc, s22, v146
	v_lshl_add_u64 v[92:93], v[88:89], 0, v[144:145]
	v_lshl_add_u64 v[72:73], s[10:11], 0, v[72:73]
	v_addc_co_u32_e32 v15, vcc, 0, v147, vcc
	v_cvt_pk_bf16_f32 v124, v124, v125
	v_cvt_pk_bf16_f32 v125, v126, v127
	v_cvt_pk_bf16_f32 v126, v120, v121
	v_cvt_pk_bf16_f32 v127, v122, v123
	v_cvt_pk_bf16_f32 v104, v116, v117
	v_cvt_pk_bf16_f32 v105, v118, v119
	v_cvt_pk_bf16_f32 v106, v112, v113
	v_cvt_pk_bf16_f32 v107, v114, v115
	v_cvt_pk_bf16_f32 v88, v100, v101
	v_cvt_pk_bf16_f32 v89, v102, v103
	v_cvt_pk_bf16_f32 v90, v96, v97
	v_cvt_pk_bf16_f32 v91, v98, v99
	global_store_dwordx4 v[92:93], v[76:79], off offset:256
	v_cvt_pk_bf16_f32 v74, v80, v81
	v_cvt_pk_bf16_f32 v75, v82, v83
	v_lshl_add_u64 v[76:77], v[72:73], 0, v[144:145]
	v_cvt_pk_bf16_f32 v72, v84, v85
	v_cvt_pk_bf16_f32 v73, v86, v87
	v_cvt_pk_bf16_f32 v71, v66, v67
	v_cvt_pk_bf16_f32 v63, v58, v59
	v_cvt_pk_bf16_f32 v40, v52, v53
	v_cvt_pk_bf16_f32 v41, v54, v55
	v_cvt_pk_bf16_f32 v42, v48, v49
	v_cvt_pk_bf16_f32 v43, v50, v51
	v_cvt_pk_bf16_f32 v24, v36, v37
	v_cvt_pk_bf16_f32 v25, v38, v39
	v_cvt_pk_bf16_f32 v26, v32, v33
	v_cvt_pk_bf16_f32 v27, v34, v35
	v_lshl_add_u64 v[12:13], v[146:147], 0, s[2:3]
	v_cvt_pk_bf16_f32 v8, v20, v21
	v_cvt_pk_bf16_f32 v9, v22, v23
	v_cvt_pk_bf16_f32 v10, v16, v17
	v_cvt_pk_bf16_f32 v11, v18, v19
	v_cvt_pk_bf16_f32 v4, v4, v5
	v_cvt_pk_bf16_f32 v5, v6, v7
	v_cvt_pk_bf16_f32 v6, v0, v1
	v_cvt_pk_bf16_f32 v7, v2, v3
	s_and_b64 vcc, exec, s[36:37]
	s_mov_b64 s[22:23], -1
	global_store_dwordx4 v[146:147], v[124:127], off
	global_store_dwordx4 v[108:109], v[104:107], off
	global_store_dwordx4 v[92:93], v[88:91], off
	global_store_dwordx4 v[76:77], v[72:75], off
	global_store_dwordx4 v[76:77], v[68:71], off offset:256
	global_store_dwordx4 v[56:57], v[60:63], off
	global_store_dwordx4 v[46:47], v[40:43], off
	global_store_dwordx4 v[30:31], v[24:27], off
	global_store_dwordx4 v[14:15], v[8:11], off
	global_store_dwordx4 v[12:13], v[4:7], off offset:256
	s_cbranch_vccnz .LBB0_1034
	s_andn2_b64 vcc, exec, s[8:9]
	s_cbranch_vccnz .LBB0_1033
	s_barrier
	s_branch .LBB0_1033
